# all per-segment s_setprio flips of the GEMM loops deleted, no static raise (separating the two effects)
# speedup vs baseline: 1.0117x; 1.0117x over previous
; #define PG8_STAGE(bufoff, gbase, voff) do { _Pragma("unroll") for (int _i = 0; _i < 2; ++_i) \
;         __builtin_amdgcn_global_load_lds((const unsigned*)((const char*)(gbase) + (voff)[_i]), (LAS unsigned*)(lds + (bufoff) + ldsw + _i * 8192), 16, 0, 0); } while (0)
; #define PG8_LDA(dst, b, h) do { _Pragma("unroll") for (int m = 0; m < 4; ++m) _Pragma("unroll") for (int k = 0; k < 2; ++k) dst[m][k] = *(const LAS bf16x8*)(lds + PG8_SA(b, h) + aoff + m * 2048 + k * 1024); } while (0)
; #define PG8_LDB(dst, b, h) do { _Pragma("unroll") for (int n = 0; n < 2; ++n) _Pragma("unroll") for (int k = 0; k < 2; ++k) dst[n][k] = *(const LAS bf16x8*)(lds + PG8_SB(b, h) + boff + n * 2048 + k * 1024); } while (0)
; #define PG8_WAIT_V(n) asm volatile("s_waitcnt vmcnt(" #n ")" ::: "memory")
; template <class Epi, class Geom, class Sched, bool ALIGN_EPI, bool I8 = false>
; __device__ __forceinline__ void gemm_phase(LAS unsigned char* lds, const Gemm g, const Sched& S, const Epi& E) {
;     ...
;         for (int t = 0; t < nt; t += 2) {
;             const bool last = (t == nt - 2);
;             const char* a1 = cA + (size_t)(t + 1) * kstep;
;             const char* a2 = last ? nA : cA + (size_t)(t + 2) * kstep; const char* b2 = last ? nB : cB + (size_t)(t + 2) * kstep;
;             const char* a3 = a2 + kstep; const char* b3 = b2 + kstep;
;             PG8_LDB(B0, 0, 0); PG8_LDB(B1, 0, 1); PG8_SCHED; PG8_LDA(At, 0, 0); PG8_STAGE(PG8_SA(1, 1), a1 + hsA, voffA);
;             PG8_WAIT_V(8); PG8_WAIT_L(0); PG8_BAR; PG8_MMA(0, 0, At, B0); PG8_MMA(0, 1, At, B1); PG8_BAR; PG8_SCHED;
;             PG8_LDA(At, 0, 1); PG8_STAGE(PG8_SB(0, 0), b2, voffB); PG8_STAGE(PG8_SB(0, 1), b2 + hsB, voffB); PG8_STAGE(PG8_SA(0, 0), a2, voffA);
;             PG8_WAIT_V(8); PG8_WAIT_L(0); PG8_BAR; PG8_MMA(1, 0, At, B0); PG8_MMA(1, 1, At, B1); PG8_BAR; PG8_SCHED;
;             PG8_LDB(B0, 1, 0); PG8_LDB(B1, 1, 1); PG8_SCHED; PG8_LDA(At, 1, 0); PG8_STAGE(PG8_SA(0, 1), a2 + hsA, voffA);
;             PG8_WAIT_V(8); PG8_WAIT_L(0); PG8_BAR; PG8_MMA(0, 0, At, B0); PG8_MMA(0, 1, At, B1); PG8_BAR; PG8_SCHED;
;             PG8_LDA(At, 1, 1); PG8_STAGE(PG8_SB(1, 0), b3, voffB); PG8_STAGE(PG8_SB(1, 1), b3 + hsB, voffB); PG8_STAGE(PG8_SA(1, 0), a3, voffA);
;             PG8_WAIT_V(8); PG8_WAIT_L(0); PG8_BAR; PG8_MMA(1, 0, At, B0); PG8_MMA(1, 1, At, B1); PG8_BAR; PG8_SCHED;
;         }
.LBB0_194:
	ds_read_b128 v[106:109], v241
	ds_read_b128 v[110:113], v241 offset:1024
	ds_read_b128 v[138:141], v241 offset:2048
	ds_read_b128 v[142:145], v241 offset:3072
	ds_read_b128 v[146:149], v242
	ds_read_b128 v[150:153], v242 offset:1024
	ds_read_b128 v[154:157], v242 offset:2048
	ds_read_b128 v[158:161], v242 offset:3072
	s_add_u32 s4, s0, 0xfff00080
	s_addc_u32 s5, s1, -1
	s_cmp_eq_u32 s13, 60
	s_cselect_b32 s7, s3, s5
	s_cselect_b32 s6, s8, s4
	s_cselect_b32 s5, s9, s12
	s_cselect_b32 s4, s10, s11
	v_lshl_add_u64 v[208:209], s[0:1], 0, v[184:185]
	s_add_i32 m0, s73, 0xc000
	ds_read_b128 v[162:165], v243
	ds_read_b128 v[166:169], v243 offset:1024
	ds_read_b128 v[170:173], v243 offset:2048
	ds_read_b128 v[188:191], v243 offset:3072
	ds_read_b128 v[192:195], v243 offset:4096
	ds_read_b128 v[196:199], v243 offset:5120
	ds_read_b128 v[200:203], v243 offset:6144
	ds_read_b128 v[204:207], v243 offset:7168
	global_load_lds_dwordx4 v[208:209], off
	v_lshl_add_u64 v[208:209], s[0:1], 0, v[186:187]
	s_add_i32 m0, s73, 0xe000
	s_nop 0
	global_load_lds_dwordx4 v[208:209], off
	s_waitcnt vmcnt(8)
	s_waitcnt lgkmcnt(0)
	s_barrier
	s_waitcnt lgkmcnt(0)
	v_mfma_f32_16x16x32_bf16 v[122:125], v[106:109], v[162:165], v[122:125]
	v_mfma_f32_16x16x32_bf16 v[126:129], v[138:141], v[162:165], v[126:129]
	v_mfma_f32_16x16x32_bf16 v[102:105], v[106:109], v[170:173], v[102:105]
	v_mfma_f32_16x16x32_bf16 v[98:101], v[138:141], v[170:173], v[98:101]
	v_mfma_f32_16x16x32_bf16 v[94:97], v[106:109], v[192:195], v[94:97]
	v_mfma_f32_16x16x32_bf16 v[86:89], v[138:141], v[192:195], v[86:89]
	v_mfma_f32_16x16x32_bf16 v[78:81], v[106:109], v[200:203], v[78:81]
	v_mfma_f32_16x16x32_bf16 v[70:73], v[138:141], v[200:203], v[70:73]
	v_mfma_f32_16x16x32_bf16 v[122:125], v[110:113], v[166:169], v[122:125]
	v_mfma_f32_16x16x32_bf16 v[126:129], v[142:145], v[166:169], v[126:129]
	v_mfma_f32_16x16x32_bf16 v[102:105], v[110:113], v[188:191], v[102:105]
	v_mfma_f32_16x16x32_bf16 v[98:101], v[142:145], v[188:191], v[98:101]
	v_mfma_f32_16x16x32_bf16 v[94:97], v[110:113], v[196:199], v[94:97]
	v_mfma_f32_16x16x32_bf16 v[86:89], v[142:145], v[196:199], v[86:89]
	v_mfma_f32_16x16x32_bf16 v[78:81], v[110:113], v[204:207], v[78:81]
	v_mfma_f32_16x16x32_bf16 v[70:73], v[142:145], v[204:207], v[70:73]
	v_mfma_f32_16x16x32_bf16 v[118:121], v[146:149], v[162:165], v[118:121]
	v_mfma_f32_16x16x32_bf16 v[114:117], v[154:157], v[162:165], v[114:117]
	v_mfma_f32_16x16x32_bf16 v[90:93], v[146:149], v[170:173], v[90:93]
	v_mfma_f32_16x16x32_bf16 v[82:85], v[154:157], v[170:173], v[82:85]
	v_mfma_f32_16x16x32_bf16 v[74:77], v[146:149], v[192:195], v[74:77]
	v_mfma_f32_16x16x32_bf16 v[66:69], v[154:157], v[192:195], v[66:69]
	v_mfma_f32_16x16x32_bf16 v[62:65], v[146:149], v[200:203], v[62:65]
	v_mfma_f32_16x16x32_bf16 v[58:61], v[154:157], v[200:203], v[58:61]
	v_mfma_f32_16x16x32_bf16 v[118:121], v[150:153], v[166:169], v[118:121]
	v_mfma_f32_16x16x32_bf16 v[114:117], v[158:161], v[166:169], v[114:117]
	v_mfma_f32_16x16x32_bf16 v[90:93], v[150:153], v[188:191], v[90:93]
	v_mfma_f32_16x16x32_bf16 v[82:85], v[158:161], v[188:191], v[82:85]
	v_mfma_f32_16x16x32_bf16 v[74:77], v[150:153], v[196:199], v[74:77]
	v_mfma_f32_16x16x32_bf16 v[66:69], v[158:161], v[196:199], v[66:69]
	v_mfma_f32_16x16x32_bf16 v[62:65], v[150:153], v[204:207], v[62:65]
	v_mfma_f32_16x16x32_bf16 v[58:61], v[158:161], v[204:207], v[58:61]
	s_barrier
	s_add_i32 s14, s34, s89
	v_lshl_add_u64 v[208:209], s[4:5], 0, v[176:177]
	s_mov_b32 m0, s14
	ds_read_b128 v[162:165], v243 offset:16384
	ds_read_b128 v[166:169], v243 offset:17408
	ds_read_b128 v[170:173], v243 offset:18432
	ds_read_b128 v[188:191], v243 offset:19456
	ds_read_b128 v[192:195], v243 offset:20480
	ds_read_b128 v[196:199], v243 offset:21504
	ds_read_b128 v[200:203], v243 offset:22528
	ds_read_b128 v[204:207], v243 offset:23552
	global_load_lds_dwordx4 v[208:209], off
	s_add_i32 m0, s14, 0x2000
	s_add_u32 s14, s4, 0x100000
	v_lshl_add_u64 v[210:211], s[4:5], 0, v[180:181]
	s_addc_u32 s15, s5, 0
	s_add_i32 s16, s35, s89
	global_load_lds_dwordx4 v[210:211], off
	v_lshl_add_u64 v[212:213], s[14:15], 0, v[176:177]
	s_mov_b32 m0, s16
	v_lshl_add_u64 v[214:215], s[6:7], 0, v[178:179]
	global_load_lds_dwordx4 v[212:213], off
	v_lshl_add_u64 v[212:213], s[14:15], 0, v[180:181]
	s_add_i32 m0, s16, 0x2000
	s_nop 0
	global_load_lds_dwordx4 v[212:213], off
	v_lshl_add_u64 v[212:213], s[6:7], 0, v[174:175]
	s_mov_b32 m0, s73
	s_nop 0
	global_load_lds_dwordx4 v[212:213], off
	s_mov_b32 m0, s90
	s_nop 0
	global_load_lds_dwordx4 v[214:215], off
	s_waitcnt vmcnt(8)
	s_waitcnt lgkmcnt(0)
	s_barrier
; #define PG8_STAGE(bufoff, gbase, voff) do { _Pragma("unroll") for (int _i = 0; _i < 2; ++_i) \
;         __builtin_amdgcn_global_load_lds((const unsigned*)((const char*)(gbase) + (voff)[_i]), (LAS unsigned*)(lds + (bufoff) + ldsw + _i * 8192), 16, 0, 0); } while (0)
; #define PG8_LDA(dst, b, h) do { _Pragma("unroll") for (int m = 0; m < 4; ++m) _Pragma("unroll") for (int k = 0; k < 2; ++k) dst[m][k] = *(const LAS bf16x8*)(lds + PG8_SA(b, h) + aoff + m * 2048 + k * 1024); } while (0)
; #define PG8_LDB(dst, b, h) do { _Pragma("unroll") for (int n = 0; n < 2; ++n) _Pragma("unroll") for (int k = 0; k < 2; ++k) dst[n][k] = *(const LAS bf16x8*)(lds + PG8_SB(b, h) + boff + n * 2048 + k * 1024); } while (0)
; #define PG8_WAIT_V(n) asm volatile("s_waitcnt vmcnt(" #n ")" ::: "memory")
; template <class Epi, class Geom, class Sched, bool ALIGN_EPI, bool I8 = false>
; __device__ __forceinline__ void gemm_phase(LAS unsigned char* lds, const Gemm g, const Sched& S, const Epi& E) {
;     ...
;         for (int t = 0; t < nt; t += 2) {
;             const bool last = (t == nt - 2);
;             const char* a1 = cA + (size_t)(t + 1) * kstep;
;             const char* a2 = last ? nA : cA + (size_t)(t + 2) * kstep; const char* b2 = last ? nB : cB + (size_t)(t + 2) * kstep;
;             const char* a3 = a2 + kstep; const char* b3 = b2 + kstep;
;             PG8_LDB(B0, 0, 0); PG8_LDB(B1, 0, 1); PG8_SCHED; PG8_LDA(At, 0, 0); PG8_STAGE(PG8_SA(1, 1), a1 + hsA, voffA);
;             PG8_WAIT_V(8); PG8_WAIT_L(0); PG8_BAR; PG8_MMA(0, 0, At, B0); PG8_MMA(0, 1, At, B1); PG8_BAR; PG8_SCHED;
;             PG8_LDA(At, 0, 1); PG8_STAGE(PG8_SB(0, 0), b2, voffB); PG8_STAGE(PG8_SB(0, 1), b2 + hsB, voffB); PG8_STAGE(PG8_SA(0, 0), a2, voffA);
;             PG8_WAIT_V(8); PG8_WAIT_L(0); PG8_BAR; PG8_MMA(1, 0, At, B0); PG8_MMA(1, 1, At, B1); PG8_BAR; PG8_SCHED;
;             PG8_LDB(B0, 1, 0); PG8_LDB(B1, 1, 1); PG8_SCHED; PG8_LDA(At, 1, 0); PG8_STAGE(PG8_SA(0, 1), a2 + hsA, voffA);
;             PG8_WAIT_V(8); PG8_WAIT_L(0); PG8_BAR; PG8_MMA(0, 0, At, B0); PG8_MMA(0, 1, At, B1); PG8_BAR; PG8_SCHED;
;             PG8_LDA(At, 1, 1); PG8_STAGE(PG8_SB(1, 0), b3, voffB); PG8_STAGE(PG8_SB(1, 1), b3 + hsB, voffB); PG8_STAGE(PG8_SA(1, 0), a3, voffA);
;             PG8_WAIT_V(8); PG8_WAIT_L(0); PG8_BAR; PG8_MMA(1, 0, At, B0); PG8_MMA(1, 1, At, B1); PG8_BAR; PG8_SCHED;
;         }
	s_waitcnt lgkmcnt(0)
	v_mfma_f32_16x16x32_bf16 v[54:57], v[106:109], v[162:165], v[54:57]
	v_mfma_f32_16x16x32_bf16 v[50:53], v[138:141], v[162:165], v[50:53]
	v_mfma_f32_16x16x32_bf16 v[46:49], v[106:109], v[170:173], v[46:49]
	v_mfma_f32_16x16x32_bf16 v[38:41], v[138:141], v[170:173], v[38:41]
	v_mfma_f32_16x16x32_bf16 v[30:33], v[106:109], v[192:195], v[30:33]
	v_mfma_f32_16x16x32_bf16 v[18:21], v[138:141], v[192:195], v[18:21]
	v_mfma_f32_16x16x32_bf16 v[106:109], v[106:109], v[200:203], v[134:137]
	v_mfma_f32_16x16x32_bf16 v[54:57], v[110:113], v[166:169], v[54:57]
	v_mfma_f32_16x16x32_bf16 v[50:53], v[142:145], v[166:169], v[50:53]
	v_mfma_f32_16x16x32_bf16 v[46:49], v[110:113], v[188:191], v[46:49]
	v_mfma_f32_16x16x32_bf16 v[38:41], v[142:145], v[188:191], v[38:41]
	v_mfma_f32_16x16x32_bf16 v[30:33], v[110:113], v[196:199], v[30:33]
	v_mfma_f32_16x16x32_bf16 v[18:21], v[142:145], v[196:199], v[18:21]
	v_mfma_f32_16x16x32_bf16 v[106:109], v[110:113], v[204:207], v[106:109]
	v_mfma_f32_16x16x32_bf16 v[110:113], v[138:141], v[200:203], v[130:133]
	v_mfma_f32_16x16x32_bf16 v[110:113], v[142:145], v[204:207], v[110:113]
	v_mfma_f32_16x16x32_bf16 v[42:45], v[146:149], v[162:165], v[42:45]
	v_mfma_f32_16x16x32_bf16 v[34:37], v[154:157], v[162:165], v[34:37]
	v_mfma_f32_16x16x32_bf16 v[26:29], v[146:149], v[170:173], v[26:29]
	v_mfma_f32_16x16x32_bf16 v[22:25], v[154:157], v[170:173], v[22:25]
	v_mfma_f32_16x16x32_bf16 v[14:17], v[146:149], v[192:195], v[14:17]
	v_mfma_f32_16x16x32_bf16 v[10:13], v[154:157], v[192:195], v[10:13]
	v_mfma_f32_16x16x32_bf16 v[6:9], v[146:149], v[200:203], v[6:9]
	v_mfma_f32_16x16x32_bf16 v[2:5], v[154:157], v[200:203], v[2:5]
	v_mfma_f32_16x16x32_bf16 v[42:45], v[150:153], v[166:169], v[42:45]
	v_mfma_f32_16x16x32_bf16 v[34:37], v[158:161], v[166:169], v[34:37]
	v_mfma_f32_16x16x32_bf16 v[26:29], v[150:153], v[188:191], v[26:29]
	v_mfma_f32_16x16x32_bf16 v[22:25], v[158:161], v[188:191], v[22:25]
	v_mfma_f32_16x16x32_bf16 v[14:17], v[150:153], v[196:199], v[14:17]
	v_mfma_f32_16x16x32_bf16 v[10:13], v[158:161], v[196:199], v[10:13]
	v_mfma_f32_16x16x32_bf16 v[6:9], v[150:153], v[204:207], v[6:9]
	v_mfma_f32_16x16x32_bf16 v[2:5], v[158:161], v[204:207], v[2:5]
	s_barrier
	s_add_i32 s14, 0, 0x18000
	s_add_i32 s15, 0, 0x1c000
	v_add_u32_e32 v142, s14, v240
	v_add_u32_e32 v158, s15, v240
	ds_read_b128 v[130:133], v142
	ds_read_b128 v[134:137], v142 offset:1024
	ds_read_b128 v[138:141], v142 offset:2048
	ds_read_b128 v[142:145], v142 offset:3072
	ds_read_b128 v[146:149], v158
	ds_read_b128 v[150:153], v158 offset:1024
	ds_read_b128 v[154:157], v158 offset:2048
	ds_read_b128 v[158:161], v158 offset:3072
	s_add_u32 s6, s6, 0x100000
	s_addc_u32 s7, s7, 0
	s_mov_b32 m0, s91
	v_lshl_add_u64 v[216:217], s[6:7], 0, v[174:175]
	ds_read_b128 v[162:165], v243 offset:32768
	ds_read_b128 v[166:169], v243 offset:33792
	ds_read_b128 v[170:173], v243 offset:34816
	ds_read_b128 v[188:191], v243 offset:35840
	ds_read_b128 v[192:195], v243 offset:36864
	ds_read_b128 v[196:199], v243 offset:37888
	ds_read_b128 v[200:203], v243 offset:38912
	ds_read_b128 v[204:207], v243 offset:39936
	global_load_lds_dwordx4 v[216:217], off
	v_lshl_add_u64 v[216:217], s[6:7], 0, v[178:179]
	s_mov_b32 m0, s92
	s_nop 0
	global_load_lds_dwordx4 v[216:217], off
	s_waitcnt vmcnt(8)
	s_waitcnt lgkmcnt(0)
	s_barrier
	s_waitcnt lgkmcnt(0)
	v_mfma_f32_16x16x32_bf16 v[122:125], v[130:133], v[162:165], v[122:125]
	v_mfma_f32_16x16x32_bf16 v[126:129], v[138:141], v[162:165], v[126:129]
	v_mfma_f32_16x16x32_bf16 v[102:105], v[130:133], v[170:173], v[102:105]
	v_mfma_f32_16x16x32_bf16 v[98:101], v[138:141], v[170:173], v[98:101]
	v_mfma_f32_16x16x32_bf16 v[94:97], v[130:133], v[192:195], v[94:97]
	v_mfma_f32_16x16x32_bf16 v[86:89], v[138:141], v[192:195], v[86:89]
	v_mfma_f32_16x16x32_bf16 v[78:81], v[130:133], v[200:203], v[78:81]
	v_mfma_f32_16x16x32_bf16 v[70:73], v[138:141], v[200:203], v[70:73]
	v_mfma_f32_16x16x32_bf16 v[122:125], v[134:137], v[166:169], v[122:125]
	v_mfma_f32_16x16x32_bf16 v[126:129], v[142:145], v[166:169], v[126:129]
	v_mfma_f32_16x16x32_bf16 v[102:105], v[134:137], v[188:191], v[102:105]
	v_mfma_f32_16x16x32_bf16 v[98:101], v[142:145], v[188:191], v[98:101]
	v_mfma_f32_16x16x32_bf16 v[94:97], v[134:137], v[196:199], v[94:97]
	v_mfma_f32_16x16x32_bf16 v[86:89], v[142:145], v[196:199], v[86:89]
	v_mfma_f32_16x16x32_bf16 v[78:81], v[134:137], v[204:207], v[78:81]
	v_mfma_f32_16x16x32_bf16 v[70:73], v[142:145], v[204:207], v[70:73]
	v_mfma_f32_16x16x32_bf16 v[118:121], v[146:149], v[162:165], v[118:121]
	v_mfma_f32_16x16x32_bf16 v[114:117], v[154:157], v[162:165], v[114:117]
	v_mfma_f32_16x16x32_bf16 v[90:93], v[146:149], v[170:173], v[90:93]
	v_mfma_f32_16x16x32_bf16 v[82:85], v[154:157], v[170:173], v[82:85]
	v_mfma_f32_16x16x32_bf16 v[74:77], v[146:149], v[192:195], v[74:77]
	v_mfma_f32_16x16x32_bf16 v[66:69], v[154:157], v[192:195], v[66:69]
	v_mfma_f32_16x16x32_bf16 v[62:65], v[146:149], v[200:203], v[62:65]
	v_mfma_f32_16x16x32_bf16 v[58:61], v[154:157], v[200:203], v[58:61]
	v_mfma_f32_16x16x32_bf16 v[118:121], v[150:153], v[166:169], v[118:121]
	v_mfma_f32_16x16x32_bf16 v[114:117], v[158:161], v[166:169], v[114:117]
	v_mfma_f32_16x16x32_bf16 v[90:93], v[150:153], v[188:191], v[90:93]
	v_mfma_f32_16x16x32_bf16 v[82:85], v[158:161], v[188:191], v[82:85]
	v_mfma_f32_16x16x32_bf16 v[74:77], v[150:153], v[196:199], v[74:77]
	v_mfma_f32_16x16x32_bf16 v[66:69], v[158:161], v[196:199], v[66:69]
	v_mfma_f32_16x16x32_bf16 v[62:65], v[150:153], v[204:207], v[62:65]
	v_mfma_f32_16x16x32_bf16 v[58:61], v[158:161], v[204:207], v[58:61]
	s_barrier
; #define PG8_STAGE(bufoff, gbase, voff) do { _Pragma("unroll") for (int _i = 0; _i < 2; ++_i) \
;         __builtin_amdgcn_global_load_lds((const unsigned*)((const char*)(gbase) + (voff)[_i]), (LAS unsigned*)(lds + (bufoff) + ldsw + _i * 8192), 16, 0, 0); } while (0)
; #define PG8_LDA(dst, b, h) do { _Pragma("unroll") for (int m = 0; m < 4; ++m) _Pragma("unroll") for (int k = 0; k < 2; ++k) dst[m][k] = *(const LAS bf16x8*)(lds + PG8_SA(b, h) + aoff + m * 2048 + k * 1024); } while (0)
; #define PG8_LDB(dst, b, h) do { _Pragma("unroll") for (int n = 0; n < 2; ++n) _Pragma("unroll") for (int k = 0; k < 2; ++k) dst[n][k] = *(const LAS bf16x8*)(lds + PG8_SB(b, h) + boff + n * 2048 + k * 1024); } while (0)
; #define PG8_WAIT_V(n) asm volatile("s_waitcnt vmcnt(" #n ")" ::: "memory")
; template <class Epi, class Geom, class Sched, bool ALIGN_EPI, bool I8 = false>
; __device__ __forceinline__ void gemm_phase(LAS unsigned char* lds, const Gemm g, const Sched& S, const Epi& E) {
;     ...
;         for (int t = 0; t < nt; t += 2) {
;             const bool last = (t == nt - 2);
;             const char* a1 = cA + (size_t)(t + 1) * kstep;
;             const char* a2 = last ? nA : cA + (size_t)(t + 2) * kstep; const char* b2 = last ? nB : cB + (size_t)(t + 2) * kstep;
;             const char* a3 = a2 + kstep; const char* b3 = b2 + kstep;
;             PG8_LDB(B0, 0, 0); PG8_LDB(B1, 0, 1); PG8_SCHED; PG8_LDA(At, 0, 0); PG8_STAGE(PG8_SA(1, 1), a1 + hsA, voffA);
;             PG8_WAIT_V(8); PG8_WAIT_L(0); PG8_BAR; PG8_MMA(0, 0, At, B0); PG8_MMA(0, 1, At, B1); PG8_BAR; PG8_SCHED;
;             PG8_LDA(At, 0, 1); PG8_STAGE(PG8_SB(0, 0), b2, voffB); PG8_STAGE(PG8_SB(0, 1), b2 + hsB, voffB); PG8_STAGE(PG8_SA(0, 0), a2, voffA);
;             PG8_WAIT_V(8); PG8_WAIT_L(0); PG8_BAR; PG8_MMA(1, 0, At, B0); PG8_MMA(1, 1, At, B1); PG8_BAR; PG8_SCHED;
;             PG8_LDB(B0, 1, 0); PG8_LDB(B1, 1, 1); PG8_SCHED; PG8_LDA(At, 1, 0); PG8_STAGE(PG8_SA(0, 1), a2 + hsA, voffA);
;             PG8_WAIT_V(8); PG8_WAIT_L(0); PG8_BAR; PG8_MMA(0, 0, At, B0); PG8_MMA(0, 1, At, B1); PG8_BAR; PG8_SCHED;
;             PG8_LDA(At, 1, 1); PG8_STAGE(PG8_SB(1, 0), b3, voffB); PG8_STAGE(PG8_SB(1, 1), b3 + hsB, voffB); PG8_STAGE(PG8_SA(1, 0), a3, voffA);
;             PG8_WAIT_V(8); PG8_WAIT_L(0); PG8_BAR; PG8_MMA(1, 0, At, B0); PG8_MMA(1, 1, At, B1); PG8_BAR; PG8_SCHED;
;         }
	s_add_i32 s6, s14, s89
	v_lshl_add_u64 v[208:209], v[208:209], 0, s[28:29]
	s_mov_b32 m0, s6
	ds_read_b128 v[162:165], v243 offset:49152
	ds_read_b128 v[166:169], v243 offset:50176
	ds_read_b128 v[170:173], v243 offset:51200
	ds_read_b128 v[188:191], v243 offset:52224
	ds_read_b128 v[192:195], v243 offset:53248
	ds_read_b128 v[196:199], v243 offset:54272
	ds_read_b128 v[200:203], v243 offset:55296
	ds_read_b128 v[204:207], v243 offset:56320
	global_load_lds_dwordx4 v[208:209], off
	s_add_i32 m0, s6, 0x2000
	s_add_u32 s4, s4, 0x100080
	v_lshl_add_u64 v[208:209], v[210:211], 0, s[28:29]
	s_addc_u32 s5, s5, 0
	s_add_i32 s6, s15, s89
	global_load_lds_dwordx4 v[208:209], off
	v_lshl_add_u64 v[208:209], s[4:5], 0, v[176:177]
	s_mov_b32 m0, s6
	s_nop 0
	global_load_lds_dwordx4 v[208:209], off
	v_lshl_add_u64 v[208:209], s[4:5], 0, v[180:181]
	s_add_i32 m0, s6, 0x2000
	s_nop 0
	global_load_lds_dwordx4 v[208:209], off
	v_lshl_add_u64 v[208:209], v[212:213], 0, s[28:29]
	s_mov_b32 m0, s96
	s_nop 0
	global_load_lds_dwordx4 v[208:209], off
	v_lshl_add_u64 v[208:209], v[214:215], 0, s[28:29]
	s_mov_b32 m0, s97
	s_nop 0
	global_load_lds_dwordx4 v[208:209], off
	s_waitcnt vmcnt(8)
	s_waitcnt lgkmcnt(0)
	s_barrier
	s_waitcnt lgkmcnt(0)
	v_mfma_f32_16x16x32_bf16 v[54:57], v[130:133], v[162:165], v[54:57]
	v_mfma_f32_16x16x32_bf16 v[46:49], v[130:133], v[170:173], v[46:49]
	v_mfma_f32_16x16x32_bf16 v[30:33], v[130:133], v[192:195], v[30:33]
	v_mfma_f32_16x16x32_bf16 v[106:109], v[130:133], v[200:203], v[106:109]
	v_mfma_f32_16x16x32_bf16 v[54:57], v[134:137], v[166:169], v[54:57]
	v_mfma_f32_16x16x32_bf16 v[50:53], v[138:141], v[162:165], v[50:53]
	v_mfma_f32_16x16x32_bf16 v[46:49], v[134:137], v[188:191], v[46:49]
	v_mfma_f32_16x16x32_bf16 v[38:41], v[138:141], v[170:173], v[38:41]
	v_mfma_f32_16x16x32_bf16 v[30:33], v[134:137], v[196:199], v[30:33]
	v_mfma_f32_16x16x32_bf16 v[18:21], v[138:141], v[192:195], v[18:21]
	v_mfma_f32_16x16x32_bf16 v[134:137], v[134:137], v[204:207], v[106:109]
	v_mfma_f32_16x16x32_bf16 v[106:109], v[138:141], v[200:203], v[110:113]
	v_mfma_f32_16x16x32_bf16 v[50:53], v[142:145], v[166:169], v[50:53]
	v_mfma_f32_16x16x32_bf16 v[38:41], v[142:145], v[188:191], v[38:41]
	v_mfma_f32_16x16x32_bf16 v[18:21], v[142:145], v[196:199], v[18:21]
	v_mfma_f32_16x16x32_bf16 v[130:133], v[142:145], v[204:207], v[106:109]
	v_mfma_f32_16x16x32_bf16 v[42:45], v[146:149], v[162:165], v[42:45]
	v_mfma_f32_16x16x32_bf16 v[34:37], v[154:157], v[162:165], v[34:37]
	v_mfma_f32_16x16x32_bf16 v[26:29], v[146:149], v[170:173], v[26:29]
	v_mfma_f32_16x16x32_bf16 v[22:25], v[154:157], v[170:173], v[22:25]
	v_mfma_f32_16x16x32_bf16 v[14:17], v[146:149], v[192:195], v[14:17]
	v_mfma_f32_16x16x32_bf16 v[10:13], v[154:157], v[192:195], v[10:13]
	v_mfma_f32_16x16x32_bf16 v[6:9], v[146:149], v[200:203], v[6:9]
	v_mfma_f32_16x16x32_bf16 v[2:5], v[154:157], v[200:203], v[2:5]
	v_mfma_f32_16x16x32_bf16 v[42:45], v[150:153], v[166:169], v[42:45]
	v_mfma_f32_16x16x32_bf16 v[34:37], v[158:161], v[166:169], v[34:37]
	v_mfma_f32_16x16x32_bf16 v[26:29], v[150:153], v[188:191], v[26:29]
	v_mfma_f32_16x16x32_bf16 v[22:25], v[158:161], v[188:191], v[22:25]
	v_mfma_f32_16x16x32_bf16 v[14:17], v[150:153], v[196:199], v[14:17]
	v_mfma_f32_16x16x32_bf16 v[10:13], v[158:161], v[196:199], v[10:13]
	v_mfma_f32_16x16x32_bf16 v[6:9], v[150:153], v[204:207], v[6:9]
	v_mfma_f32_16x16x32_bf16 v[2:5], v[158:161], v[204:207], v[2:5]
	s_barrier
	s_add_i32 s13, s13, 2
	s_add_u32 s0, s0, 0x100
	s_addc_u32 s1, s1, 0
	s_add_u32 s11, s11, 0x100
	s_addc_u32 s12, s12, 0
	s_cmp_gt_u32 s13, 61
	s_cbranch_scc0 .LBB0_194
	s_and_b64 vcc, exec, s[84:85]
	s_cbranch_vccz .LBB0_197
	s_barrier

; #define PG8_STAGE(bufoff, gbase, voff) do { _Pragma("unroll") for (int _i = 0; _i < 2; ++_i) \
;         __builtin_amdgcn_global_load_lds((const unsigned*)((const char*)(gbase) + (voff)[_i]), (LAS unsigned*)(lds + (bufoff) + ldsw + _i * 8192), 16, 0, 0); } while (0)
; #define PG8_LDA(dst, b, h) do { _Pragma("unroll") for (int m = 0; m < 4; ++m) _Pragma("unroll") for (int k = 0; k < 2; ++k) dst[m][k] = *(const LAS bf16x8*)(lds + PG8_SA(b, h) + aoff + m * 2048 + k * 1024); } while (0)
; #define PG8_LDB(dst, b, h) do { _Pragma("unroll") for (int n = 0; n < 2; ++n) _Pragma("unroll") for (int k = 0; k < 2; ++k) dst[n][k] = *(const LAS bf16x8*)(lds + PG8_SB(b, h) + boff + n * 2048 + k * 1024); } while (0)
; #define PG8_WAIT_V(n) asm volatile("s_waitcnt vmcnt(" #n ")" ::: "memory")
; template <class Epi, class Geom, class Sched, bool ALIGN_EPI, bool I8 = false>
; __device__ __forceinline__ void gemm_phase(LAS unsigned char* lds, const Gemm g, const Sched& S, const Epi& E) {
;     ...
;         for (int t = 0; t < nt; t += 2) {
;             const bool last = (t == nt - 2);
;             const char* a1 = cA + (size_t)(t + 1) * kstep;
;             const char* a2 = last ? nA : cA + (size_t)(t + 2) * kstep; const char* b2 = last ? nB : cB + (size_t)(t + 2) * kstep;
;             const char* a3 = a2 + kstep; const char* b3 = b2 + kstep;
;             PG8_LDB(B0, 0, 0); PG8_LDB(B1, 0, 1); PG8_SCHED; PG8_LDA(At, 0, 0); PG8_STAGE(PG8_SA(1, 1), a1 + hsA, voffA);
;             PG8_WAIT_V(8); PG8_WAIT_L(0); PG8_BAR; PG8_MMA(0, 0, At, B0); PG8_MMA(0, 1, At, B1); PG8_BAR; PG8_SCHED;
;             PG8_LDA(At, 0, 1); PG8_STAGE(PG8_SB(0, 0), b2, voffB); PG8_STAGE(PG8_SB(0, 1), b2 + hsB, voffB); PG8_STAGE(PG8_SA(0, 0), a2, voffA);
;             PG8_WAIT_V(8); PG8_WAIT_L(0); PG8_BAR; PG8_MMA(1, 0, At, B0); PG8_MMA(1, 1, At, B1); PG8_BAR; PG8_SCHED;
;             PG8_LDB(B0, 1, 0); PG8_LDB(B1, 1, 1); PG8_SCHED; PG8_LDA(At, 1, 0); PG8_STAGE(PG8_SA(0, 1), a2 + hsA, voffA);
;             PG8_WAIT_V(8); PG8_WAIT_L(0); PG8_BAR; PG8_MMA(0, 0, At, B0); PG8_MMA(0, 1, At, B1); PG8_BAR; PG8_SCHED;
;             PG8_LDA(At, 1, 1); PG8_STAGE(PG8_SB(1, 0), b3, voffB); PG8_STAGE(PG8_SB(1, 1), b3 + hsB, voffB); PG8_STAGE(PG8_SA(1, 0), a3, voffA);
;             PG8_WAIT_V(8); PG8_WAIT_L(0); PG8_BAR; PG8_MMA(1, 0, At, B0); PG8_MMA(1, 1, At, B1); PG8_BAR; PG8_SCHED;
;         }
.LBB0_1860:
	s_add_u32 s35, s26, s34
	s_addc_u32 s40, s27, 0
	s_add_u32 s38, s35, 0x100
	s_addc_u32 s39, s40, 0
	s_and_b64 s[36:37], s[30:31], exec
	s_cselect_b32 s37, s1, s39
	s_cselect_b32 s36, s21, s38
	s_add_u32 s34, s2, s34
	s_addc_u32 s38, s3, 0
	s_add_u32 s34, s34, 0x100
	s_addc_u32 s38, s38, 0
	s_and_b64 s[30:31], s[30:31], exec
	s_cselect_b32 s39, s19, s38
	s_cselect_b32 s38, s63, s34
	s_add_u32 s42, s35, 0x80080
	ds_read_b128 v[50:53], v203
	ds_read_b128 v[54:57], v203 offset:1024
	ds_read_b128 v[58:61], v203 offset:2048
	ds_read_b128 v[122:125], v203 offset:3072
	ds_read_b128 v[126:129], v204
	ds_read_b128 v[130:133], v204 offset:1024
	ds_read_b128 v[168:171], v204 offset:2048
	ds_read_b128 v[172:175], v204 offset:3072
	s_addc_u32 s43, s40, 0
	s_add_i32 s73, s61, s50
	s_add_i32 m0, s53, 0xc000
	s_add_i32 s74, s53, 0xe000
	s_add_i32 s70, s73, 0x2000
	s_add_u32 s40, s38, 0x10000
	s_addc_u32 s41, s39, 0
	s_add_i32 s72, s62, s50
	s_add_i32 s71, s72, 0x2000
	s_add_i32 s69, 0, 0x18000
	s_add_i32 s68, 0, 0x1c000
	s_add_u32 s34, s36, 0x80000
	s_addc_u32 s35, s37, 0
	s_add_i32 s67, s69, s50
	s_add_i32 s65, s67, 0x2000
	s_add_u32 s30, s38, 0x10080
	s_addc_u32 s31, s39, 0
	s_add_i32 s66, s68, s50
	s_add_i32 s64, s66, 0x2000
	v_lshl_add_u64 v[216:217], s[42:43], 0, v[160:161]
	ds_read_b128 v[176:179], v205
	ds_read_b128 v[180:183], v205 offset:1024
	ds_read_b128 v[184:187], v205 offset:2048
	ds_read_b128 v[188:191], v205 offset:3072
	ds_read_b128 v[192:195], v205 offset:4096
	ds_read_b128 v[196:199], v205 offset:5120
	ds_read_b128 v[208:211], v205 offset:6144
	ds_read_b128 v[212:215], v205 offset:7168
	global_load_lds_dwordx4 v[216:217], off
	v_lshl_add_u64 v[216:217], s[42:43], 0, v[156:157]
	s_mov_b32 m0, s74
	s_nop 0
	global_load_lds_dwordx4 v[216:217], off
	s_waitcnt vmcnt(8)
	s_waitcnt lgkmcnt(0)
	s_barrier
	s_waitcnt lgkmcnt(0)
	v_mfma_f32_16x16x32_bf16 v[150:153], v[50:53], v[176:179], v[150:153]
	v_mfma_f32_16x16x32_bf16 v[74:77], v[58:61], v[176:179], v[74:77]
	v_mfma_f32_16x16x32_bf16 v[142:145], v[50:53], v[184:187], v[142:145]
	v_mfma_f32_16x16x32_bf16 v[66:69], v[58:61], v[184:187], v[66:69]
	v_mfma_f32_16x16x32_bf16 v[134:137], v[50:53], v[192:195], v[134:137]
	v_mfma_f32_16x16x32_bf16 v[46:49], v[58:61], v[192:195], v[46:49]
	v_mfma_f32_16x16x32_bf16 v[114:117], v[50:53], v[208:211], v[114:117]
	v_mfma_f32_16x16x32_bf16 v[38:41], v[58:61], v[208:211], v[38:41]
	v_mfma_f32_16x16x32_bf16 v[150:153], v[54:57], v[180:183], v[150:153]
	v_mfma_f32_16x16x32_bf16 v[74:77], v[122:125], v[180:183], v[74:77]
	v_mfma_f32_16x16x32_bf16 v[142:145], v[54:57], v[188:191], v[142:145]
	v_mfma_f32_16x16x32_bf16 v[66:69], v[122:125], v[188:191], v[66:69]
	v_mfma_f32_16x16x32_bf16 v[134:137], v[54:57], v[196:199], v[134:137]
	v_mfma_f32_16x16x32_bf16 v[46:49], v[122:125], v[196:199], v[46:49]
	v_mfma_f32_16x16x32_bf16 v[114:117], v[54:57], v[212:215], v[114:117]
	v_mfma_f32_16x16x32_bf16 v[38:41], v[122:125], v[212:215], v[38:41]
	v_mfma_f32_16x16x32_bf16 v[146:149], v[126:129], v[176:179], v[146:149]
	v_mfma_f32_16x16x32_bf16 v[70:73], v[168:171], v[176:179], v[70:73]
	v_mfma_f32_16x16x32_bf16 v[138:141], v[126:129], v[184:187], v[138:141]
	v_mfma_f32_16x16x32_bf16 v[62:65], v[168:171], v[184:187], v[62:65]
	v_mfma_f32_16x16x32_bf16 v[118:121], v[126:129], v[192:195], v[118:121]
	v_mfma_f32_16x16x32_bf16 v[42:45], v[168:171], v[192:195], v[42:45]
	v_mfma_f32_16x16x32_bf16 v[110:113], v[126:129], v[208:211], v[110:113]
	v_mfma_f32_16x16x32_bf16 v[34:37], v[168:171], v[208:211], v[34:37]
	v_mfma_f32_16x16x32_bf16 v[146:149], v[130:133], v[180:183], v[146:149]
	v_mfma_f32_16x16x32_bf16 v[70:73], v[172:175], v[180:183], v[70:73]
	v_mfma_f32_16x16x32_bf16 v[138:141], v[130:133], v[188:191], v[138:141]
	v_mfma_f32_16x16x32_bf16 v[62:65], v[172:175], v[188:191], v[62:65]
	v_mfma_f32_16x16x32_bf16 v[118:121], v[130:133], v[196:199], v[118:121]
	v_mfma_f32_16x16x32_bf16 v[42:45], v[172:175], v[196:199], v[42:45]
	v_mfma_f32_16x16x32_bf16 v[110:113], v[130:133], v[212:215], v[110:113]
	v_mfma_f32_16x16x32_bf16 v[34:37], v[172:175], v[212:215], v[34:37]
	s_barrier
	s_mov_b32 m0, s73
	v_lshl_add_u64 v[216:217], s[38:39], 0, v[158:159]
	ds_read_b128 v[176:179], v205 offset:16384
	ds_read_b128 v[180:183], v205 offset:17408
	ds_read_b128 v[184:187], v205 offset:18432
	ds_read_b128 v[188:191], v205 offset:19456
	ds_read_b128 v[192:195], v205 offset:20480
	ds_read_b128 v[196:199], v205 offset:21504
	ds_read_b128 v[208:211], v205 offset:22528
	ds_read_b128 v[212:215], v205 offset:23552
	global_load_lds_dwordx4 v[216:217], off
	v_lshl_add_u64 v[218:219], s[38:39], 0, v[154:155]
	s_mov_b32 m0, s70
	v_lshl_add_u64 v[220:221], s[40:41], 0, v[158:159]
	global_load_lds_dwordx4 v[218:219], off
	s_mov_b32 m0, s72
	v_lshl_add_u64 v[222:223], s[36:37], 0, v[156:157]
	global_load_lds_dwordx4 v[220:221], off
	v_lshl_add_u64 v[220:221], s[40:41], 0, v[154:155]
	s_mov_b32 m0, s71
	s_nop 0
	global_load_lds_dwordx4 v[220:221], off
	v_lshl_add_u64 v[220:221], s[36:37], 0, v[160:161]
	s_mov_b32 m0, s53
	s_nop 0
	global_load_lds_dwordx4 v[220:221], off
	s_mov_b32 m0, s54
	s_nop 0
	global_load_lds_dwordx4 v[222:223], off
	s_waitcnt vmcnt(8)
	s_waitcnt lgkmcnt(0)
	s_barrier
; #define PG8_STAGE(bufoff, gbase, voff) do { _Pragma("unroll") for (int _i = 0; _i < 2; ++_i) \
;         __builtin_amdgcn_global_load_lds((const unsigned*)((const char*)(gbase) + (voff)[_i]), (LAS unsigned*)(lds + (bufoff) + ldsw + _i * 8192), 16, 0, 0); } while (0)
; #define PG8_LDA(dst, b, h) do { _Pragma("unroll") for (int m = 0; m < 4; ++m) _Pragma("unroll") for (int k = 0; k < 2; ++k) dst[m][k] = *(const LAS bf16x8*)(lds + PG8_SA(b, h) + aoff + m * 2048 + k * 1024); } while (0)
; #define PG8_LDB(dst, b, h) do { _Pragma("unroll") for (int n = 0; n < 2; ++n) _Pragma("unroll") for (int k = 0; k < 2; ++k) dst[n][k] = *(const LAS bf16x8*)(lds + PG8_SB(b, h) + boff + n * 2048 + k * 1024); } while (0)
; #define PG8_WAIT_V(n) asm volatile("s_waitcnt vmcnt(" #n ")" ::: "memory")
; template <class Epi, class Geom, class Sched, bool ALIGN_EPI, bool I8 = false>
; __device__ __forceinline__ void gemm_phase(LAS unsigned char* lds, const Gemm g, const Sched& S, const Epi& E) {
;     ...
;         for (int t = 0; t < nt; t += 2) {
;             const bool last = (t == nt - 2);
;             const char* a1 = cA + (size_t)(t + 1) * kstep;
;             const char* a2 = last ? nA : cA + (size_t)(t + 2) * kstep; const char* b2 = last ? nB : cB + (size_t)(t + 2) * kstep;
;             const char* a3 = a2 + kstep; const char* b3 = b2 + kstep;
;             PG8_LDB(B0, 0, 0); PG8_LDB(B1, 0, 1); PG8_SCHED; PG8_LDA(At, 0, 0); PG8_STAGE(PG8_SA(1, 1), a1 + hsA, voffA);
;             PG8_WAIT_V(8); PG8_WAIT_L(0); PG8_BAR; PG8_MMA(0, 0, At, B0); PG8_MMA(0, 1, At, B1); PG8_BAR; PG8_SCHED;
;             PG8_LDA(At, 0, 1); PG8_STAGE(PG8_SB(0, 0), b2, voffB); PG8_STAGE(PG8_SB(0, 1), b2 + hsB, voffB); PG8_STAGE(PG8_SA(0, 0), a2, voffA);
;             PG8_WAIT_V(8); PG8_WAIT_L(0); PG8_BAR; PG8_MMA(1, 0, At, B0); PG8_MMA(1, 1, At, B1); PG8_BAR; PG8_SCHED;
;             PG8_LDB(B0, 1, 0); PG8_LDB(B1, 1, 1); PG8_SCHED; PG8_LDA(At, 1, 0); PG8_STAGE(PG8_SA(0, 1), a2 + hsA, voffA);
;             PG8_WAIT_V(8); PG8_WAIT_L(0); PG8_BAR; PG8_MMA(0, 0, At, B0); PG8_MMA(0, 1, At, B1); PG8_BAR; PG8_SCHED;
;             PG8_LDA(At, 1, 1); PG8_STAGE(PG8_SB(1, 0), b3, voffB); PG8_STAGE(PG8_SB(1, 1), b3 + hsB, voffB); PG8_STAGE(PG8_SA(1, 0), a3, voffA);
;             PG8_WAIT_V(8); PG8_WAIT_L(0); PG8_BAR; PG8_MMA(1, 0, At, B0); PG8_MMA(1, 1, At, B1); PG8_BAR; PG8_SCHED;
;         }
	s_waitcnt lgkmcnt(0)
	v_mfma_f32_16x16x32_bf16 v[106:109], v[50:53], v[176:179], v[106:109]
	v_mfma_f32_16x16x32_bf16 v[30:33], v[58:61], v[176:179], v[30:33]
	v_mfma_f32_16x16x32_bf16 v[98:101], v[50:53], v[184:187], v[98:101]
	v_mfma_f32_16x16x32_bf16 v[22:25], v[58:61], v[184:187], v[22:25]
	v_mfma_f32_16x16x32_bf16 v[90:93], v[50:53], v[192:195], v[90:93]
	v_mfma_f32_16x16x32_bf16 v[14:17], v[58:61], v[192:195], v[14:17]
	v_mfma_f32_16x16x32_bf16 v[6:9], v[58:61], v[208:211], v[6:9]
	v_mfma_f32_16x16x32_bf16 v[106:109], v[54:57], v[180:183], v[106:109]
	v_mfma_f32_16x16x32_bf16 v[30:33], v[122:125], v[180:183], v[30:33]
	v_mfma_f32_16x16x32_bf16 v[98:101], v[54:57], v[188:191], v[98:101]
	v_mfma_f32_16x16x32_bf16 v[22:25], v[122:125], v[188:191], v[22:25]
	v_mfma_f32_16x16x32_bf16 v[90:93], v[54:57], v[196:199], v[90:93]
	v_mfma_f32_16x16x32_bf16 v[14:17], v[122:125], v[196:199], v[14:17]
	v_mfma_f32_16x16x32_bf16 v[50:53], v[50:53], v[208:211], v[82:85]
	v_mfma_f32_16x16x32_bf16 v[6:9], v[122:125], v[212:215], v[6:9]
	v_mfma_f32_16x16x32_bf16 v[50:53], v[54:57], v[212:215], v[50:53]
	v_mfma_f32_16x16x32_bf16 v[26:29], v[168:171], v[176:179], v[26:29]
	v_mfma_f32_16x16x32_bf16 v[18:21], v[168:171], v[184:187], v[18:21]
	v_mfma_f32_16x16x32_bf16 v[82:85], v[126:129], v[192:195], v[86:89]
	v_mfma_f32_16x16x32_bf16 v[10:13], v[168:171], v[192:195], v[10:13]
	v_mfma_f32_16x16x32_bf16 v[78:81], v[126:129], v[208:211], v[78:81]
	v_mfma_f32_16x16x32_bf16 v[2:5], v[168:171], v[208:211], v[2:5]
	v_mfma_f32_16x16x32_bf16 v[54:57], v[126:129], v[176:179], v[102:105]
	v_mfma_f32_16x16x32_bf16 v[26:29], v[172:175], v[180:183], v[26:29]
	v_mfma_f32_16x16x32_bf16 v[58:61], v[126:129], v[184:187], v[94:97]
	v_mfma_f32_16x16x32_bf16 v[18:21], v[172:175], v[188:191], v[18:21]
	v_mfma_f32_16x16x32_bf16 v[86:89], v[130:133], v[196:199], v[82:85]
	v_mfma_f32_16x16x32_bf16 v[10:13], v[172:175], v[196:199], v[10:13]
	v_mfma_f32_16x16x32_bf16 v[78:81], v[130:133], v[212:215], v[78:81]
	v_mfma_f32_16x16x32_bf16 v[2:5], v[172:175], v[212:215], v[2:5]
	v_mfma_f32_16x16x32_bf16 v[54:57], v[130:133], v[180:183], v[54:57]
	v_mfma_f32_16x16x32_bf16 v[58:61], v[130:133], v[188:191], v[58:61]
	s_barrier
	v_add_u32_e32 v122, s69, v200
	v_add_u32_e32 v162, s68, v200
	ds_read_b128 v[82:85], v122
	ds_read_b128 v[94:97], v122 offset:1024
	ds_read_b128 v[102:105], v122 offset:2048
	ds_read_b128 v[122:125], v122 offset:3072
	ds_read_b128 v[126:129], v162
	ds_read_b128 v[130:133], v162 offset:1024
	ds_read_b128 v[168:171], v162 offset:2048
	ds_read_b128 v[172:175], v162 offset:3072
	s_mov_b32 m0, s55
	v_lshl_add_u64 v[224:225], s[34:35], 0, v[160:161]
	ds_read_b128 v[176:179], v205 offset:32768
	ds_read_b128 v[180:183], v205 offset:33792
	ds_read_b128 v[184:187], v205 offset:34816
	ds_read_b128 v[188:191], v205 offset:35840
	ds_read_b128 v[192:195], v205 offset:36864
	ds_read_b128 v[196:199], v205 offset:37888
	ds_read_b128 v[208:211], v205 offset:38912
	ds_read_b128 v[212:215], v205 offset:39936
	global_load_lds_dwordx4 v[224:225], off
	v_lshl_add_u64 v[224:225], s[34:35], 0, v[156:157]
	s_mov_b32 m0, s56
	s_nop 0
	global_load_lds_dwordx4 v[224:225], off
	s_waitcnt vmcnt(8)
	s_waitcnt lgkmcnt(0)
	s_barrier
	s_waitcnt lgkmcnt(0)
	v_mfma_f32_16x16x32_bf16 v[150:153], v[82:85], v[176:179], v[150:153]
	v_mfma_f32_16x16x32_bf16 v[74:77], v[102:105], v[176:179], v[74:77]
	v_mfma_f32_16x16x32_bf16 v[142:145], v[82:85], v[184:187], v[142:145]
	v_mfma_f32_16x16x32_bf16 v[66:69], v[102:105], v[184:187], v[66:69]
	v_mfma_f32_16x16x32_bf16 v[134:137], v[82:85], v[192:195], v[134:137]
	v_mfma_f32_16x16x32_bf16 v[46:49], v[102:105], v[192:195], v[46:49]
	v_mfma_f32_16x16x32_bf16 v[114:117], v[82:85], v[208:211], v[114:117]
	v_mfma_f32_16x16x32_bf16 v[38:41], v[102:105], v[208:211], v[38:41]
	v_mfma_f32_16x16x32_bf16 v[150:153], v[94:97], v[180:183], v[150:153]
	v_mfma_f32_16x16x32_bf16 v[74:77], v[122:125], v[180:183], v[74:77]
	v_mfma_f32_16x16x32_bf16 v[142:145], v[94:97], v[188:191], v[142:145]
	v_mfma_f32_16x16x32_bf16 v[66:69], v[122:125], v[188:191], v[66:69]
	v_mfma_f32_16x16x32_bf16 v[134:137], v[94:97], v[196:199], v[134:137]
	v_mfma_f32_16x16x32_bf16 v[46:49], v[122:125], v[196:199], v[46:49]
	v_mfma_f32_16x16x32_bf16 v[114:117], v[94:97], v[212:215], v[114:117]
	v_mfma_f32_16x16x32_bf16 v[38:41], v[122:125], v[212:215], v[38:41]
	v_mfma_f32_16x16x32_bf16 v[146:149], v[126:129], v[176:179], v[146:149]
	v_mfma_f32_16x16x32_bf16 v[70:73], v[168:171], v[176:179], v[70:73]
	v_mfma_f32_16x16x32_bf16 v[138:141], v[126:129], v[184:187], v[138:141]
	v_mfma_f32_16x16x32_bf16 v[62:65], v[168:171], v[184:187], v[62:65]
	v_mfma_f32_16x16x32_bf16 v[118:121], v[126:129], v[192:195], v[118:121]
	v_mfma_f32_16x16x32_bf16 v[42:45], v[168:171], v[192:195], v[42:45]
	v_mfma_f32_16x16x32_bf16 v[110:113], v[126:129], v[208:211], v[110:113]
	v_mfma_f32_16x16x32_bf16 v[34:37], v[168:171], v[208:211], v[34:37]
	v_mfma_f32_16x16x32_bf16 v[146:149], v[130:133], v[180:183], v[146:149]
	v_mfma_f32_16x16x32_bf16 v[70:73], v[172:175], v[180:183], v[70:73]
	v_mfma_f32_16x16x32_bf16 v[138:141], v[130:133], v[188:191], v[138:141]
	v_mfma_f32_16x16x32_bf16 v[62:65], v[172:175], v[188:191], v[62:65]
	v_mfma_f32_16x16x32_bf16 v[118:121], v[130:133], v[196:199], v[118:121]
	v_mfma_f32_16x16x32_bf16 v[42:45], v[172:175], v[196:199], v[42:45]
	v_mfma_f32_16x16x32_bf16 v[110:113], v[130:133], v[212:215], v[110:113]
	v_mfma_f32_16x16x32_bf16 v[34:37], v[172:175], v[212:215], v[34:37]
	s_barrier
; #define PG8_STAGE(bufoff, gbase, voff) do { _Pragma("unroll") for (int _i = 0; _i < 2; ++_i) \
;         __builtin_amdgcn_global_load_lds((const unsigned*)((const char*)(gbase) + (voff)[_i]), (LAS unsigned*)(lds + (bufoff) + ldsw + _i * 8192), 16, 0, 0); } while (0)
; #define PG8_LDA(dst, b, h) do { _Pragma("unroll") for (int m = 0; m < 4; ++m) _Pragma("unroll") for (int k = 0; k < 2; ++k) dst[m][k] = *(const LAS bf16x8*)(lds + PG8_SA(b, h) + aoff + m * 2048 + k * 1024); } while (0)
; #define PG8_LDB(dst, b, h) do { _Pragma("unroll") for (int n = 0; n < 2; ++n) _Pragma("unroll") for (int k = 0; k < 2; ++k) dst[n][k] = *(const LAS bf16x8*)(lds + PG8_SB(b, h) + boff + n * 2048 + k * 1024); } while (0)
; #define PG8_WAIT_V(n) asm volatile("s_waitcnt vmcnt(" #n ")" ::: "memory")
; template <class Epi, class Geom, class Sched, bool ALIGN_EPI, bool I8 = false>
; __device__ __forceinline__ void gemm_phase(LAS unsigned char* lds, const Gemm g, const Sched& S, const Epi& E) {
;     ...
;         for (int t = 0; t < nt; t += 2) {
;             const bool last = (t == nt - 2);
;             const char* a1 = cA + (size_t)(t + 1) * kstep;
;             const char* a2 = last ? nA : cA + (size_t)(t + 2) * kstep; const char* b2 = last ? nB : cB + (size_t)(t + 2) * kstep;
;             const char* a3 = a2 + kstep; const char* b3 = b2 + kstep;
;             PG8_LDB(B0, 0, 0); PG8_LDB(B1, 0, 1); PG8_SCHED; PG8_LDA(At, 0, 0); PG8_STAGE(PG8_SA(1, 1), a1 + hsA, voffA);
;             PG8_WAIT_V(8); PG8_WAIT_L(0); PG8_BAR; PG8_MMA(0, 0, At, B0); PG8_MMA(0, 1, At, B1); PG8_BAR; PG8_SCHED;
;             PG8_LDA(At, 0, 1); PG8_STAGE(PG8_SB(0, 0), b2, voffB); PG8_STAGE(PG8_SB(0, 1), b2 + hsB, voffB); PG8_STAGE(PG8_SA(0, 0), a2, voffA);
;             PG8_WAIT_V(8); PG8_WAIT_L(0); PG8_BAR; PG8_MMA(1, 0, At, B0); PG8_MMA(1, 1, At, B1); PG8_BAR; PG8_SCHED;
;             PG8_LDB(B0, 1, 0); PG8_LDB(B1, 1, 1); PG8_SCHED; PG8_LDA(At, 1, 0); PG8_STAGE(PG8_SA(0, 1), a2 + hsA, voffA);
;             PG8_WAIT_V(8); PG8_WAIT_L(0); PG8_BAR; PG8_MMA(0, 0, At, B0); PG8_MMA(0, 1, At, B1); PG8_BAR; PG8_SCHED;
;             PG8_LDA(At, 1, 1); PG8_STAGE(PG8_SB(1, 0), b3, voffB); PG8_STAGE(PG8_SB(1, 1), b3 + hsB, voffB); PG8_STAGE(PG8_SA(1, 0), a3, voffA);
;             PG8_WAIT_V(8); PG8_WAIT_L(0); PG8_BAR; PG8_MMA(1, 0, At, B0); PG8_MMA(1, 1, At, B1); PG8_BAR; PG8_SCHED;
;         }
	s_mov_b32 m0, s67
	v_lshl_add_u64 v[216:217], v[216:217], 0, s[14:15]
	ds_read_b128 v[176:179], v205 offset:49152
	ds_read_b128 v[180:183], v205 offset:50176
	ds_read_b128 v[184:187], v205 offset:51200
	ds_read_b128 v[188:191], v205 offset:52224
	ds_read_b128 v[192:195], v205 offset:53248
	ds_read_b128 v[196:199], v205 offset:54272
	ds_read_b128 v[208:211], v205 offset:55296
	ds_read_b128 v[212:215], v205 offset:56320
	global_load_lds_dwordx4 v[216:217], off
	v_lshl_add_u64 v[216:217], v[218:219], 0, s[14:15]
	s_mov_b32 m0, s65
	s_nop 0
	global_load_lds_dwordx4 v[216:217], off
	v_lshl_add_u64 v[216:217], s[30:31], 0, v[158:159]
	s_mov_b32 m0, s66
	s_nop 0
	global_load_lds_dwordx4 v[216:217], off
	v_lshl_add_u64 v[216:217], s[30:31], 0, v[154:155]
	s_mov_b32 m0, s64
	s_nop 0
	global_load_lds_dwordx4 v[216:217], off
	v_lshl_add_u64 v[216:217], v[220:221], 0, s[14:15]
	s_mov_b32 m0, s58
	s_nop 0
	global_load_lds_dwordx4 v[216:217], off
	v_lshl_add_u64 v[216:217], v[222:223], 0, s[14:15]
	s_mov_b32 m0, s59
	s_nop 0
	global_load_lds_dwordx4 v[216:217], off
	s_waitcnt vmcnt(8)
	s_waitcnt lgkmcnt(0)
	s_barrier
	s_waitcnt lgkmcnt(0)
	v_mfma_f32_16x16x32_bf16 v[106:109], v[82:85], v[176:179], v[106:109]
	v_mfma_f32_16x16x32_bf16 v[30:33], v[102:105], v[176:179], v[30:33]
	v_mfma_f32_16x16x32_bf16 v[98:101], v[82:85], v[184:187], v[98:101]
	v_mfma_f32_16x16x32_bf16 v[22:25], v[102:105], v[184:187], v[22:25]
	v_mfma_f32_16x16x32_bf16 v[90:93], v[82:85], v[192:195], v[90:93]
	v_mfma_f32_16x16x32_bf16 v[14:17], v[102:105], v[192:195], v[14:17]
	v_mfma_f32_16x16x32_bf16 v[50:53], v[82:85], v[208:211], v[50:53]
	v_mfma_f32_16x16x32_bf16 v[6:9], v[102:105], v[208:211], v[6:9]
	v_mfma_f32_16x16x32_bf16 v[106:109], v[94:97], v[180:183], v[106:109]
	v_mfma_f32_16x16x32_bf16 v[30:33], v[122:125], v[180:183], v[30:33]
	v_mfma_f32_16x16x32_bf16 v[98:101], v[94:97], v[188:191], v[98:101]
	v_mfma_f32_16x16x32_bf16 v[22:25], v[122:125], v[188:191], v[22:25]
	v_mfma_f32_16x16x32_bf16 v[90:93], v[94:97], v[196:199], v[90:93]
	v_mfma_f32_16x16x32_bf16 v[14:17], v[122:125], v[196:199], v[14:17]
	v_mfma_f32_16x16x32_bf16 v[82:85], v[94:97], v[212:215], v[50:53]
	v_mfma_f32_16x16x32_bf16 v[6:9], v[122:125], v[212:215], v[6:9]
	v_mfma_f32_16x16x32_bf16 v[50:53], v[126:129], v[176:179], v[54:57]
	v_mfma_f32_16x16x32_bf16 v[102:105], v[130:133], v[180:183], v[50:53]
	v_mfma_f32_16x16x32_bf16 v[50:53], v[126:129], v[184:187], v[58:61]
	v_mfma_f32_16x16x32_bf16 v[94:97], v[130:133], v[188:191], v[50:53]
	v_mfma_f32_16x16x32_bf16 v[50:53], v[126:129], v[192:195], v[86:89]
	v_mfma_f32_16x16x32_bf16 v[26:29], v[168:171], v[176:179], v[26:29]
	v_mfma_f32_16x16x32_bf16 v[18:21], v[168:171], v[184:187], v[18:21]
	v_mfma_f32_16x16x32_bf16 v[86:89], v[130:133], v[196:199], v[50:53]
	v_mfma_f32_16x16x32_bf16 v[10:13], v[168:171], v[192:195], v[10:13]
	v_mfma_f32_16x16x32_bf16 v[50:53], v[126:129], v[208:211], v[78:81]
	v_mfma_f32_16x16x32_bf16 v[2:5], v[168:171], v[208:211], v[2:5]
	v_mfma_f32_16x16x32_bf16 v[26:29], v[172:175], v[180:183], v[26:29]
	v_mfma_f32_16x16x32_bf16 v[18:21], v[172:175], v[188:191], v[18:21]
	v_mfma_f32_16x16x32_bf16 v[10:13], v[172:175], v[196:199], v[10:13]
	v_mfma_f32_16x16x32_bf16 v[78:81], v[130:133], v[212:215], v[50:53]
	v_mfma_f32_16x16x32_bf16 v[2:5], v[172:175], v[212:215], v[2:5]
	s_barrier
	s_movk_i32 s34, 0x100
	s_andn2_b64 vcc, exec, s[28:29]
	s_mov_b64 s[30:31], -1
	s_mov_b64 s[28:29], 0
	s_cbranch_vccz .LBB0_1860
	s_and_b64 vcc, exec, s[16:17]
	s_cbranch_vccz .LBB0_1863
	s_barrier

; #define PG8_STAGE(bufoff, gbase, voff) do { _Pragma("unroll") for (int _i = 0; _i < 2; ++_i) \
;         __builtin_amdgcn_global_load_lds((const unsigned*)((const char*)(gbase) + (voff)[_i]), (LAS unsigned*)(lds + (bufoff) + ldsw + _i * 8192), 16, 0, 0); } while (0)
; #define PG8_LDA(dst, b, h) do { _Pragma("unroll") for (int m = 0; m < 4; ++m) _Pragma("unroll") for (int k = 0; k < 2; ++k) dst[m][k] = *(const LAS bf16x8*)(lds + PG8_SA(b, h) + aoff + m * 2048 + k * 1024); } while (0)
; #define PG8_LDB(dst, b, h) do { _Pragma("unroll") for (int n = 0; n < 2; ++n) _Pragma("unroll") for (int k = 0; k < 2; ++k) dst[n][k] = *(const LAS bf16x8*)(lds + PG8_SB(b, h) + boff + n * 2048 + k * 1024); } while (0)
; #define PG8_WAIT_V(n) asm volatile("s_waitcnt vmcnt(" #n ")" ::: "memory")
; template <class Epi, class Geom, class Sched, bool ALIGN_EPI, bool I8 = false>
; __device__ __forceinline__ void gemm_phase(LAS unsigned char* lds, const Gemm g, const Sched& S, const Epi& E) {
;     ...
;         for (int t = 0; t < nt; t += 2) {
;             const bool last = (t == nt - 2);
;             const char* a1 = cA + (size_t)(t + 1) * kstep;
;             const char* a2 = last ? nA : cA + (size_t)(t + 2) * kstep; const char* b2 = last ? nB : cB + (size_t)(t + 2) * kstep;
;             const char* a3 = a2 + kstep; const char* b3 = b2 + kstep;
;             PG8_LDB(B0, 0, 0); PG8_LDB(B1, 0, 1); PG8_SCHED; PG8_LDA(At, 0, 0); PG8_STAGE(PG8_SA(1, 1), a1 + hsA, voffA);
;             PG8_WAIT_V(8); PG8_WAIT_L(0); PG8_BAR; PG8_MMA(0, 0, At, B0); PG8_MMA(0, 1, At, B1); PG8_BAR; PG8_SCHED;
;             PG8_LDA(At, 0, 1); PG8_STAGE(PG8_SB(0, 0), b2, voffB); PG8_STAGE(PG8_SB(0, 1), b2 + hsB, voffB); PG8_STAGE(PG8_SA(0, 0), a2, voffA);
;             PG8_WAIT_V(8); PG8_WAIT_L(0); PG8_BAR; PG8_MMA(1, 0, At, B0); PG8_MMA(1, 1, At, B1); PG8_BAR; PG8_SCHED;
;             PG8_LDB(B0, 1, 0); PG8_LDB(B1, 1, 1); PG8_SCHED; PG8_LDA(At, 1, 0); PG8_STAGE(PG8_SA(0, 1), a2 + hsA, voffA);
;             PG8_WAIT_V(8); PG8_WAIT_L(0); PG8_BAR; PG8_MMA(0, 0, At, B0); PG8_MMA(0, 1, At, B1); PG8_BAR; PG8_SCHED;
;             PG8_LDA(At, 1, 1); PG8_STAGE(PG8_SB(1, 0), b3, voffB); PG8_STAGE(PG8_SB(1, 1), b3 + hsB, voffB); PG8_STAGE(PG8_SA(1, 0), a3, voffA);
;             PG8_WAIT_V(8); PG8_WAIT_L(0); PG8_BAR; PG8_MMA(1, 0, At, B0); PG8_MMA(1, 1, At, B1); PG8_BAR; PG8_SCHED;
;         }
.LBB0_2231:
	ds_read_b128 v[102:105], v166
	ds_read_b128 v[106:109], v166 offset:1024
	ds_read_b128 v[114:117], v166 offset:2048
	ds_read_b128 v[118:121], v166 offset:3072
	ds_read_b128 v[156:159], v167
	ds_read_b128 v[170:173], v167 offset:1024
	ds_read_b128 v[174:177], v167 offset:2048
	ds_read_b128 v[178:181], v167 offset:3072
	s_add_u32 s34, s30, 0xfff80080
	s_addc_u32 s35, s31, -1
	s_cmp_eq_u32 s61, 28
	s_cselect_b32 s37, s23, s35
	s_cselect_b32 s36, s57, s34
	s_cselect_b32 s35, s21, s60
	s_cselect_b32 s34, s58, s59
	v_lshl_add_u64 v[160:161], s[30:31], 0, v[150:151]
	s_add_i32 m0, s29, 0xc000
	ds_read_b128 v[182:185], v168
	ds_read_b128 v[186:189], v168 offset:1024
	ds_read_b128 v[190:193], v168 offset:2048
	ds_read_b128 v[194:197], v168 offset:3072
	ds_read_b128 v[198:201], v168 offset:4096
	ds_read_b128 v[202:205], v168 offset:5120
	ds_read_b128 v[206:209], v168 offset:6144
	ds_read_b128 v[210:213], v168 offset:7168
	global_load_lds_dwordx4 v[160:161], off
	v_lshl_add_u64 v[160:161], s[30:31], 0, v[152:153]
	s_add_i32 m0, s29, 0xe000
	s_nop 0
	global_load_lds_dwordx4 v[160:161], off
	s_waitcnt vmcnt(8)
	s_waitcnt lgkmcnt(0)
	s_barrier
	s_waitcnt lgkmcnt(0)
	v_mfma_i32_16x16x64_i8 v[142:145], v[102:105], v[182:185], v[142:145]
	v_mfma_i32_16x16x64_i8 v[138:141], v[114:117], v[182:185], v[138:141]
	v_mfma_i32_16x16x64_i8 v[126:129], v[102:105], v[190:193], v[126:129]
	v_mfma_i32_16x16x64_i8 v[122:125], v[114:117], v[190:193], v[122:125]
	v_mfma_i32_16x16x64_i8 v[94:97], v[102:105], v[198:201], v[94:97]
	v_mfma_i32_16x16x64_i8 v[90:93], v[114:117], v[198:201], v[90:93]
	v_mfma_i32_16x16x64_i8 v[82:85], v[102:105], v[206:209], v[82:85]
	v_mfma_i32_16x16x64_i8 v[74:77], v[114:117], v[206:209], v[74:77]
	v_mfma_i32_16x16x64_i8 v[142:145], v[106:109], v[186:189], v[142:145]
	v_mfma_i32_16x16x64_i8 v[138:141], v[118:121], v[186:189], v[138:141]
	v_mfma_i32_16x16x64_i8 v[126:129], v[106:109], v[194:197], v[126:129]
	v_mfma_i32_16x16x64_i8 v[122:125], v[118:121], v[194:197], v[122:125]
	v_mfma_i32_16x16x64_i8 v[94:97], v[106:109], v[202:205], v[94:97]
	v_mfma_i32_16x16x64_i8 v[90:93], v[118:121], v[202:205], v[90:93]
	v_mfma_i32_16x16x64_i8 v[82:85], v[106:109], v[210:213], v[82:85]
	v_mfma_i32_16x16x64_i8 v[74:77], v[118:121], v[210:213], v[74:77]
	v_mfma_i32_16x16x64_i8 v[134:137], v[156:159], v[182:185], v[134:137]
	v_mfma_i32_16x16x64_i8 v[130:133], v[174:177], v[182:185], v[130:133]
	v_mfma_i32_16x16x64_i8 v[110:113], v[156:159], v[190:193], v[110:113]
	v_mfma_i32_16x16x64_i8 v[98:101], v[174:177], v[190:193], v[98:101]
	v_mfma_i32_16x16x64_i8 v[86:89], v[156:159], v[198:201], v[86:89]
	v_mfma_i32_16x16x64_i8 v[78:81], v[174:177], v[198:201], v[78:81]
	v_mfma_i32_16x16x64_i8 v[70:73], v[156:159], v[206:209], v[70:73]
	v_mfma_i32_16x16x64_i8 v[66:69], v[174:177], v[206:209], v[66:69]
	v_mfma_i32_16x16x64_i8 v[134:137], v[170:173], v[186:189], v[134:137]
	v_mfma_i32_16x16x64_i8 v[130:133], v[178:181], v[186:189], v[130:133]
	v_mfma_i32_16x16x64_i8 v[110:113], v[170:173], v[194:197], v[110:113]
	v_mfma_i32_16x16x64_i8 v[98:101], v[178:181], v[194:197], v[98:101]
	v_mfma_i32_16x16x64_i8 v[86:89], v[170:173], v[202:205], v[86:89]
	v_mfma_i32_16x16x64_i8 v[78:81], v[178:181], v[202:205], v[78:81]
	v_mfma_i32_16x16x64_i8 v[70:73], v[170:173], v[210:213], v[70:73]
	v_mfma_i32_16x16x64_i8 v[66:69], v[178:181], v[210:213], v[66:69]
	s_barrier
	s_add_i32 s62, s10, s41
	v_lshl_add_u64 v[160:161], s[34:35], 0, v[146:147]
	s_mov_b32 m0, s62
	ds_read_b128 v[182:185], v168 offset:16384
	ds_read_b128 v[186:189], v168 offset:17408
	ds_read_b128 v[190:193], v168 offset:18432
	ds_read_b128 v[194:197], v168 offset:19456
	ds_read_b128 v[198:201], v168 offset:20480
	ds_read_b128 v[202:205], v168 offset:21504
	ds_read_b128 v[206:209], v168 offset:22528
	ds_read_b128 v[210:213], v168 offset:23552
	global_load_lds_dwordx4 v[160:161], off
	s_add_i32 m0, s62, 0x2000
	s_add_u32 s62, s34, 0x80000
	v_lshl_add_u64 v[214:215], s[34:35], 0, v[148:149]
	s_addc_u32 s63, s35, 0
	s_add_i32 s64, s50, s41
	global_load_lds_dwordx4 v[214:215], off
	v_lshl_add_u64 v[216:217], s[62:63], 0, v[146:147]
	s_mov_b32 m0, s64
	v_lshl_add_u64 v[218:219], s[36:37], 0, v[148:149]
	global_load_lds_dwordx4 v[216:217], off
	v_lshl_add_u64 v[216:217], s[62:63], 0, v[148:149]
	s_add_i32 m0, s64, 0x2000
	s_nop 0
	global_load_lds_dwordx4 v[216:217], off
	v_lshl_add_u64 v[216:217], s[36:37], 0, v[146:147]
	s_mov_b32 m0, s29
	s_nop 0
	global_load_lds_dwordx4 v[216:217], off
	s_mov_b32 m0, s44
	s_nop 0
	global_load_lds_dwordx4 v[218:219], off
	s_waitcnt vmcnt(8)
	s_waitcnt lgkmcnt(0)
	s_barrier
; #define PG8_STAGE(bufoff, gbase, voff) do { _Pragma("unroll") for (int _i = 0; _i < 2; ++_i) \
;         __builtin_amdgcn_global_load_lds((const unsigned*)((const char*)(gbase) + (voff)[_i]), (LAS unsigned*)(lds + (bufoff) + ldsw + _i * 8192), 16, 0, 0); } while (0)
; #define PG8_LDA(dst, b, h) do { _Pragma("unroll") for (int m = 0; m < 4; ++m) _Pragma("unroll") for (int k = 0; k < 2; ++k) dst[m][k] = *(const LAS bf16x8*)(lds + PG8_SA(b, h) + aoff + m * 2048 + k * 1024); } while (0)
; #define PG8_LDB(dst, b, h) do { _Pragma("unroll") for (int n = 0; n < 2; ++n) _Pragma("unroll") for (int k = 0; k < 2; ++k) dst[n][k] = *(const LAS bf16x8*)(lds + PG8_SB(b, h) + boff + n * 2048 + k * 1024); } while (0)
; #define PG8_WAIT_V(n) asm volatile("s_waitcnt vmcnt(" #n ")" ::: "memory")
; template <class Epi, class Geom, class Sched, bool ALIGN_EPI, bool I8 = false>
; __device__ __forceinline__ void gemm_phase(LAS unsigned char* lds, const Gemm g, const Sched& S, const Epi& E) {
;     ...
;         for (int t = 0; t < nt; t += 2) {
;             const bool last = (t == nt - 2);
;             const char* a1 = cA + (size_t)(t + 1) * kstep;
;             const char* a2 = last ? nA : cA + (size_t)(t + 2) * kstep; const char* b2 = last ? nB : cB + (size_t)(t + 2) * kstep;
;             const char* a3 = a2 + kstep; const char* b3 = b2 + kstep;
;             PG8_LDB(B0, 0, 0); PG8_LDB(B1, 0, 1); PG8_SCHED; PG8_LDA(At, 0, 0); PG8_STAGE(PG8_SA(1, 1), a1 + hsA, voffA);
;             PG8_WAIT_V(8); PG8_WAIT_L(0); PG8_BAR; PG8_MMA(0, 0, At, B0); PG8_MMA(0, 1, At, B1); PG8_BAR; PG8_SCHED;
;             PG8_LDA(At, 0, 1); PG8_STAGE(PG8_SB(0, 0), b2, voffB); PG8_STAGE(PG8_SB(0, 1), b2 + hsB, voffB); PG8_STAGE(PG8_SA(0, 0), a2, voffA);
;             PG8_WAIT_V(8); PG8_WAIT_L(0); PG8_BAR; PG8_MMA(1, 0, At, B0); PG8_MMA(1, 1, At, B1); PG8_BAR; PG8_SCHED;
;             PG8_LDB(B0, 1, 0); PG8_LDB(B1, 1, 1); PG8_SCHED; PG8_LDA(At, 1, 0); PG8_STAGE(PG8_SA(0, 1), a2 + hsA, voffA);
;             PG8_WAIT_V(8); PG8_WAIT_L(0); PG8_BAR; PG8_MMA(0, 0, At, B0); PG8_MMA(0, 1, At, B1); PG8_BAR; PG8_SCHED;
;             PG8_LDA(At, 1, 1); PG8_STAGE(PG8_SB(1, 0), b3, voffB); PG8_STAGE(PG8_SB(1, 1), b3 + hsB, voffB); PG8_STAGE(PG8_SA(1, 0), a3, voffA);
;             PG8_WAIT_V(8); PG8_WAIT_L(0); PG8_BAR; PG8_MMA(1, 0, At, B0); PG8_MMA(1, 1, At, B1); PG8_BAR; PG8_SCHED;
;         }
	s_waitcnt lgkmcnt(0)
	v_mfma_i32_16x16x64_i8 v[62:65], v[102:105], v[182:185], v[62:65]
	v_mfma_i32_16x16x64_i8 v[58:61], v[114:117], v[182:185], v[58:61]
	v_mfma_i32_16x16x64_i8 v[50:53], v[102:105], v[190:193], v[50:53]
	v_mfma_i32_16x16x64_i8 v[42:45], v[114:117], v[190:193], v[42:45]
	v_mfma_i32_16x16x64_i8 v[30:33], v[102:105], v[198:201], v[30:33]
	v_mfma_i32_16x16x64_i8 v[26:29], v[114:117], v[198:201], v[26:29]
	v_mfma_i32_16x16x64_i8 v[18:21], v[102:105], v[206:209], v[18:21]
	v_mfma_i32_16x16x64_i8 v[10:13], v[114:117], v[206:209], v[10:13]
	v_mfma_i32_16x16x64_i8 v[62:65], v[106:109], v[186:189], v[62:65]
	v_mfma_i32_16x16x64_i8 v[58:61], v[118:121], v[186:189], v[58:61]
	v_mfma_i32_16x16x64_i8 v[50:53], v[106:109], v[194:197], v[50:53]
	v_mfma_i32_16x16x64_i8 v[42:45], v[118:121], v[194:197], v[42:45]
	v_mfma_i32_16x16x64_i8 v[30:33], v[106:109], v[202:205], v[30:33]
	v_mfma_i32_16x16x64_i8 v[26:29], v[118:121], v[202:205], v[26:29]
	v_mfma_i32_16x16x64_i8 v[18:21], v[106:109], v[210:213], v[18:21]
	v_mfma_i32_16x16x64_i8 v[10:13], v[118:121], v[210:213], v[10:13]
	v_mfma_i32_16x16x64_i8 v[54:57], v[156:159], v[182:185], v[54:57]
	v_mfma_i32_16x16x64_i8 v[46:49], v[174:177], v[182:185], v[46:49]
	v_mfma_i32_16x16x64_i8 v[38:41], v[156:159], v[190:193], v[38:41]
	v_mfma_i32_16x16x64_i8 v[34:37], v[174:177], v[190:193], v[34:37]
	v_mfma_i32_16x16x64_i8 v[22:25], v[156:159], v[198:201], v[22:25]
	v_mfma_i32_16x16x64_i8 v[14:17], v[174:177], v[198:201], v[14:17]
	v_mfma_i32_16x16x64_i8 v[6:9], v[156:159], v[206:209], v[6:9]
	v_mfma_i32_16x16x64_i8 v[2:5], v[174:177], v[206:209], v[2:5]
	v_mfma_i32_16x16x64_i8 v[54:57], v[170:173], v[186:189], v[54:57]
	v_mfma_i32_16x16x64_i8 v[46:49], v[178:181], v[186:189], v[46:49]
	v_mfma_i32_16x16x64_i8 v[38:41], v[170:173], v[194:197], v[38:41]
	v_mfma_i32_16x16x64_i8 v[34:37], v[178:181], v[194:197], v[34:37]
	v_mfma_i32_16x16x64_i8 v[22:25], v[170:173], v[202:205], v[22:25]
	v_mfma_i32_16x16x64_i8 v[14:17], v[178:181], v[202:205], v[14:17]
	v_mfma_i32_16x16x64_i8 v[6:9], v[170:173], v[210:213], v[6:9]
	v_mfma_i32_16x16x64_i8 v[2:5], v[178:181], v[210:213], v[2:5]
	s_barrier
	s_add_i32 s62, 0, 0x18000
	s_add_i32 s63, 0, 0x1c000
	v_add_u32_e32 v118, s62, v164
	v_add_u32_e32 v162, s63, v164
	ds_read_b128 v[102:105], v118
	ds_read_b128 v[106:109], v118 offset:1024
	ds_read_b128 v[114:117], v118 offset:2048
	ds_read_b128 v[118:121], v118 offset:3072
	ds_read_b128 v[156:159], v162
	ds_read_b128 v[170:173], v162 offset:1024
	ds_read_b128 v[174:177], v162 offset:2048
	ds_read_b128 v[178:181], v162 offset:3072
	s_add_u32 s36, s36, 0x80000
	s_addc_u32 s37, s37, 0
	s_mov_b32 m0, s45
	v_lshl_add_u64 v[220:221], s[36:37], 0, v[146:147]
	ds_read_b128 v[182:185], v168 offset:32768
	ds_read_b128 v[186:189], v168 offset:33792
	ds_read_b128 v[190:193], v168 offset:34816
	ds_read_b128 v[194:197], v168 offset:35840
	ds_read_b128 v[198:201], v168 offset:36864
	ds_read_b128 v[202:205], v168 offset:37888
	ds_read_b128 v[206:209], v168 offset:38912
	ds_read_b128 v[210:213], v168 offset:39936
	global_load_lds_dwordx4 v[220:221], off
	v_lshl_add_u64 v[220:221], s[36:37], 0, v[148:149]
	s_mov_b32 m0, s46
	s_nop 0
	global_load_lds_dwordx4 v[220:221], off
	s_waitcnt vmcnt(8)
	s_waitcnt lgkmcnt(0)
	s_barrier
	s_waitcnt lgkmcnt(0)
	v_mfma_i32_16x16x64_i8 v[142:145], v[102:105], v[182:185], v[142:145]
	v_mfma_i32_16x16x64_i8 v[138:141], v[114:117], v[182:185], v[138:141]
	v_mfma_i32_16x16x64_i8 v[126:129], v[102:105], v[190:193], v[126:129]
	v_mfma_i32_16x16x64_i8 v[122:125], v[114:117], v[190:193], v[122:125]
	v_mfma_i32_16x16x64_i8 v[94:97], v[102:105], v[198:201], v[94:97]
	v_mfma_i32_16x16x64_i8 v[90:93], v[114:117], v[198:201], v[90:93]
	v_mfma_i32_16x16x64_i8 v[82:85], v[102:105], v[206:209], v[82:85]
	v_mfma_i32_16x16x64_i8 v[74:77], v[114:117], v[206:209], v[74:77]
	v_mfma_i32_16x16x64_i8 v[142:145], v[106:109], v[186:189], v[142:145]
	v_mfma_i32_16x16x64_i8 v[138:141], v[118:121], v[186:189], v[138:141]
	v_mfma_i32_16x16x64_i8 v[126:129], v[106:109], v[194:197], v[126:129]
	v_mfma_i32_16x16x64_i8 v[122:125], v[118:121], v[194:197], v[122:125]
	v_mfma_i32_16x16x64_i8 v[94:97], v[106:109], v[202:205], v[94:97]
	v_mfma_i32_16x16x64_i8 v[90:93], v[118:121], v[202:205], v[90:93]
	v_mfma_i32_16x16x64_i8 v[82:85], v[106:109], v[210:213], v[82:85]
	v_mfma_i32_16x16x64_i8 v[74:77], v[118:121], v[210:213], v[74:77]
	v_mfma_i32_16x16x64_i8 v[134:137], v[156:159], v[182:185], v[134:137]
	v_mfma_i32_16x16x64_i8 v[130:133], v[174:177], v[182:185], v[130:133]
	v_mfma_i32_16x16x64_i8 v[110:113], v[156:159], v[190:193], v[110:113]
	v_mfma_i32_16x16x64_i8 v[98:101], v[174:177], v[190:193], v[98:101]
	v_mfma_i32_16x16x64_i8 v[86:89], v[156:159], v[198:201], v[86:89]
	v_mfma_i32_16x16x64_i8 v[78:81], v[174:177], v[198:201], v[78:81]
	v_mfma_i32_16x16x64_i8 v[70:73], v[156:159], v[206:209], v[70:73]
	v_mfma_i32_16x16x64_i8 v[66:69], v[174:177], v[206:209], v[66:69]
	v_mfma_i32_16x16x64_i8 v[134:137], v[170:173], v[186:189], v[134:137]
	v_mfma_i32_16x16x64_i8 v[130:133], v[178:181], v[186:189], v[130:133]
	v_mfma_i32_16x16x64_i8 v[110:113], v[170:173], v[194:197], v[110:113]
	v_mfma_i32_16x16x64_i8 v[98:101], v[178:181], v[194:197], v[98:101]
	v_mfma_i32_16x16x64_i8 v[86:89], v[170:173], v[202:205], v[86:89]
	v_mfma_i32_16x16x64_i8 v[78:81], v[178:181], v[202:205], v[78:81]
	v_mfma_i32_16x16x64_i8 v[70:73], v[170:173], v[210:213], v[70:73]
	v_mfma_i32_16x16x64_i8 v[66:69], v[178:181], v[210:213], v[66:69]
	s_barrier
; #define PG8_STAGE(bufoff, gbase, voff) do { _Pragma("unroll") for (int _i = 0; _i < 2; ++_i) \
;         __builtin_amdgcn_global_load_lds((const unsigned*)((const char*)(gbase) + (voff)[_i]), (LAS unsigned*)(lds + (bufoff) + ldsw + _i * 8192), 16, 0, 0); } while (0)
; #define PG8_LDA(dst, b, h) do { _Pragma("unroll") for (int m = 0; m < 4; ++m) _Pragma("unroll") for (int k = 0; k < 2; ++k) dst[m][k] = *(const LAS bf16x8*)(lds + PG8_SA(b, h) + aoff + m * 2048 + k * 1024); } while (0)
; #define PG8_LDB(dst, b, h) do { _Pragma("unroll") for (int n = 0; n < 2; ++n) _Pragma("unroll") for (int k = 0; k < 2; ++k) dst[n][k] = *(const LAS bf16x8*)(lds + PG8_SB(b, h) + boff + n * 2048 + k * 1024); } while (0)
; #define PG8_WAIT_V(n) asm volatile("s_waitcnt vmcnt(" #n ")" ::: "memory")
; template <class Epi, class Geom, class Sched, bool ALIGN_EPI, bool I8 = false>
; __device__ __forceinline__ void gemm_phase(LAS unsigned char* lds, const Gemm g, const Sched& S, const Epi& E) {
;     ...
;         for (int t = 0; t < nt; t += 2) {
;             const bool last = (t == nt - 2);
;             const char* a1 = cA + (size_t)(t + 1) * kstep;
;             const char* a2 = last ? nA : cA + (size_t)(t + 2) * kstep; const char* b2 = last ? nB : cB + (size_t)(t + 2) * kstep;
;             const char* a3 = a2 + kstep; const char* b3 = b2 + kstep;
;             PG8_LDB(B0, 0, 0); PG8_LDB(B1, 0, 1); PG8_SCHED; PG8_LDA(At, 0, 0); PG8_STAGE(PG8_SA(1, 1), a1 + hsA, voffA);
;             PG8_WAIT_V(8); PG8_WAIT_L(0); PG8_BAR; PG8_MMA(0, 0, At, B0); PG8_MMA(0, 1, At, B1); PG8_BAR; PG8_SCHED;
;             PG8_LDA(At, 0, 1); PG8_STAGE(PG8_SB(0, 0), b2, voffB); PG8_STAGE(PG8_SB(0, 1), b2 + hsB, voffB); PG8_STAGE(PG8_SA(0, 0), a2, voffA);
;             PG8_WAIT_V(8); PG8_WAIT_L(0); PG8_BAR; PG8_MMA(1, 0, At, B0); PG8_MMA(1, 1, At, B1); PG8_BAR; PG8_SCHED;
;             PG8_LDB(B0, 1, 0); PG8_LDB(B1, 1, 1); PG8_SCHED; PG8_LDA(At, 1, 0); PG8_STAGE(PG8_SA(0, 1), a2 + hsA, voffA);
;             PG8_WAIT_V(8); PG8_WAIT_L(0); PG8_BAR; PG8_MMA(0, 0, At, B0); PG8_MMA(0, 1, At, B1); PG8_BAR; PG8_SCHED;
;             PG8_LDA(At, 1, 1); PG8_STAGE(PG8_SB(1, 0), b3, voffB); PG8_STAGE(PG8_SB(1, 1), b3 + hsB, voffB); PG8_STAGE(PG8_SA(1, 0), a3, voffA);
;             PG8_WAIT_V(8); PG8_WAIT_L(0); PG8_BAR; PG8_MMA(1, 0, At, B0); PG8_MMA(1, 1, At, B1); PG8_BAR; PG8_SCHED;
;         }
	s_add_i32 s36, s62, s41
	v_lshl_add_u64 v[160:161], v[160:161], 0, s[16:17]
	s_mov_b32 m0, s36
	ds_read_b128 v[182:185], v168 offset:49152
	ds_read_b128 v[186:189], v168 offset:50176
	ds_read_b128 v[190:193], v168 offset:51200
	ds_read_b128 v[194:197], v168 offset:52224
	ds_read_b128 v[198:201], v168 offset:53248
	ds_read_b128 v[202:205], v168 offset:54272
	ds_read_b128 v[206:209], v168 offset:55296
	ds_read_b128 v[210:213], v168 offset:56320
	global_load_lds_dwordx4 v[160:161], off
	s_add_i32 m0, s36, 0x2000
	s_add_u32 s34, s34, 0x80080
	v_lshl_add_u64 v[160:161], v[214:215], 0, s[16:17]
	s_addc_u32 s35, s35, 0
	s_add_i32 s36, s63, s41
	global_load_lds_dwordx4 v[160:161], off
	v_lshl_add_u64 v[160:161], s[34:35], 0, v[146:147]
	s_mov_b32 m0, s36
	s_nop 0
	global_load_lds_dwordx4 v[160:161], off
	v_lshl_add_u64 v[160:161], s[34:35], 0, v[148:149]
	s_add_i32 m0, s36, 0x2000
	s_nop 0
	global_load_lds_dwordx4 v[160:161], off
	v_lshl_add_u64 v[160:161], v[216:217], 0, s[16:17]
	s_mov_b32 m0, s47
	s_nop 0
	global_load_lds_dwordx4 v[160:161], off
	v_lshl_add_u64 v[160:161], v[218:219], 0, s[16:17]
	s_mov_b32 m0, s48
	s_nop 0
	global_load_lds_dwordx4 v[160:161], off
	s_waitcnt vmcnt(8)
	s_waitcnt lgkmcnt(0)
	s_barrier
	s_waitcnt lgkmcnt(0)
	v_mfma_i32_16x16x64_i8 v[62:65], v[102:105], v[182:185], v[62:65]
	v_mfma_i32_16x16x64_i8 v[58:61], v[114:117], v[182:185], v[58:61]
	v_mfma_i32_16x16x64_i8 v[50:53], v[102:105], v[190:193], v[50:53]
	v_mfma_i32_16x16x64_i8 v[42:45], v[114:117], v[190:193], v[42:45]
	v_mfma_i32_16x16x64_i8 v[30:33], v[102:105], v[198:201], v[30:33]
	v_mfma_i32_16x16x64_i8 v[26:29], v[114:117], v[198:201], v[26:29]
	v_mfma_i32_16x16x64_i8 v[18:21], v[102:105], v[206:209], v[18:21]
	v_mfma_i32_16x16x64_i8 v[10:13], v[114:117], v[206:209], v[10:13]
	v_mfma_i32_16x16x64_i8 v[62:65], v[106:109], v[186:189], v[62:65]
	v_mfma_i32_16x16x64_i8 v[58:61], v[118:121], v[186:189], v[58:61]
	v_mfma_i32_16x16x64_i8 v[50:53], v[106:109], v[194:197], v[50:53]
	v_mfma_i32_16x16x64_i8 v[42:45], v[118:121], v[194:197], v[42:45]
	v_mfma_i32_16x16x64_i8 v[30:33], v[106:109], v[202:205], v[30:33]
	v_mfma_i32_16x16x64_i8 v[26:29], v[118:121], v[202:205], v[26:29]
	v_mfma_i32_16x16x64_i8 v[18:21], v[106:109], v[210:213], v[18:21]
	v_mfma_i32_16x16x64_i8 v[10:13], v[118:121], v[210:213], v[10:13]
	v_mfma_i32_16x16x64_i8 v[54:57], v[156:159], v[182:185], v[54:57]
	v_mfma_i32_16x16x64_i8 v[46:49], v[174:177], v[182:185], v[46:49]
	v_mfma_i32_16x16x64_i8 v[38:41], v[156:159], v[190:193], v[38:41]
	v_mfma_i32_16x16x64_i8 v[34:37], v[174:177], v[190:193], v[34:37]
	v_mfma_i32_16x16x64_i8 v[22:25], v[156:159], v[198:201], v[22:25]
	v_mfma_i32_16x16x64_i8 v[14:17], v[174:177], v[198:201], v[14:17]
	v_mfma_i32_16x16x64_i8 v[6:9], v[156:159], v[206:209], v[6:9]
	v_mfma_i32_16x16x64_i8 v[2:5], v[174:177], v[206:209], v[2:5]
	v_mfma_i32_16x16x64_i8 v[54:57], v[170:173], v[186:189], v[54:57]
	v_mfma_i32_16x16x64_i8 v[46:49], v[178:181], v[186:189], v[46:49]
	v_mfma_i32_16x16x64_i8 v[38:41], v[170:173], v[194:197], v[38:41]
	v_mfma_i32_16x16x64_i8 v[34:37], v[178:181], v[194:197], v[34:37]
	v_mfma_i32_16x16x64_i8 v[22:25], v[170:173], v[202:205], v[22:25]
	v_mfma_i32_16x16x64_i8 v[14:17], v[178:181], v[202:205], v[14:17]
	v_mfma_i32_16x16x64_i8 v[6:9], v[170:173], v[210:213], v[6:9]
	v_mfma_i32_16x16x64_i8 v[2:5], v[178:181], v[210:213], v[2:5]
	s_barrier
	s_add_i32 s61, s61, 2
	s_add_u32 s30, s30, 0x100
	s_addc_u32 s31, s31, 0
	s_add_u32 s59, s59, 0x100
	s_addc_u32 s60, s60, 0
	s_cmp_gt_u32 s61, 29
	s_cbranch_scc0 .LBB0_2231
	s_and_b64 vcc, exec, s[18:19]
	s_cbranch_vccz .LBB0_2234
	s_barrier

; #define PG8_STAGE(bufoff, gbase, voff) do { _Pragma("unroll") for (int _i = 0; _i < 2; ++_i) \
;         __builtin_amdgcn_global_load_lds((const unsigned*)((const char*)(gbase) + (voff)[_i]), (LAS unsigned*)(lds + (bufoff) + ldsw + _i * 8192), 16, 0, 0); } while (0)
; #define PG8_LDA(dst, b, h) do { _Pragma("unroll") for (int m = 0; m < 4; ++m) _Pragma("unroll") for (int k = 0; k < 2; ++k) dst[m][k] = *(const LAS bf16x8*)(lds + PG8_SA(b, h) + aoff + m * 2048 + k * 1024); } while (0)
; #define PG8_LDB(dst, b, h) do { _Pragma("unroll") for (int n = 0; n < 2; ++n) _Pragma("unroll") for (int k = 0; k < 2; ++k) dst[n][k] = *(const LAS bf16x8*)(lds + PG8_SB(b, h) + boff + n * 2048 + k * 1024); } while (0)
; #define PG8_WAIT_V(n) asm volatile("s_waitcnt vmcnt(" #n ")" ::: "memory")
; template <class Epi, class Geom, class Sched, bool ALIGN_EPI, bool I8 = false>
; __device__ __forceinline__ void gemm_phase(LAS unsigned char* lds, const Gemm g, const Sched& S, const Epi& E) {
;     ...
;         for (int t = 0; t < nt; t += 2) {
;             const bool last = (t == nt - 2);
;             const char* a1 = cA + (size_t)(t + 1) * kstep;
;             const char* a2 = last ? nA : cA + (size_t)(t + 2) * kstep; const char* b2 = last ? nB : cB + (size_t)(t + 2) * kstep;
;             const char* a3 = a2 + kstep; const char* b3 = b2 + kstep;
;             PG8_LDB(B0, 0, 0); PG8_LDB(B1, 0, 1); PG8_SCHED; PG8_LDA(At, 0, 0); PG8_STAGE(PG8_SA(1, 1), a1 + hsA, voffA);
;             PG8_WAIT_V(8); PG8_WAIT_L(0); PG8_BAR; PG8_MMA(0, 0, At, B0); PG8_MMA(0, 1, At, B1); PG8_BAR; PG8_SCHED;
;             PG8_LDA(At, 0, 1); PG8_STAGE(PG8_SB(0, 0), b2, voffB); PG8_STAGE(PG8_SB(0, 1), b2 + hsB, voffB); PG8_STAGE(PG8_SA(0, 0), a2, voffA);
;             PG8_WAIT_V(8); PG8_WAIT_L(0); PG8_BAR; PG8_MMA(1, 0, At, B0); PG8_MMA(1, 1, At, B1); PG8_BAR; PG8_SCHED;
;             PG8_LDB(B0, 1, 0); PG8_LDB(B1, 1, 1); PG8_SCHED; PG8_LDA(At, 1, 0); PG8_STAGE(PG8_SA(0, 1), a2 + hsA, voffA);
;             PG8_WAIT_V(8); PG8_WAIT_L(0); PG8_BAR; PG8_MMA(0, 0, At, B0); PG8_MMA(0, 1, At, B1); PG8_BAR; PG8_SCHED;
;             PG8_LDA(At, 1, 1); PG8_STAGE(PG8_SB(1, 0), b3, voffB); PG8_STAGE(PG8_SB(1, 1), b3 + hsB, voffB); PG8_STAGE(PG8_SA(1, 0), a3, voffA);
;             PG8_WAIT_V(8); PG8_WAIT_L(0); PG8_BAR; PG8_MMA(1, 0, At, B0); PG8_MMA(1, 1, At, B1); PG8_BAR; PG8_SCHED;
;         }
.LBB0_2243:
	s_add_i32 s20, s24, 0x100
	s_and_b64 s[18:19], s[18:19], exec
	s_cselect_b32 s19, 0, s20
	s_cselect_b32 s18, 0, 0
	s_add_u32 s20, s10, s19
	s_addc_u32 s21, s11, s18
	s_add_u32 s22, s4, s19
	v_add_u32_e32 v127, s41, v1
	s_addc_u32 s23, s5, s18
	ds_read_b128 v[128:131], v127
	ds_read_b128 v[132:135], v127 offset:1024
	ds_read_b128 v[136:139], v127 offset:2048
	ds_read_b128 v[152:155], v127 offset:3072
	v_add_u32_e32 v127, s42, v1
	s_add_u32 s28, s12, s24
	ds_read_b128 v[156:159], v127
	ds_read_b128 v[160:163], v127 offset:1024
	ds_read_b128 v[164:167], v127 offset:2048
	ds_read_b128 v[168:171], v127 offset:3072
	s_addc_u32 s29, s13, 0
	s_add_u32 s24, s22, 0x80000
	s_addc_u32 s25, s23, 0
	s_add_u32 s18, s20, 0x80000
	s_addc_u32 s19, s21, 0
	s_add_u32 s26, s22, 0x80080
	s_addc_u32 s27, s23, 0
	v_lshl_add_u64 v[140:141], s[28:29], 0, v[146:147]
	s_mov_b32 m0, s43
	v_lshl_add_u64 v[140:141], v[140:141], 0, s[14:15]
	ds_read_b128 v[172:175], v126
	ds_read_b128 v[176:179], v126 offset:1024
	ds_read_b128 v[180:183], v126 offset:2048
	ds_read_b128 v[184:187], v126 offset:3072
	ds_read_b128 v[188:191], v126 offset:4096
	ds_read_b128 v[192:195], v126 offset:5120
	ds_read_b128 v[196:199], v126 offset:6144
	ds_read_b128 v[200:203], v126 offset:7168
	global_load_lds_dwordx4 v[140:141], off
	v_lshl_add_u64 v[140:141], s[28:29], 0, v[148:149]
	v_lshl_add_u64 v[140:141], v[140:141], 0, s[14:15]
	s_mov_b32 m0, s44
	s_nop 0
	global_load_lds_dwordx4 v[140:141], off
	s_waitcnt vmcnt(8)
	s_waitcnt lgkmcnt(0)
	s_barrier
	s_waitcnt lgkmcnt(0)
	v_mfma_i32_16x16x64_i8 v[140:143], v[128:131], v[172:175], v[142:145]
	v_mfma_i32_16x16x64_i8 v[122:125], v[136:139], v[172:175], v[122:125]
	v_mfma_i32_16x16x64_i8 v[110:113], v[128:131], v[180:183], v[110:113]
	v_mfma_i32_16x16x64_i8 v[106:109], v[136:139], v[180:183], v[106:109]
	v_mfma_i32_16x16x64_i8 v[94:97], v[128:131], v[188:191], v[94:97]
	v_mfma_i32_16x16x64_i8 v[90:93], v[136:139], v[188:191], v[90:93]
	v_mfma_i32_16x16x64_i8 v[78:81], v[128:131], v[196:199], v[78:81]
	v_mfma_i32_16x16x64_i8 v[74:77], v[136:139], v[196:199], v[74:77]
	v_mfma_i32_16x16x64_i8 v[140:143], v[132:135], v[176:179], v[140:143]
	v_mfma_i32_16x16x64_i8 v[122:125], v[152:155], v[176:179], v[122:125]
	v_mfma_i32_16x16x64_i8 v[110:113], v[132:135], v[184:187], v[110:113]
	v_mfma_i32_16x16x64_i8 v[106:109], v[152:155], v[184:187], v[106:109]
	v_mfma_i32_16x16x64_i8 v[94:97], v[132:135], v[192:195], v[94:97]
	v_mfma_i32_16x16x64_i8 v[90:93], v[152:155], v[192:195], v[90:93]
	v_mfma_i32_16x16x64_i8 v[78:81], v[132:135], v[200:203], v[78:81]
	v_mfma_i32_16x16x64_i8 v[74:77], v[152:155], v[200:203], v[74:77]
	v_mfma_i32_16x16x64_i8 v[118:121], v[156:159], v[172:175], v[118:121]
	v_mfma_i32_16x16x64_i8 v[114:117], v[164:167], v[172:175], v[114:117]
	v_mfma_i32_16x16x64_i8 v[102:105], v[156:159], v[180:183], v[102:105]
	v_mfma_i32_16x16x64_i8 v[98:101], v[164:167], v[180:183], v[98:101]
	v_mfma_i32_16x16x64_i8 v[86:89], v[156:159], v[188:191], v[86:89]
	v_mfma_i32_16x16x64_i8 v[82:85], v[164:167], v[188:191], v[82:85]
	v_mfma_i32_16x16x64_i8 v[70:73], v[156:159], v[196:199], v[70:73]
	v_mfma_i32_16x16x64_i8 v[66:69], v[164:167], v[196:199], v[66:69]
	v_mfma_i32_16x16x64_i8 v[118:121], v[160:163], v[176:179], v[118:121]
	v_mfma_i32_16x16x64_i8 v[114:117], v[168:171], v[176:179], v[114:117]
	v_mfma_i32_16x16x64_i8 v[102:105], v[160:163], v[184:187], v[102:105]
	v_mfma_i32_16x16x64_i8 v[98:101], v[168:171], v[184:187], v[98:101]
	v_mfma_i32_16x16x64_i8 v[86:89], v[160:163], v[192:195], v[86:89]
	v_mfma_i32_16x16x64_i8 v[82:85], v[168:171], v[192:195], v[82:85]
	v_mfma_i32_16x16x64_i8 v[70:73], v[160:163], v[200:203], v[70:73]
	v_mfma_i32_16x16x64_i8 v[66:69], v[168:171], v[200:203], v[66:69]
	s_barrier
	s_mov_b32 m0, s45
	v_lshl_add_u64 v[204:205], s[22:23], 0, v[146:147]
	ds_read_b128 v[172:175], v126 offset:16384
	ds_read_b128 v[176:179], v126 offset:17408
	ds_read_b128 v[180:183], v126 offset:18432
	ds_read_b128 v[184:187], v126 offset:19456
	ds_read_b128 v[188:191], v126 offset:20480
	ds_read_b128 v[192:195], v126 offset:21504
	ds_read_b128 v[196:199], v126 offset:22528
	ds_read_b128 v[200:203], v126 offset:23552
	global_load_lds_dwordx4 v[204:205], off
	v_lshl_add_u64 v[206:207], s[22:23], 0, v[148:149]
	s_mov_b32 m0, s46
	v_lshl_add_u64 v[144:145], s[24:25], 0, v[146:147]
	global_load_lds_dwordx4 v[206:207], off
	s_mov_b32 m0, s47
	v_lshl_add_u64 v[208:209], s[20:21], 0, v[146:147]
	global_load_lds_dwordx4 v[144:145], off
	v_lshl_add_u64 v[144:145], s[24:25], 0, v[148:149]
	s_mov_b32 m0, s48
	v_lshl_add_u64 v[210:211], s[20:21], 0, v[148:149]
	global_load_lds_dwordx4 v[144:145], off
	s_mov_b32 m0, s36
	s_nop 0
	global_load_lds_dwordx4 v[208:209], off
	s_mov_b32 m0, s33
	s_nop 0
	global_load_lds_dwordx4 v[210:211], off
	s_waitcnt vmcnt(8)
	s_waitcnt lgkmcnt(0)
	s_barrier
; #define PG8_STAGE(bufoff, gbase, voff) do { _Pragma("unroll") for (int _i = 0; _i < 2; ++_i) \
;         __builtin_amdgcn_global_load_lds((const unsigned*)((const char*)(gbase) + (voff)[_i]), (LAS unsigned*)(lds + (bufoff) + ldsw + _i * 8192), 16, 0, 0); } while (0)
; #define PG8_LDA(dst, b, h) do { _Pragma("unroll") for (int m = 0; m < 4; ++m) _Pragma("unroll") for (int k = 0; k < 2; ++k) dst[m][k] = *(const LAS bf16x8*)(lds + PG8_SA(b, h) + aoff + m * 2048 + k * 1024); } while (0)
; #define PG8_LDB(dst, b, h) do { _Pragma("unroll") for (int n = 0; n < 2; ++n) _Pragma("unroll") for (int k = 0; k < 2; ++k) dst[n][k] = *(const LAS bf16x8*)(lds + PG8_SB(b, h) + boff + n * 2048 + k * 1024); } while (0)
; #define PG8_WAIT_V(n) asm volatile("s_waitcnt vmcnt(" #n ")" ::: "memory")
; template <class Epi, class Geom, class Sched, bool ALIGN_EPI, bool I8 = false>
; __device__ __forceinline__ void gemm_phase(LAS unsigned char* lds, const Gemm g, const Sched& S, const Epi& E) {
;     ...
;         for (int t = 0; t < nt; t += 2) {
;             const bool last = (t == nt - 2);
;             const char* a1 = cA + (size_t)(t + 1) * kstep;
;             const char* a2 = last ? nA : cA + (size_t)(t + 2) * kstep; const char* b2 = last ? nB : cB + (size_t)(t + 2) * kstep;
;             const char* a3 = a2 + kstep; const char* b3 = b2 + kstep;
;             PG8_LDB(B0, 0, 0); PG8_LDB(B1, 0, 1); PG8_SCHED; PG8_LDA(At, 0, 0); PG8_STAGE(PG8_SA(1, 1), a1 + hsA, voffA);
;             PG8_WAIT_V(8); PG8_WAIT_L(0); PG8_BAR; PG8_MMA(0, 0, At, B0); PG8_MMA(0, 1, At, B1); PG8_BAR; PG8_SCHED;
;             PG8_LDA(At, 0, 1); PG8_STAGE(PG8_SB(0, 0), b2, voffB); PG8_STAGE(PG8_SB(0, 1), b2 + hsB, voffB); PG8_STAGE(PG8_SA(0, 0), a2, voffA);
;             PG8_WAIT_V(8); PG8_WAIT_L(0); PG8_BAR; PG8_MMA(1, 0, At, B0); PG8_MMA(1, 1, At, B1); PG8_BAR; PG8_SCHED;
;             PG8_LDB(B0, 1, 0); PG8_LDB(B1, 1, 1); PG8_SCHED; PG8_LDA(At, 1, 0); PG8_STAGE(PG8_SA(0, 1), a2 + hsA, voffA);
;             PG8_WAIT_V(8); PG8_WAIT_L(0); PG8_BAR; PG8_MMA(0, 0, At, B0); PG8_MMA(0, 1, At, B1); PG8_BAR; PG8_SCHED;
;             PG8_LDA(At, 1, 1); PG8_STAGE(PG8_SB(1, 0), b3, voffB); PG8_STAGE(PG8_SB(1, 1), b3 + hsB, voffB); PG8_STAGE(PG8_SA(1, 0), a3, voffA);
;             PG8_WAIT_V(8); PG8_WAIT_L(0); PG8_BAR; PG8_MMA(1, 0, At, B0); PG8_MMA(1, 1, At, B1); PG8_BAR; PG8_SCHED;
;         }
	s_waitcnt lgkmcnt(0)
	v_mfma_i32_16x16x64_i8 v[62:65], v[128:131], v[172:175], v[62:65]
	v_mfma_i32_16x16x64_i8 v[58:61], v[136:139], v[172:175], v[58:61]
	v_mfma_i32_16x16x64_i8 v[46:49], v[128:131], v[180:183], v[46:49]
	v_mfma_i32_16x16x64_i8 v[42:45], v[136:139], v[180:183], v[42:45]
	v_mfma_i32_16x16x64_i8 v[30:33], v[128:131], v[188:191], v[30:33]
	v_mfma_i32_16x16x64_i8 v[26:29], v[136:139], v[188:191], v[26:29]
	v_mfma_i32_16x16x64_i8 v[14:17], v[128:131], v[196:199], v[14:17]
	v_mfma_i32_16x16x64_i8 v[10:13], v[136:139], v[196:199], v[10:13]
	v_mfma_i32_16x16x64_i8 v[62:65], v[132:135], v[176:179], v[62:65]
	v_mfma_i32_16x16x64_i8 v[58:61], v[152:155], v[176:179], v[58:61]
	v_mfma_i32_16x16x64_i8 v[46:49], v[132:135], v[184:187], v[46:49]
	v_mfma_i32_16x16x64_i8 v[42:45], v[152:155], v[184:187], v[42:45]
	v_mfma_i32_16x16x64_i8 v[30:33], v[132:135], v[192:195], v[30:33]
	v_mfma_i32_16x16x64_i8 v[26:29], v[152:155], v[192:195], v[26:29]
	v_mfma_i32_16x16x64_i8 v[14:17], v[132:135], v[200:203], v[14:17]
	v_mfma_i32_16x16x64_i8 v[10:13], v[152:155], v[200:203], v[10:13]
	v_mfma_i32_16x16x64_i8 v[54:57], v[156:159], v[172:175], v[54:57]
	v_mfma_i32_16x16x64_i8 v[50:53], v[164:167], v[172:175], v[50:53]
	v_mfma_i32_16x16x64_i8 v[38:41], v[156:159], v[180:183], v[38:41]
	v_mfma_i32_16x16x64_i8 v[34:37], v[164:167], v[180:183], v[34:37]
	v_mfma_i32_16x16x64_i8 v[22:25], v[156:159], v[188:191], v[22:25]
	v_mfma_i32_16x16x64_i8 v[18:21], v[164:167], v[188:191], v[18:21]
	v_mfma_i32_16x16x64_i8 v[6:9], v[156:159], v[196:199], v[6:9]
	v_mfma_i32_16x16x64_i8 v[2:5], v[164:167], v[196:199], v[2:5]
	v_mfma_i32_16x16x64_i8 v[54:57], v[160:163], v[176:179], v[54:57]
	v_mfma_i32_16x16x64_i8 v[50:53], v[168:171], v[176:179], v[50:53]
	v_mfma_i32_16x16x64_i8 v[38:41], v[160:163], v[184:187], v[38:41]
	v_mfma_i32_16x16x64_i8 v[34:37], v[168:171], v[184:187], v[34:37]
	v_mfma_i32_16x16x64_i8 v[22:25], v[160:163], v[192:195], v[22:25]
	v_mfma_i32_16x16x64_i8 v[18:21], v[168:171], v[192:195], v[18:21]
	v_mfma_i32_16x16x64_i8 v[6:9], v[160:163], v[200:203], v[6:9]
	v_mfma_i32_16x16x64_i8 v[2:5], v[168:171], v[200:203], v[2:5]
	s_barrier
	v_add_u32_e32 v127, s49, v1
	ds_read_b128 v[128:131], v127
	ds_read_b128 v[132:135], v127 offset:1024
	ds_read_b128 v[136:139], v127 offset:2048
	ds_read_b128 v[152:155], v127 offset:3072
	v_add_u32_e32 v127, s50, v1
	ds_read_b128 v[156:159], v127
	ds_read_b128 v[160:163], v127 offset:1024
	ds_read_b128 v[164:167], v127 offset:2048
	ds_read_b128 v[168:171], v127 offset:3072
	s_mov_b32 m0, s37
	v_lshl_add_u64 v[144:145], s[18:19], 0, v[146:147]
	ds_read_b128 v[172:175], v126 offset:32768
	ds_read_b128 v[176:179], v126 offset:33792
	ds_read_b128 v[180:183], v126 offset:34816
	ds_read_b128 v[184:187], v126 offset:35840
	ds_read_b128 v[188:191], v126 offset:36864
	ds_read_b128 v[192:195], v126 offset:37888
	ds_read_b128 v[196:199], v126 offset:38912
	ds_read_b128 v[200:203], v126 offset:39936
	global_load_lds_dwordx4 v[144:145], off
	v_lshl_add_u64 v[144:145], s[18:19], 0, v[148:149]
	s_mov_b32 m0, s38
	s_nop 0
	global_load_lds_dwordx4 v[144:145], off
	s_waitcnt vmcnt(8)
	s_waitcnt lgkmcnt(0)
	s_barrier
	s_waitcnt lgkmcnt(0)
	v_mfma_i32_16x16x64_i8 v[140:143], v[128:131], v[172:175], v[140:143]
	v_mfma_i32_16x16x64_i8 v[122:125], v[136:139], v[172:175], v[122:125]
	v_mfma_i32_16x16x64_i8 v[110:113], v[128:131], v[180:183], v[110:113]
	v_mfma_i32_16x16x64_i8 v[106:109], v[136:139], v[180:183], v[106:109]
	v_mfma_i32_16x16x64_i8 v[94:97], v[128:131], v[188:191], v[94:97]
	v_mfma_i32_16x16x64_i8 v[90:93], v[136:139], v[188:191], v[90:93]
	v_mfma_i32_16x16x64_i8 v[78:81], v[128:131], v[196:199], v[78:81]
	v_mfma_i32_16x16x64_i8 v[74:77], v[136:139], v[196:199], v[74:77]
	v_mfma_i32_16x16x64_i8 v[142:145], v[132:135], v[176:179], v[140:143]
	v_mfma_i32_16x16x64_i8 v[122:125], v[152:155], v[176:179], v[122:125]
	v_mfma_i32_16x16x64_i8 v[110:113], v[132:135], v[184:187], v[110:113]
	v_mfma_i32_16x16x64_i8 v[106:109], v[152:155], v[184:187], v[106:109]
	v_mfma_i32_16x16x64_i8 v[94:97], v[132:135], v[192:195], v[94:97]
	v_mfma_i32_16x16x64_i8 v[90:93], v[152:155], v[192:195], v[90:93]
	v_mfma_i32_16x16x64_i8 v[78:81], v[132:135], v[200:203], v[78:81]
	v_mfma_i32_16x16x64_i8 v[74:77], v[152:155], v[200:203], v[74:77]
	v_mfma_i32_16x16x64_i8 v[118:121], v[156:159], v[172:175], v[118:121]
	v_mfma_i32_16x16x64_i8 v[114:117], v[164:167], v[172:175], v[114:117]
	v_mfma_i32_16x16x64_i8 v[102:105], v[156:159], v[180:183], v[102:105]
	v_mfma_i32_16x16x64_i8 v[98:101], v[164:167], v[180:183], v[98:101]
	v_mfma_i32_16x16x64_i8 v[86:89], v[156:159], v[188:191], v[86:89]
	v_mfma_i32_16x16x64_i8 v[82:85], v[164:167], v[188:191], v[82:85]
	v_mfma_i32_16x16x64_i8 v[70:73], v[156:159], v[196:199], v[70:73]
	v_mfma_i32_16x16x64_i8 v[66:69], v[164:167], v[196:199], v[66:69]
	v_mfma_i32_16x16x64_i8 v[118:121], v[160:163], v[176:179], v[118:121]
	v_mfma_i32_16x16x64_i8 v[114:117], v[168:171], v[176:179], v[114:117]
	v_mfma_i32_16x16x64_i8 v[102:105], v[160:163], v[184:187], v[102:105]
	v_mfma_i32_16x16x64_i8 v[98:101], v[168:171], v[184:187], v[98:101]
	v_mfma_i32_16x16x64_i8 v[86:89], v[160:163], v[192:195], v[86:89]
	v_mfma_i32_16x16x64_i8 v[82:85], v[168:171], v[192:195], v[82:85]
	v_mfma_i32_16x16x64_i8 v[70:73], v[160:163], v[200:203], v[70:73]
	v_mfma_i32_16x16x64_i8 v[66:69], v[168:171], v[200:203], v[66:69]
	s_barrier
; #define PG8_STAGE(bufoff, gbase, voff) do { _Pragma("unroll") for (int _i = 0; _i < 2; ++_i) \
;         __builtin_amdgcn_global_load_lds((const unsigned*)((const char*)(gbase) + (voff)[_i]), (LAS unsigned*)(lds + (bufoff) + ldsw + _i * 8192), 16, 0, 0); } while (0)
; #define PG8_LDA(dst, b, h) do { _Pragma("unroll") for (int m = 0; m < 4; ++m) _Pragma("unroll") for (int k = 0; k < 2; ++k) dst[m][k] = *(const LAS bf16x8*)(lds + PG8_SA(b, h) + aoff + m * 2048 + k * 1024); } while (0)
; #define PG8_LDB(dst, b, h) do { _Pragma("unroll") for (int n = 0; n < 2; ++n) _Pragma("unroll") for (int k = 0; k < 2; ++k) dst[n][k] = *(const LAS bf16x8*)(lds + PG8_SB(b, h) + boff + n * 2048 + k * 1024); } while (0)
; #define PG8_WAIT_V(n) asm volatile("s_waitcnt vmcnt(" #n ")" ::: "memory")
; template <class Epi, class Geom, class Sched, bool ALIGN_EPI, bool I8 = false>
; __device__ __forceinline__ void gemm_phase(LAS unsigned char* lds, const Gemm g, const Sched& S, const Epi& E) {
;     ...
;         for (int t = 0; t < nt; t += 2) {
;             const bool last = (t == nt - 2);
;             const char* a1 = cA + (size_t)(t + 1) * kstep;
;             const char* a2 = last ? nA : cA + (size_t)(t + 2) * kstep; const char* b2 = last ? nB : cB + (size_t)(t + 2) * kstep;
;             const char* a3 = a2 + kstep; const char* b3 = b2 + kstep;
;             PG8_LDB(B0, 0, 0); PG8_LDB(B1, 0, 1); PG8_SCHED; PG8_LDA(At, 0, 0); PG8_STAGE(PG8_SA(1, 1), a1 + hsA, voffA);
;             PG8_WAIT_V(8); PG8_WAIT_L(0); PG8_BAR; PG8_MMA(0, 0, At, B0); PG8_MMA(0, 1, At, B1); PG8_BAR; PG8_SCHED;
;             PG8_LDA(At, 0, 1); PG8_STAGE(PG8_SB(0, 0), b2, voffB); PG8_STAGE(PG8_SB(0, 1), b2 + hsB, voffB); PG8_STAGE(PG8_SA(0, 0), a2, voffA);
;             PG8_WAIT_V(8); PG8_WAIT_L(0); PG8_BAR; PG8_MMA(1, 0, At, B0); PG8_MMA(1, 1, At, B1); PG8_BAR; PG8_SCHED;
;             PG8_LDB(B0, 1, 0); PG8_LDB(B1, 1, 1); PG8_SCHED; PG8_LDA(At, 1, 0); PG8_STAGE(PG8_SA(0, 1), a2 + hsA, voffA);
;             PG8_WAIT_V(8); PG8_WAIT_L(0); PG8_BAR; PG8_MMA(0, 0, At, B0); PG8_MMA(0, 1, At, B1); PG8_BAR; PG8_SCHED;
;             PG8_LDA(At, 1, 1); PG8_STAGE(PG8_SB(1, 0), b3, voffB); PG8_STAGE(PG8_SB(1, 1), b3 + hsB, voffB); PG8_STAGE(PG8_SA(1, 0), a3, voffA);
;             PG8_WAIT_V(8); PG8_WAIT_L(0); PG8_BAR; PG8_MMA(1, 0, At, B0); PG8_MMA(1, 1, At, B1); PG8_BAR; PG8_SCHED;
;         }
	s_mov_b32 m0, s51
	v_lshl_add_u64 v[140:141], v[204:205], 0, s[14:15]
	ds_read_b128 v[172:175], v126 offset:49152
	ds_read_b128 v[176:179], v126 offset:50176
	ds_read_b128 v[180:183], v126 offset:51200
	ds_read_b128 v[184:187], v126 offset:52224
	ds_read_b128 v[188:191], v126 offset:53248
	ds_read_b128 v[192:195], v126 offset:54272
	ds_read_b128 v[196:199], v126 offset:55296
	ds_read_b128 v[200:203], v126 offset:56320
	global_load_lds_dwordx4 v[140:141], off
	v_lshl_add_u64 v[140:141], v[206:207], 0, s[14:15]
	s_mov_b32 m0, s52
	s_nop 0
	global_load_lds_dwordx4 v[140:141], off
	v_lshl_add_u64 v[140:141], s[26:27], 0, v[146:147]
	s_mov_b32 m0, s53
	s_nop 0
	global_load_lds_dwordx4 v[140:141], off
	v_lshl_add_u64 v[140:141], s[26:27], 0, v[148:149]
	s_mov_b32 m0, s54
	s_nop 0
	global_load_lds_dwordx4 v[140:141], off
	v_lshl_add_u64 v[140:141], v[208:209], 0, s[14:15]
	s_mov_b32 m0, s39
	s_nop 0
	global_load_lds_dwordx4 v[140:141], off
	v_lshl_add_u64 v[140:141], v[210:211], 0, s[14:15]
	s_mov_b32 m0, s40
	s_nop 0
	global_load_lds_dwordx4 v[140:141], off
	s_waitcnt vmcnt(8)
	s_waitcnt lgkmcnt(0)
	s_barrier
	s_waitcnt lgkmcnt(0)
	v_mfma_i32_16x16x64_i8 v[62:65], v[128:131], v[172:175], v[62:65]
	v_mfma_i32_16x16x64_i8 v[58:61], v[136:139], v[172:175], v[58:61]
	v_mfma_i32_16x16x64_i8 v[46:49], v[128:131], v[180:183], v[46:49]
	v_mfma_i32_16x16x64_i8 v[42:45], v[136:139], v[180:183], v[42:45]
	v_mfma_i32_16x16x64_i8 v[30:33], v[128:131], v[188:191], v[30:33]
	v_mfma_i32_16x16x64_i8 v[26:29], v[136:139], v[188:191], v[26:29]
	v_mfma_i32_16x16x64_i8 v[14:17], v[128:131], v[196:199], v[14:17]
	v_mfma_i32_16x16x64_i8 v[10:13], v[136:139], v[196:199], v[10:13]
	v_mfma_i32_16x16x64_i8 v[62:65], v[132:135], v[176:179], v[62:65]
	v_mfma_i32_16x16x64_i8 v[58:61], v[152:155], v[176:179], v[58:61]
	v_mfma_i32_16x16x64_i8 v[46:49], v[132:135], v[184:187], v[46:49]
	v_mfma_i32_16x16x64_i8 v[42:45], v[152:155], v[184:187], v[42:45]
	v_mfma_i32_16x16x64_i8 v[30:33], v[132:135], v[192:195], v[30:33]
	v_mfma_i32_16x16x64_i8 v[26:29], v[152:155], v[192:195], v[26:29]
	v_mfma_i32_16x16x64_i8 v[14:17], v[132:135], v[200:203], v[14:17]
	v_mfma_i32_16x16x64_i8 v[10:13], v[152:155], v[200:203], v[10:13]
	v_mfma_i32_16x16x64_i8 v[54:57], v[156:159], v[172:175], v[54:57]
	v_mfma_i32_16x16x64_i8 v[50:53], v[164:167], v[172:175], v[50:53]
	v_mfma_i32_16x16x64_i8 v[38:41], v[156:159], v[180:183], v[38:41]
	v_mfma_i32_16x16x64_i8 v[34:37], v[164:167], v[180:183], v[34:37]
	v_mfma_i32_16x16x64_i8 v[22:25], v[156:159], v[188:191], v[22:25]
	v_mfma_i32_16x16x64_i8 v[18:21], v[164:167], v[188:191], v[18:21]
	v_mfma_i32_16x16x64_i8 v[6:9], v[156:159], v[196:199], v[6:9]
	v_mfma_i32_16x16x64_i8 v[2:5], v[164:167], v[196:199], v[2:5]
	v_mfma_i32_16x16x64_i8 v[54:57], v[160:163], v[176:179], v[54:57]
	v_mfma_i32_16x16x64_i8 v[50:53], v[168:171], v[176:179], v[50:53]
	v_mfma_i32_16x16x64_i8 v[38:41], v[160:163], v[184:187], v[38:41]
	v_mfma_i32_16x16x64_i8 v[34:37], v[168:171], v[184:187], v[34:37]
	v_mfma_i32_16x16x64_i8 v[22:25], v[160:163], v[192:195], v[22:25]
	v_mfma_i32_16x16x64_i8 v[18:21], v[168:171], v[192:195], v[18:21]
	v_mfma_i32_16x16x64_i8 v[6:9], v[160:163], v[200:203], v[6:9]
	v_mfma_i32_16x16x64_i8 v[2:5], v[168:171], v[200:203], v[2:5]
	s_barrier
	s_andn2_b64 vcc, exec, s[16:17]
	s_mov_b64 s[18:19], -1
	s_mov_b64 s[16:17], 0
	s_movk_i32 s24, 0x100
	s_cbranch_vccz .LBB0_2243
	s_cmpk_lt_u32 s34, 0x100
	s_cbranch_scc0 .LBB0_2246
	s_barrier

; #define PG8_STAGE(bufoff, gbase, voff) do { _Pragma("unroll") for (int _i = 0; _i < 2; ++_i) \
;         __builtin_amdgcn_global_load_lds((const unsigned*)((const char*)(gbase) + (voff)[_i]), (LAS unsigned*)(lds + (bufoff) + ldsw + _i * 8192), 16, 0, 0); } while (0)
; #define PG8_LDA(dst, b, h) do { _Pragma("unroll") for (int m = 0; m < 4; ++m) _Pragma("unroll") for (int k = 0; k < 2; ++k) dst[m][k] = *(const LAS bf16x8*)(lds + PG8_SA(b, h) + aoff + m * 2048 + k * 1024); } while (0)
; #define PG8_LDB(dst, b, h) do { _Pragma("unroll") for (int n = 0; n < 2; ++n) _Pragma("unroll") for (int k = 0; k < 2; ++k) dst[n][k] = *(const LAS bf16x8*)(lds + PG8_SB(b, h) + boff + n * 2048 + k * 1024); } while (0)
; #define PG8_WAIT_V(n) asm volatile("s_waitcnt vmcnt(" #n ")" ::: "memory")
; template <class Epi, class Geom, class Sched, bool ALIGN_EPI, bool I8 = false>
; __device__ __forceinline__ void gemm_phase(LAS unsigned char* lds, const Gemm g, const Sched& S, const Epi& E) {
;     ...
;         for (int t = 0; t < nt; t += 2) {
;             const bool last = (t == nt - 2);
;             const char* a1 = cA + (size_t)(t + 1) * kstep;
;             const char* a2 = last ? nA : cA + (size_t)(t + 2) * kstep; const char* b2 = last ? nB : cB + (size_t)(t + 2) * kstep;
;             const char* a3 = a2 + kstep; const char* b3 = b2 + kstep;
;             PG8_LDB(B0, 0, 0); PG8_LDB(B1, 0, 1); PG8_SCHED; PG8_LDA(At, 0, 0); PG8_STAGE(PG8_SA(1, 1), a1 + hsA, voffA);
;             PG8_WAIT_V(8); PG8_WAIT_L(0); PG8_BAR; PG8_MMA(0, 0, At, B0); PG8_MMA(0, 1, At, B1); PG8_BAR; PG8_SCHED;
;             PG8_LDA(At, 0, 1); PG8_STAGE(PG8_SB(0, 0), b2, voffB); PG8_STAGE(PG8_SB(0, 1), b2 + hsB, voffB); PG8_STAGE(PG8_SA(0, 0), a2, voffA);
;             PG8_WAIT_V(8); PG8_WAIT_L(0); PG8_BAR; PG8_MMA(1, 0, At, B0); PG8_MMA(1, 1, At, B1); PG8_BAR; PG8_SCHED;
;             PG8_LDB(B0, 1, 0); PG8_LDB(B1, 1, 1); PG8_SCHED; PG8_LDA(At, 1, 0); PG8_STAGE(PG8_SA(0, 1), a2 + hsA, voffA);
;             PG8_WAIT_V(8); PG8_WAIT_L(0); PG8_BAR; PG8_MMA(0, 0, At, B0); PG8_MMA(0, 1, At, B1); PG8_BAR; PG8_SCHED;
;             PG8_LDA(At, 1, 1); PG8_STAGE(PG8_SB(1, 0), b3, voffB); PG8_STAGE(PG8_SB(1, 1), b3 + hsB, voffB); PG8_STAGE(PG8_SA(1, 0), a3, voffA);
;             PG8_WAIT_V(8); PG8_WAIT_L(0); PG8_BAR; PG8_MMA(1, 0, At, B0); PG8_MMA(1, 1, At, B1); PG8_BAR; PG8_SCHED;
;         }
.LBB0_2520:
	ds_read_b128 v[130:133], v248
	ds_read_b128 v[134:137], v248 offset:1024
	ds_read_b128 v[138:141], v248 offset:2048
	ds_read_b128 v[142:145], v248 offset:3072
	ds_read_b128 v[146:149], v249
	ds_read_b128 v[150:153], v249 offset:1024
	ds_read_b128 v[154:157], v249 offset:2048
	ds_read_b128 v[158:161], v249 offset:3072
	s_add_u32 s62, s20, 0xfff80080
	s_addc_u32 s63, s21, -1
	s_cmp_eq_u32 s69, 28
	s_cselect_b32 s67, s3, s63
	s_cselect_b32 s66, s33, s62
	s_cselect_b32 s63, s55, s68
	s_cselect_b32 s62, s57, s65
	v_lshl_add_u64 v[166:167], s[20:21], 0, v[182:183]
	s_add_i32 m0, s78, 0xc000
	ds_read_b128 v[162:165], v250
	ds_read_b128 v[190:193], v250 offset:1024
	ds_read_b128 v[194:197], v250 offset:2048
	ds_read_b128 v[198:201], v250 offset:3072
	ds_read_b128 v[202:205], v250 offset:4096
	ds_read_b128 v[206:209], v250 offset:5120
	ds_read_b128 v[210:213], v250 offset:6144
	ds_read_b128 v[214:217], v250 offset:7168
	global_load_lds_dwordx4 v[166:167], off
	v_lshl_add_u64 v[166:167], s[20:21], 0, v[184:185]
	s_add_i32 m0, s78, 0xe000
	s_nop 0
	global_load_lds_dwordx4 v[166:167], off
	s_waitcnt vmcnt(8)
	s_waitcnt lgkmcnt(0)
	s_barrier
	s_waitcnt lgkmcnt(0)
	v_mfma_i32_16x16x64_i8 v[126:129], v[130:133], v[162:165], v[126:129]
	v_mfma_i32_16x16x64_i8 v[122:125], v[138:141], v[162:165], v[122:125]
	v_mfma_i32_16x16x64_i8 v[114:117], v[130:133], v[194:197], v[114:117]
	v_mfma_i32_16x16x64_i8 v[106:109], v[138:141], v[194:197], v[106:109]
	v_mfma_i32_16x16x64_i8 v[102:105], v[130:133], v[202:205], v[102:105]
	v_mfma_i32_16x16x64_i8 v[94:97], v[138:141], v[202:205], v[94:97]
	v_mfma_i32_16x16x64_i8 v[86:89], v[130:133], v[210:213], v[86:89]
	v_mfma_i32_16x16x64_i8 v[78:81], v[138:141], v[210:213], v[78:81]
	v_mfma_i32_16x16x64_i8 v[126:129], v[134:137], v[190:193], v[126:129]
	v_mfma_i32_16x16x64_i8 v[122:125], v[142:145], v[190:193], v[122:125]
	v_mfma_i32_16x16x64_i8 v[114:117], v[134:137], v[198:201], v[114:117]
	v_mfma_i32_16x16x64_i8 v[106:109], v[142:145], v[198:201], v[106:109]
	v_mfma_i32_16x16x64_i8 v[102:105], v[134:137], v[206:209], v[102:105]
	v_mfma_i32_16x16x64_i8 v[94:97], v[142:145], v[206:209], v[94:97]
	v_mfma_i32_16x16x64_i8 v[86:89], v[134:137], v[214:217], v[86:89]
	v_mfma_i32_16x16x64_i8 v[78:81], v[142:145], v[214:217], v[78:81]
	v_mfma_i32_16x16x64_i8 v[118:121], v[146:149], v[162:165], v[118:121]
	v_mfma_i32_16x16x64_i8 v[82:85], v[154:157], v[162:165], v[82:85]
	v_mfma_i32_16x16x64_i8 v[110:113], v[146:149], v[194:197], v[110:113]
	v_mfma_i32_16x16x64_i8 v[74:77], v[154:157], v[194:197], v[74:77]
	v_mfma_i32_16x16x64_i8 v[98:101], v[146:149], v[202:205], v[98:101]
	v_mfma_i32_16x16x64_i8 v[66:69], v[154:157], v[202:205], v[66:69]
	v_mfma_i32_16x16x64_i8 v[90:93], v[146:149], v[210:213], v[90:93]
	v_mfma_i32_16x16x64_i8 v[58:61], v[154:157], v[210:213], v[58:61]
	v_mfma_i32_16x16x64_i8 v[118:121], v[150:153], v[190:193], v[118:121]
	v_mfma_i32_16x16x64_i8 v[82:85], v[158:161], v[190:193], v[82:85]
	v_mfma_i32_16x16x64_i8 v[110:113], v[150:153], v[198:201], v[110:113]
	v_mfma_i32_16x16x64_i8 v[74:77], v[158:161], v[198:201], v[74:77]
	v_mfma_i32_16x16x64_i8 v[98:101], v[150:153], v[206:209], v[98:101]
	v_mfma_i32_16x16x64_i8 v[66:69], v[158:161], v[206:209], v[66:69]
	v_mfma_i32_16x16x64_i8 v[90:93], v[150:153], v[214:217], v[90:93]
	v_mfma_i32_16x16x64_i8 v[58:61], v[158:161], v[214:217], v[58:61]
	s_barrier
	s_add_i32 s70, s92, s77
	v_lshl_add_u64 v[166:167], s[62:63], 0, v[170:171]
	s_mov_b32 m0, s70
	ds_read_b128 v[162:165], v250 offset:16384
	ds_read_b128 v[190:193], v250 offset:17408
	ds_read_b128 v[194:197], v250 offset:18432
	ds_read_b128 v[198:201], v250 offset:19456
	ds_read_b128 v[202:205], v250 offset:20480
	ds_read_b128 v[206:209], v250 offset:21504
	ds_read_b128 v[210:213], v250 offset:22528
	ds_read_b128 v[214:217], v250 offset:23552
	global_load_lds_dwordx4 v[166:167], off
	s_add_i32 m0, s70, 0x2000
	s_add_u32 s70, s62, 0x80000
	v_lshl_add_u64 v[218:219], s[62:63], 0, v[174:175]
	s_addc_u32 s71, s63, 0
	s_add_i32 s72, s93, s77
	global_load_lds_dwordx4 v[218:219], off
	v_lshl_add_u64 v[220:221], s[70:71], 0, v[170:171]
	s_mov_b32 m0, s72
	v_lshl_add_u64 v[222:223], s[66:67], 0, v[172:173]
	global_load_lds_dwordx4 v[220:221], off
	v_lshl_add_u64 v[220:221], s[70:71], 0, v[174:175]
	s_add_i32 m0, s72, 0x2000
	s_nop 0
	global_load_lds_dwordx4 v[220:221], off
	v_lshl_add_u64 v[220:221], s[66:67], 0, v[168:169]
	s_mov_b32 m0, s78
	s_nop 0
	global_load_lds_dwordx4 v[220:221], off
	s_mov_b32 m0, s79
	s_nop 0
	global_load_lds_dwordx4 v[222:223], off
	s_waitcnt vmcnt(8)
	s_waitcnt lgkmcnt(0)
	s_barrier
; #define PG8_STAGE(bufoff, gbase, voff) do { _Pragma("unroll") for (int _i = 0; _i < 2; ++_i) \
;         __builtin_amdgcn_global_load_lds((const unsigned*)((const char*)(gbase) + (voff)[_i]), (LAS unsigned*)(lds + (bufoff) + ldsw + _i * 8192), 16, 0, 0); } while (0)
; #define PG8_LDA(dst, b, h) do { _Pragma("unroll") for (int m = 0; m < 4; ++m) _Pragma("unroll") for (int k = 0; k < 2; ++k) dst[m][k] = *(const LAS bf16x8*)(lds + PG8_SA(b, h) + aoff + m * 2048 + k * 1024); } while (0)
; #define PG8_LDB(dst, b, h) do { _Pragma("unroll") for (int n = 0; n < 2; ++n) _Pragma("unroll") for (int k = 0; k < 2; ++k) dst[n][k] = *(const LAS bf16x8*)(lds + PG8_SB(b, h) + boff + n * 2048 + k * 1024); } while (0)
; #define PG8_WAIT_V(n) asm volatile("s_waitcnt vmcnt(" #n ")" ::: "memory")
; template <class Epi, class Geom, class Sched, bool ALIGN_EPI, bool I8 = false>
; __device__ __forceinline__ void gemm_phase(LAS unsigned char* lds, const Gemm g, const Sched& S, const Epi& E) {
;     ...
;         for (int t = 0; t < nt; t += 2) {
;             const bool last = (t == nt - 2);
;             const char* a1 = cA + (size_t)(t + 1) * kstep;
;             const char* a2 = last ? nA : cA + (size_t)(t + 2) * kstep; const char* b2 = last ? nB : cB + (size_t)(t + 2) * kstep;
;             const char* a3 = a2 + kstep; const char* b3 = b2 + kstep;
;             PG8_LDB(B0, 0, 0); PG8_LDB(B1, 0, 1); PG8_SCHED; PG8_LDA(At, 0, 0); PG8_STAGE(PG8_SA(1, 1), a1 + hsA, voffA);
;             PG8_WAIT_V(8); PG8_WAIT_L(0); PG8_BAR; PG8_MMA(0, 0, At, B0); PG8_MMA(0, 1, At, B1); PG8_BAR; PG8_SCHED;
;             PG8_LDA(At, 0, 1); PG8_STAGE(PG8_SB(0, 0), b2, voffB); PG8_STAGE(PG8_SB(0, 1), b2 + hsB, voffB); PG8_STAGE(PG8_SA(0, 0), a2, voffA);
;             PG8_WAIT_V(8); PG8_WAIT_L(0); PG8_BAR; PG8_MMA(1, 0, At, B0); PG8_MMA(1, 1, At, B1); PG8_BAR; PG8_SCHED;
;             PG8_LDB(B0, 1, 0); PG8_LDB(B1, 1, 1); PG8_SCHED; PG8_LDA(At, 1, 0); PG8_STAGE(PG8_SA(0, 1), a2 + hsA, voffA);
;             PG8_WAIT_V(8); PG8_WAIT_L(0); PG8_BAR; PG8_MMA(0, 0, At, B0); PG8_MMA(0, 1, At, B1); PG8_BAR; PG8_SCHED;
;             PG8_LDA(At, 1, 1); PG8_STAGE(PG8_SB(1, 0), b3, voffB); PG8_STAGE(PG8_SB(1, 1), b3 + hsB, voffB); PG8_STAGE(PG8_SA(1, 0), a3, voffA);
;             PG8_WAIT_V(8); PG8_WAIT_L(0); PG8_BAR; PG8_MMA(1, 0, At, B0); PG8_MMA(1, 1, At, B1); PG8_BAR; PG8_SCHED;
;         }
	s_waitcnt lgkmcnt(0)
	v_mfma_i32_16x16x64_i8 v[70:73], v[130:133], v[162:165], v[70:73]
	v_mfma_i32_16x16x64_i8 v[62:65], v[138:141], v[162:165], v[62:65]
	v_mfma_i32_16x16x64_i8 v[38:41], v[130:133], v[194:197], v[38:41]
	v_mfma_i32_16x16x64_i8 v[54:57], v[138:141], v[194:197], v[54:57]
	v_mfma_i32_16x16x64_i8 v[30:33], v[130:133], v[202:205], v[30:33]
	v_mfma_i32_16x16x64_i8 v[50:53], v[138:141], v[202:205], v[50:53]
	v_mfma_i32_16x16x64_i8 v[26:29], v[130:133], v[210:213], v[26:29]
	v_mfma_i32_16x16x64_i8 v[18:21], v[138:141], v[210:213], v[18:21]
	v_mfma_i32_16x16x64_i8 v[70:73], v[134:137], v[190:193], v[70:73]
	v_mfma_i32_16x16x64_i8 v[62:65], v[142:145], v[190:193], v[62:65]
	v_mfma_i32_16x16x64_i8 v[38:41], v[134:137], v[198:201], v[38:41]
	v_mfma_i32_16x16x64_i8 v[54:57], v[142:145], v[198:201], v[54:57]
	v_mfma_i32_16x16x64_i8 v[30:33], v[134:137], v[206:209], v[30:33]
	v_mfma_i32_16x16x64_i8 v[50:53], v[142:145], v[206:209], v[50:53]
	v_mfma_i32_16x16x64_i8 v[26:29], v[134:137], v[214:217], v[26:29]
	v_mfma_i32_16x16x64_i8 v[18:21], v[142:145], v[214:217], v[18:21]
	v_mfma_i32_16x16x64_i8 v[46:49], v[146:149], v[162:165], v[46:49]
	v_mfma_i32_16x16x64_i8 v[14:17], v[154:157], v[162:165], v[14:17]
	v_mfma_i32_16x16x64_i8 v[42:45], v[146:149], v[194:197], v[42:45]
	v_mfma_i32_16x16x64_i8 v[10:13], v[154:157], v[194:197], v[10:13]
	v_mfma_i32_16x16x64_i8 v[34:37], v[146:149], v[202:205], v[34:37]
	v_mfma_i32_16x16x64_i8 v[6:9], v[154:157], v[202:205], v[6:9]
	v_mfma_i32_16x16x64_i8 v[22:25], v[146:149], v[210:213], v[22:25]
	v_mfma_i32_16x16x64_i8 v[2:5], v[154:157], v[210:213], v[2:5]
	v_mfma_i32_16x16x64_i8 v[46:49], v[150:153], v[190:193], v[46:49]
	v_mfma_i32_16x16x64_i8 v[14:17], v[158:161], v[190:193], v[14:17]
	v_mfma_i32_16x16x64_i8 v[42:45], v[150:153], v[198:201], v[42:45]
	v_mfma_i32_16x16x64_i8 v[10:13], v[158:161], v[198:201], v[10:13]
	v_mfma_i32_16x16x64_i8 v[34:37], v[150:153], v[206:209], v[34:37]
	v_mfma_i32_16x16x64_i8 v[6:9], v[158:161], v[206:209], v[6:9]
	v_mfma_i32_16x16x64_i8 v[22:25], v[150:153], v[214:217], v[22:25]
	v_mfma_i32_16x16x64_i8 v[2:5], v[158:161], v[214:217], v[2:5]
	s_barrier
	s_add_i32 s70, 0, 0x18000
	s_add_i32 s71, 0, 0x1c000
	v_add_u32_e32 v142, s70, v1
	v_add_u32_e32 v158, s71, v1
	ds_read_b128 v[130:133], v142
	ds_read_b128 v[134:137], v142 offset:1024
	ds_read_b128 v[138:141], v142 offset:2048
	ds_read_b128 v[142:145], v142 offset:3072
	ds_read_b128 v[146:149], v158
	ds_read_b128 v[150:153], v158 offset:1024
	ds_read_b128 v[154:157], v158 offset:2048
	ds_read_b128 v[158:161], v158 offset:3072
	s_add_u32 s66, s66, 0x80000
	s_addc_u32 s67, s67, 0
	s_mov_b32 m0, s80
	v_lshl_add_u64 v[224:225], s[66:67], 0, v[168:169]
	ds_read_b128 v[162:165], v250 offset:32768
	ds_read_b128 v[190:193], v250 offset:33792
	ds_read_b128 v[194:197], v250 offset:34816
	ds_read_b128 v[198:201], v250 offset:35840
	ds_read_b128 v[202:205], v250 offset:36864
	ds_read_b128 v[206:209], v250 offset:37888
	ds_read_b128 v[210:213], v250 offset:38912
	ds_read_b128 v[214:217], v250 offset:39936
	global_load_lds_dwordx4 v[224:225], off
	v_lshl_add_u64 v[224:225], s[66:67], 0, v[172:173]
	s_mov_b32 m0, s81
	s_nop 0
	global_load_lds_dwordx4 v[224:225], off
	s_waitcnt vmcnt(8)
	s_waitcnt lgkmcnt(0)
	s_barrier
	s_waitcnt lgkmcnt(0)
	v_mfma_i32_16x16x64_i8 v[126:129], v[130:133], v[162:165], v[126:129]
	v_mfma_i32_16x16x64_i8 v[122:125], v[138:141], v[162:165], v[122:125]
	v_mfma_i32_16x16x64_i8 v[114:117], v[130:133], v[194:197], v[114:117]
	v_mfma_i32_16x16x64_i8 v[106:109], v[138:141], v[194:197], v[106:109]
	v_mfma_i32_16x16x64_i8 v[102:105], v[130:133], v[202:205], v[102:105]
	v_mfma_i32_16x16x64_i8 v[94:97], v[138:141], v[202:205], v[94:97]
	v_mfma_i32_16x16x64_i8 v[86:89], v[130:133], v[210:213], v[86:89]
	v_mfma_i32_16x16x64_i8 v[78:81], v[138:141], v[210:213], v[78:81]
	v_mfma_i32_16x16x64_i8 v[126:129], v[134:137], v[190:193], v[126:129]
	v_mfma_i32_16x16x64_i8 v[122:125], v[142:145], v[190:193], v[122:125]
	v_mfma_i32_16x16x64_i8 v[114:117], v[134:137], v[198:201], v[114:117]
	v_mfma_i32_16x16x64_i8 v[106:109], v[142:145], v[198:201], v[106:109]
	v_mfma_i32_16x16x64_i8 v[102:105], v[134:137], v[206:209], v[102:105]
	v_mfma_i32_16x16x64_i8 v[94:97], v[142:145], v[206:209], v[94:97]
	v_mfma_i32_16x16x64_i8 v[86:89], v[134:137], v[214:217], v[86:89]
	v_mfma_i32_16x16x64_i8 v[78:81], v[142:145], v[214:217], v[78:81]
	v_mfma_i32_16x16x64_i8 v[118:121], v[146:149], v[162:165], v[118:121]
	v_mfma_i32_16x16x64_i8 v[82:85], v[154:157], v[162:165], v[82:85]
	v_mfma_i32_16x16x64_i8 v[110:113], v[146:149], v[194:197], v[110:113]
	v_mfma_i32_16x16x64_i8 v[74:77], v[154:157], v[194:197], v[74:77]
	v_mfma_i32_16x16x64_i8 v[98:101], v[146:149], v[202:205], v[98:101]
	v_mfma_i32_16x16x64_i8 v[66:69], v[154:157], v[202:205], v[66:69]
	v_mfma_i32_16x16x64_i8 v[90:93], v[146:149], v[210:213], v[90:93]
	v_mfma_i32_16x16x64_i8 v[58:61], v[154:157], v[210:213], v[58:61]
	v_mfma_i32_16x16x64_i8 v[118:121], v[150:153], v[190:193], v[118:121]
	v_mfma_i32_16x16x64_i8 v[82:85], v[158:161], v[190:193], v[82:85]
	v_mfma_i32_16x16x64_i8 v[110:113], v[150:153], v[198:201], v[110:113]
	v_mfma_i32_16x16x64_i8 v[74:77], v[158:161], v[198:201], v[74:77]
	v_mfma_i32_16x16x64_i8 v[98:101], v[150:153], v[206:209], v[98:101]
	v_mfma_i32_16x16x64_i8 v[66:69], v[158:161], v[206:209], v[66:69]
	v_mfma_i32_16x16x64_i8 v[90:93], v[150:153], v[214:217], v[90:93]
	v_mfma_i32_16x16x64_i8 v[58:61], v[158:161], v[214:217], v[58:61]
	s_barrier
; #define PG8_STAGE(bufoff, gbase, voff) do { _Pragma("unroll") for (int _i = 0; _i < 2; ++_i) \
;         __builtin_amdgcn_global_load_lds((const unsigned*)((const char*)(gbase) + (voff)[_i]), (LAS unsigned*)(lds + (bufoff) + ldsw + _i * 8192), 16, 0, 0); } while (0)
; #define PG8_LDA(dst, b, h) do { _Pragma("unroll") for (int m = 0; m < 4; ++m) _Pragma("unroll") for (int k = 0; k < 2; ++k) dst[m][k] = *(const LAS bf16x8*)(lds + PG8_SA(b, h) + aoff + m * 2048 + k * 1024); } while (0)
; #define PG8_LDB(dst, b, h) do { _Pragma("unroll") for (int n = 0; n < 2; ++n) _Pragma("unroll") for (int k = 0; k < 2; ++k) dst[n][k] = *(const LAS bf16x8*)(lds + PG8_SB(b, h) + boff + n * 2048 + k * 1024); } while (0)
; #define PG8_WAIT_V(n) asm volatile("s_waitcnt vmcnt(" #n ")" ::: "memory")
; template <class Epi, class Geom, class Sched, bool ALIGN_EPI, bool I8 = false>
; __device__ __forceinline__ void gemm_phase(LAS unsigned char* lds, const Gemm g, const Sched& S, const Epi& E) {
;     ...
;         for (int t = 0; t < nt; t += 2) {
;             const bool last = (t == nt - 2);
;             const char* a1 = cA + (size_t)(t + 1) * kstep;
;             const char* a2 = last ? nA : cA + (size_t)(t + 2) * kstep; const char* b2 = last ? nB : cB + (size_t)(t + 2) * kstep;
;             const char* a3 = a2 + kstep; const char* b3 = b2 + kstep;
;             PG8_LDB(B0, 0, 0); PG8_LDB(B1, 0, 1); PG8_SCHED; PG8_LDA(At, 0, 0); PG8_STAGE(PG8_SA(1, 1), a1 + hsA, voffA);
;             PG8_WAIT_V(8); PG8_WAIT_L(0); PG8_BAR; PG8_MMA(0, 0, At, B0); PG8_MMA(0, 1, At, B1); PG8_BAR; PG8_SCHED;
;             PG8_LDA(At, 0, 1); PG8_STAGE(PG8_SB(0, 0), b2, voffB); PG8_STAGE(PG8_SB(0, 1), b2 + hsB, voffB); PG8_STAGE(PG8_SA(0, 0), a2, voffA);
;             PG8_WAIT_V(8); PG8_WAIT_L(0); PG8_BAR; PG8_MMA(1, 0, At, B0); PG8_MMA(1, 1, At, B1); PG8_BAR; PG8_SCHED;
;             PG8_LDB(B0, 1, 0); PG8_LDB(B1, 1, 1); PG8_SCHED; PG8_LDA(At, 1, 0); PG8_STAGE(PG8_SA(0, 1), a2 + hsA, voffA);
;             PG8_WAIT_V(8); PG8_WAIT_L(0); PG8_BAR; PG8_MMA(0, 0, At, B0); PG8_MMA(0, 1, At, B1); PG8_BAR; PG8_SCHED;
;             PG8_LDA(At, 1, 1); PG8_STAGE(PG8_SB(1, 0), b3, voffB); PG8_STAGE(PG8_SB(1, 1), b3 + hsB, voffB); PG8_STAGE(PG8_SA(1, 0), a3, voffA);
;             PG8_WAIT_V(8); PG8_WAIT_L(0); PG8_BAR; PG8_MMA(1, 0, At, B0); PG8_MMA(1, 1, At, B1); PG8_BAR; PG8_SCHED;
;         }
	s_add_i32 s66, s70, s77
	v_lshl_add_u64 v[166:167], v[166:167], 0, s[28:29]
	s_mov_b32 m0, s66
	ds_read_b128 v[162:165], v250 offset:49152
	ds_read_b128 v[190:193], v250 offset:50176
	ds_read_b128 v[194:197], v250 offset:51200
	ds_read_b128 v[198:201], v250 offset:52224
	ds_read_b128 v[202:205], v250 offset:53248
	ds_read_b128 v[206:209], v250 offset:54272
	ds_read_b128 v[210:213], v250 offset:55296
	ds_read_b128 v[214:217], v250 offset:56320
	global_load_lds_dwordx4 v[166:167], off
	s_add_i32 m0, s66, 0x2000
	s_add_u32 s62, s62, 0x80080
	v_lshl_add_u64 v[166:167], v[218:219], 0, s[28:29]
	s_addc_u32 s63, s63, 0
	s_add_i32 s66, s71, s77
	global_load_lds_dwordx4 v[166:167], off
	v_lshl_add_u64 v[166:167], s[62:63], 0, v[170:171]
	s_mov_b32 m0, s66
	s_nop 0
	global_load_lds_dwordx4 v[166:167], off
	v_lshl_add_u64 v[166:167], s[62:63], 0, v[174:175]
	s_add_i32 m0, s66, 0x2000
	s_nop 0
	global_load_lds_dwordx4 v[166:167], off
	v_lshl_add_u64 v[166:167], v[220:221], 0, s[28:29]
	s_mov_b32 m0, s88
	s_nop 0
	global_load_lds_dwordx4 v[166:167], off
	v_lshl_add_u64 v[166:167], v[222:223], 0, s[28:29]
	s_mov_b32 m0, s89
	s_nop 0
	global_load_lds_dwordx4 v[166:167], off
	s_waitcnt vmcnt(8)
	s_waitcnt lgkmcnt(0)
	s_barrier
	s_waitcnt lgkmcnt(0)
	v_mfma_i32_16x16x64_i8 v[70:73], v[130:133], v[162:165], v[70:73]
	v_mfma_i32_16x16x64_i8 v[62:65], v[138:141], v[162:165], v[62:65]
	v_mfma_i32_16x16x64_i8 v[38:41], v[130:133], v[194:197], v[38:41]
	v_mfma_i32_16x16x64_i8 v[54:57], v[138:141], v[194:197], v[54:57]
	v_mfma_i32_16x16x64_i8 v[30:33], v[130:133], v[202:205], v[30:33]
	v_mfma_i32_16x16x64_i8 v[50:53], v[138:141], v[202:205], v[50:53]
	v_mfma_i32_16x16x64_i8 v[26:29], v[130:133], v[210:213], v[26:29]
	v_mfma_i32_16x16x64_i8 v[18:21], v[138:141], v[210:213], v[18:21]
	v_mfma_i32_16x16x64_i8 v[70:73], v[134:137], v[190:193], v[70:73]
	v_mfma_i32_16x16x64_i8 v[62:65], v[142:145], v[190:193], v[62:65]
	v_mfma_i32_16x16x64_i8 v[38:41], v[134:137], v[198:201], v[38:41]
	v_mfma_i32_16x16x64_i8 v[54:57], v[142:145], v[198:201], v[54:57]
	v_mfma_i32_16x16x64_i8 v[30:33], v[134:137], v[206:209], v[30:33]
	v_mfma_i32_16x16x64_i8 v[50:53], v[142:145], v[206:209], v[50:53]
	v_mfma_i32_16x16x64_i8 v[26:29], v[134:137], v[214:217], v[26:29]
	v_mfma_i32_16x16x64_i8 v[18:21], v[142:145], v[214:217], v[18:21]
	v_mfma_i32_16x16x64_i8 v[46:49], v[146:149], v[162:165], v[46:49]
	v_mfma_i32_16x16x64_i8 v[14:17], v[154:157], v[162:165], v[14:17]
	v_mfma_i32_16x16x64_i8 v[42:45], v[146:149], v[194:197], v[42:45]
	v_mfma_i32_16x16x64_i8 v[10:13], v[154:157], v[194:197], v[10:13]
	v_mfma_i32_16x16x64_i8 v[34:37], v[146:149], v[202:205], v[34:37]
	v_mfma_i32_16x16x64_i8 v[6:9], v[154:157], v[202:205], v[6:9]
	v_mfma_i32_16x16x64_i8 v[22:25], v[146:149], v[210:213], v[22:25]
	v_mfma_i32_16x16x64_i8 v[2:5], v[154:157], v[210:213], v[2:5]
	v_mfma_i32_16x16x64_i8 v[46:49], v[150:153], v[190:193], v[46:49]
	v_mfma_i32_16x16x64_i8 v[14:17], v[158:161], v[190:193], v[14:17]
	v_mfma_i32_16x16x64_i8 v[42:45], v[150:153], v[198:201], v[42:45]
	v_mfma_i32_16x16x64_i8 v[10:13], v[158:161], v[198:201], v[10:13]
	v_mfma_i32_16x16x64_i8 v[34:37], v[150:153], v[206:209], v[34:37]
	v_mfma_i32_16x16x64_i8 v[6:9], v[158:161], v[206:209], v[6:9]
	v_mfma_i32_16x16x64_i8 v[22:25], v[150:153], v[214:217], v[22:25]
	v_mfma_i32_16x16x64_i8 v[2:5], v[158:161], v[214:217], v[2:5]
	s_barrier
	s_add_i32 s69, s69, 2
	s_add_u32 s20, s20, 0x100
	s_addc_u32 s21, s21, 0
	s_add_u32 s65, s65, 0x100
	s_addc_u32 s68, s68, 0
	s_cmp_gt_u32 s69, 29
	s_cbranch_scc0 .LBB0_2520
	s_and_b64 vcc, exec, s[30:31]
	s_cbranch_vccz .LBB0_2523
	s_barrier

; #define PG8_STAGE(bufoff, gbase, voff) do { _Pragma("unroll") for (int _i = 0; _i < 2; ++_i) \
;         __builtin_amdgcn_global_load_lds((const unsigned*)((const char*)(gbase) + (voff)[_i]), (LAS unsigned*)(lds + (bufoff) + ldsw + _i * 8192), 16, 0, 0); } while (0)
; #define PG8_LDA(dst, b, h) do { _Pragma("unroll") for (int m = 0; m < 4; ++m) _Pragma("unroll") for (int k = 0; k < 2; ++k) dst[m][k] = *(const LAS bf16x8*)(lds + PG8_SA(b, h) + aoff + m * 2048 + k * 1024); } while (0)
; #define PG8_LDB(dst, b, h) do { _Pragma("unroll") for (int n = 0; n < 2; ++n) _Pragma("unroll") for (int k = 0; k < 2; ++k) dst[n][k] = *(const LAS bf16x8*)(lds + PG8_SB(b, h) + boff + n * 2048 + k * 1024); } while (0)
; #define PG8_WAIT_V(n) asm volatile("s_waitcnt vmcnt(" #n ")" ::: "memory")
; template <class Epi, class Geom, class Sched, bool ALIGN_EPI, bool I8 = false>
; __device__ __forceinline__ void gemm_phase(LAS unsigned char* lds, const Gemm g, const Sched& S, const Epi& E) {
;     ...
;         for (int t = 0; t < nt; t += 2) {
;             const bool last = (t == nt - 2);
;             const char* a1 = cA + (size_t)(t + 1) * kstep;
;             const char* a2 = last ? nA : cA + (size_t)(t + 2) * kstep; const char* b2 = last ? nB : cB + (size_t)(t + 2) * kstep;
;             const char* a3 = a2 + kstep; const char* b3 = b2 + kstep;
;             PG8_LDB(B0, 0, 0); PG8_LDB(B1, 0, 1); PG8_SCHED; PG8_LDA(At, 0, 0); PG8_STAGE(PG8_SA(1, 1), a1 + hsA, voffA);
;             PG8_WAIT_V(8); PG8_WAIT_L(0); PG8_BAR; PG8_MMA(0, 0, At, B0); PG8_MMA(0, 1, At, B1); PG8_BAR; PG8_SCHED;
;             PG8_LDA(At, 0, 1); PG8_STAGE(PG8_SB(0, 0), b2, voffB); PG8_STAGE(PG8_SB(0, 1), b2 + hsB, voffB); PG8_STAGE(PG8_SA(0, 0), a2, voffA);
;             PG8_WAIT_V(8); PG8_WAIT_L(0); PG8_BAR; PG8_MMA(1, 0, At, B0); PG8_MMA(1, 1, At, B1); PG8_BAR; PG8_SCHED;
;             PG8_LDB(B0, 1, 0); PG8_LDB(B1, 1, 1); PG8_SCHED; PG8_LDA(At, 1, 0); PG8_STAGE(PG8_SA(0, 1), a2 + hsA, voffA);
;             PG8_WAIT_V(8); PG8_WAIT_L(0); PG8_BAR; PG8_MMA(0, 0, At, B0); PG8_MMA(0, 1, At, B1); PG8_BAR; PG8_SCHED;
;             PG8_LDA(At, 1, 1); PG8_STAGE(PG8_SB(1, 0), b3, voffB); PG8_STAGE(PG8_SB(1, 1), b3 + hsB, voffB); PG8_STAGE(PG8_SA(1, 0), a3, voffA);
;             PG8_WAIT_V(8); PG8_WAIT_L(0); PG8_BAR; PG8_MMA(1, 0, At, B0); PG8_MMA(1, 1, At, B1); PG8_BAR; PG8_SCHED;
;         }
.LBB0_2872:
	ds_read_b128 v[90:93], v181
	ds_read_b128 v[98:101], v181 offset:1024
	ds_read_b128 v[102:105], v181 offset:2048
	ds_read_b128 v[160:163], v181 offset:3072
	ds_read_b128 v[182:185], v206
	ds_read_b128 v[186:189], v206 offset:1024
	ds_read_b128 v[190:193], v206 offset:2048
	ds_read_b128 v[194:197], v206 offset:3072
	s_add_u32 s38, s36, 0xffe80080
	s_addc_u32 s39, s37, -1
	s_cmpk_eq_i32 s62, 0x5c
	s_cselect_b32 s41, s1, s39
	s_cselect_b32 s40, s0, s38
	s_cselect_b32 s39, s35, s61
	s_cselect_b32 s38, s34, s60
	v_lshl_add_u64 v[152:153], s[36:37], 0, v[146:147]
	s_add_i32 m0, s33, 0xc000
	ds_read_b128 v[198:201], v207
	ds_read_b128 v[202:205], v207 offset:1024
	ds_read_b128 v[208:211], v207 offset:2048
	ds_read_b128 v[212:215], v207 offset:3072
	ds_read_b128 v[216:219], v207 offset:4096
	ds_read_b128 v[220:223], v207 offset:5120
	ds_read_b128 v[224:227], v207 offset:6144
	ds_read_b128 v[228:231], v207 offset:7168
	global_load_lds_dwordx4 v[152:153], off
	v_lshl_add_u64 v[152:153], s[36:37], 0, v[148:149]
	s_add_i32 m0, s33, 0xe000
	s_nop 0
	global_load_lds_dwordx4 v[152:153], off
	s_waitcnt vmcnt(8)
	s_waitcnt lgkmcnt(0)
	s_barrier
	s_waitcnt lgkmcnt(0)
	v_mfma_i32_16x16x64_i8 v[94:97], v[90:93], v[198:201], v[94:97]
	v_mfma_i32_16x16x64_i8 v[138:141], v[102:105], v[198:201], v[138:141]
	v_mfma_i32_16x16x64_i8 v[130:133], v[90:93], v[208:211], v[130:133]
	v_mfma_i32_16x16x64_i8 v[122:125], v[102:105], v[208:211], v[122:125]
	v_mfma_i32_16x16x64_i8 v[110:113], v[90:93], v[216:219], v[110:113]
	v_mfma_i32_16x16x64_i8 v[106:109], v[102:105], v[216:219], v[106:109]
	v_mfma_i32_16x16x64_i8 v[82:85], v[90:93], v[224:227], v[82:85]
	v_mfma_i32_16x16x64_i8 v[74:77], v[102:105], v[224:227], v[74:77]
	v_mfma_i32_16x16x64_i8 v[94:97], v[98:101], v[202:205], v[94:97]
	v_mfma_i32_16x16x64_i8 v[138:141], v[160:163], v[202:205], v[138:141]
	v_mfma_i32_16x16x64_i8 v[130:133], v[98:101], v[212:215], v[130:133]
	v_mfma_i32_16x16x64_i8 v[122:125], v[160:163], v[212:215], v[122:125]
	v_mfma_i32_16x16x64_i8 v[110:113], v[98:101], v[220:223], v[110:113]
	v_mfma_i32_16x16x64_i8 v[106:109], v[160:163], v[220:223], v[106:109]
	v_mfma_i32_16x16x64_i8 v[82:85], v[98:101], v[228:231], v[82:85]
	v_mfma_i32_16x16x64_i8 v[74:77], v[160:163], v[228:231], v[74:77]
	v_mfma_i32_16x16x64_i8 v[134:137], v[182:185], v[198:201], v[134:137]
	v_mfma_i32_16x16x64_i8 v[126:129], v[190:193], v[198:201], v[126:129]
	v_mfma_i32_16x16x64_i8 v[118:121], v[182:185], v[208:211], v[118:121]
	v_mfma_i32_16x16x64_i8 v[114:117], v[190:193], v[208:211], v[114:117]
	v_mfma_i32_16x16x64_i8 v[86:89], v[182:185], v[216:219], v[86:89]
	v_mfma_i32_16x16x64_i8 v[78:81], v[190:193], v[216:219], v[78:81]
	v_mfma_i32_16x16x64_i8 v[70:73], v[182:185], v[224:227], v[70:73]
	v_mfma_i32_16x16x64_i8 v[66:69], v[190:193], v[224:227], v[66:69]
	v_mfma_i32_16x16x64_i8 v[134:137], v[186:189], v[202:205], v[134:137]
	v_mfma_i32_16x16x64_i8 v[126:129], v[194:197], v[202:205], v[126:129]
	v_mfma_i32_16x16x64_i8 v[118:121], v[186:189], v[212:215], v[118:121]
	v_mfma_i32_16x16x64_i8 v[114:117], v[194:197], v[212:215], v[114:117]
	v_mfma_i32_16x16x64_i8 v[86:89], v[186:189], v[220:223], v[86:89]
	v_mfma_i32_16x16x64_i8 v[78:81], v[194:197], v[220:223], v[78:81]
	v_mfma_i32_16x16x64_i8 v[70:73], v[186:189], v[228:231], v[70:73]
	v_mfma_i32_16x16x64_i8 v[66:69], v[194:197], v[228:231], v[66:69]
	s_barrier
	s_add_i32 s63, s14, s46
	v_lshl_add_u64 v[152:153], s[38:39], 0, v[144:145]
	s_mov_b32 m0, s63
	ds_read_b128 v[198:201], v207 offset:16384
	ds_read_b128 v[202:205], v207 offset:17408
	ds_read_b128 v[208:211], v207 offset:18432
	ds_read_b128 v[212:215], v207 offset:19456
	ds_read_b128 v[216:219], v207 offset:20480
	ds_read_b128 v[220:223], v207 offset:21504
	ds_read_b128 v[224:227], v207 offset:22528
	ds_read_b128 v[228:231], v207 offset:23552
	global_load_lds_dwordx4 v[152:153], off
	s_add_i32 m0, s63, 0x2000
	s_add_u32 s64, s38, 0x180000
	v_lshl_add_u64 v[156:157], s[38:39], 0, v[142:143]
	s_addc_u32 s65, s39, 0
	s_add_i32 s63, s55, s46
	global_load_lds_dwordx4 v[156:157], off
	v_lshl_add_u64 v[166:167], s[64:65], 0, v[144:145]
	s_mov_b32 m0, s63
	v_lshl_add_u64 v[170:171], s[40:41], 0, v[142:143]
	global_load_lds_dwordx4 v[166:167], off
	v_lshl_add_u64 v[166:167], s[64:65], 0, v[142:143]
	s_add_i32 m0, s63, 0x2000
	s_nop 0
	global_load_lds_dwordx4 v[166:167], off
	v_lshl_add_u64 v[166:167], s[40:41], 0, v[144:145]
	s_mov_b32 m0, s33
	s_nop 0
	global_load_lds_dwordx4 v[166:167], off
	s_mov_b32 m0, s49
	s_nop 0
	global_load_lds_dwordx4 v[170:171], off
	s_waitcnt vmcnt(8)
	s_waitcnt lgkmcnt(0)
	s_barrier
; #define PG8_STAGE(bufoff, gbase, voff) do { _Pragma("unroll") for (int _i = 0; _i < 2; ++_i) \
;         __builtin_amdgcn_global_load_lds((const unsigned*)((const char*)(gbase) + (voff)[_i]), (LAS unsigned*)(lds + (bufoff) + ldsw + _i * 8192), 16, 0, 0); } while (0)
; #define PG8_LDA(dst, b, h) do { _Pragma("unroll") for (int m = 0; m < 4; ++m) _Pragma("unroll") for (int k = 0; k < 2; ++k) dst[m][k] = *(const LAS bf16x8*)(lds + PG8_SA(b, h) + aoff + m * 2048 + k * 1024); } while (0)
; #define PG8_LDB(dst, b, h) do { _Pragma("unroll") for (int n = 0; n < 2; ++n) _Pragma("unroll") for (int k = 0; k < 2; ++k) dst[n][k] = *(const LAS bf16x8*)(lds + PG8_SB(b, h) + boff + n * 2048 + k * 1024); } while (0)
; #define PG8_WAIT_V(n) asm volatile("s_waitcnt vmcnt(" #n ")" ::: "memory")
; template <class Epi, class Geom, class Sched, bool ALIGN_EPI, bool I8 = false>
; __device__ __forceinline__ void gemm_phase(LAS unsigned char* lds, const Gemm g, const Sched& S, const Epi& E) {
;     ...
;         for (int t = 0; t < nt; t += 2) {
;             const bool last = (t == nt - 2);
;             const char* a1 = cA + (size_t)(t + 1) * kstep;
;             const char* a2 = last ? nA : cA + (size_t)(t + 2) * kstep; const char* b2 = last ? nB : cB + (size_t)(t + 2) * kstep;
;             const char* a3 = a2 + kstep; const char* b3 = b2 + kstep;
;             PG8_LDB(B0, 0, 0); PG8_LDB(B1, 0, 1); PG8_SCHED; PG8_LDA(At, 0, 0); PG8_STAGE(PG8_SA(1, 1), a1 + hsA, voffA);
;             PG8_WAIT_V(8); PG8_WAIT_L(0); PG8_BAR; PG8_MMA(0, 0, At, B0); PG8_MMA(0, 1, At, B1); PG8_BAR; PG8_SCHED;
;             PG8_LDA(At, 0, 1); PG8_STAGE(PG8_SB(0, 0), b2, voffB); PG8_STAGE(PG8_SB(0, 1), b2 + hsB, voffB); PG8_STAGE(PG8_SA(0, 0), a2, voffA);
;             PG8_WAIT_V(8); PG8_WAIT_L(0); PG8_BAR; PG8_MMA(1, 0, At, B0); PG8_MMA(1, 1, At, B1); PG8_BAR; PG8_SCHED;
;             PG8_LDB(B0, 1, 0); PG8_LDB(B1, 1, 1); PG8_SCHED; PG8_LDA(At, 1, 0); PG8_STAGE(PG8_SA(0, 1), a2 + hsA, voffA);
;             PG8_WAIT_V(8); PG8_WAIT_L(0); PG8_BAR; PG8_MMA(0, 0, At, B0); PG8_MMA(0, 1, At, B1); PG8_BAR; PG8_SCHED;
;             PG8_LDA(At, 1, 1); PG8_STAGE(PG8_SB(1, 0), b3, voffB); PG8_STAGE(PG8_SB(1, 1), b3 + hsB, voffB); PG8_STAGE(PG8_SA(1, 0), a3, voffA);
;             PG8_WAIT_V(8); PG8_WAIT_L(0); PG8_BAR; PG8_MMA(1, 0, At, B0); PG8_MMA(1, 1, At, B1); PG8_BAR; PG8_SCHED;
;         }
	s_waitcnt lgkmcnt(0)
	v_mfma_i32_16x16x64_i8 v[62:65], v[90:93], v[198:201], v[62:65]
	v_mfma_i32_16x16x64_i8 v[58:61], v[102:105], v[198:201], v[58:61]
	v_mfma_i32_16x16x64_i8 v[50:53], v[90:93], v[208:211], v[50:53]
	v_mfma_i32_16x16x64_i8 v[42:45], v[102:105], v[208:211], v[42:45]
	v_mfma_i32_16x16x64_i8 v[30:33], v[90:93], v[216:219], v[30:33]
	v_mfma_i32_16x16x64_i8 v[26:29], v[102:105], v[216:219], v[26:29]
	v_mfma_i32_16x16x64_i8 v[18:21], v[90:93], v[224:227], v[18:21]
	v_mfma_i32_16x16x64_i8 v[10:13], v[102:105], v[224:227], v[10:13]
	v_mfma_i32_16x16x64_i8 v[62:65], v[98:101], v[202:205], v[62:65]
	v_mfma_i32_16x16x64_i8 v[58:61], v[160:163], v[202:205], v[58:61]
	v_mfma_i32_16x16x64_i8 v[50:53], v[98:101], v[212:215], v[50:53]
	v_mfma_i32_16x16x64_i8 v[42:45], v[160:163], v[212:215], v[42:45]
	v_mfma_i32_16x16x64_i8 v[30:33], v[98:101], v[220:223], v[30:33]
	v_mfma_i32_16x16x64_i8 v[26:29], v[160:163], v[220:223], v[26:29]
	v_mfma_i32_16x16x64_i8 v[18:21], v[98:101], v[228:231], v[18:21]
	v_mfma_i32_16x16x64_i8 v[10:13], v[160:163], v[228:231], v[10:13]
	v_mfma_i32_16x16x64_i8 v[54:57], v[182:185], v[198:201], v[54:57]
	v_mfma_i32_16x16x64_i8 v[46:49], v[190:193], v[198:201], v[46:49]
	v_mfma_i32_16x16x64_i8 v[38:41], v[182:185], v[208:211], v[38:41]
	v_mfma_i32_16x16x64_i8 v[34:37], v[190:193], v[208:211], v[34:37]
	v_mfma_i32_16x16x64_i8 v[22:25], v[182:185], v[216:219], v[22:25]
	v_mfma_i32_16x16x64_i8 v[14:17], v[190:193], v[216:219], v[14:17]
	v_mfma_i32_16x16x64_i8 v[6:9], v[182:185], v[224:227], v[6:9]
	v_mfma_i32_16x16x64_i8 v[2:5], v[190:193], v[224:227], v[2:5]
	v_mfma_i32_16x16x64_i8 v[54:57], v[186:189], v[202:205], v[54:57]
	v_mfma_i32_16x16x64_i8 v[46:49], v[194:197], v[202:205], v[46:49]
	v_mfma_i32_16x16x64_i8 v[38:41], v[186:189], v[212:215], v[38:41]
	v_mfma_i32_16x16x64_i8 v[34:37], v[194:197], v[212:215], v[34:37]
	v_mfma_i32_16x16x64_i8 v[22:25], v[186:189], v[220:223], v[22:25]
	v_mfma_i32_16x16x64_i8 v[14:17], v[194:197], v[220:223], v[14:17]
	v_mfma_i32_16x16x64_i8 v[6:9], v[186:189], v[228:231], v[6:9]
	v_mfma_i32_16x16x64_i8 v[2:5], v[194:197], v[228:231], v[2:5]
	s_barrier
	s_add_i32 s63, 0, 0x18000
	v_add_u32_e32 v154, s63, v175
	s_add_i32 s64, 0, 0x1c000
	ds_read_b128 v[90:93], v154
	ds_read_b128 v[98:101], v154 offset:1024
	ds_read_b128 v[102:105], v154 offset:2048
	ds_read_b128 v[160:163], v154 offset:3072
	v_add_u32_e32 v154, s64, v175
	ds_read_b128 v[182:185], v154
	ds_read_b128 v[186:189], v154 offset:1024
	ds_read_b128 v[190:193], v154 offset:2048
	ds_read_b128 v[194:197], v154 offset:3072
	s_add_u32 s40, s40, 0x180000
	s_addc_u32 s41, s41, 0
	s_mov_b32 m0, s50
	v_lshl_add_u64 v[176:177], s[40:41], 0, v[144:145]
	ds_read_b128 v[198:201], v207 offset:32768
	ds_read_b128 v[202:205], v207 offset:33792
	ds_read_b128 v[208:211], v207 offset:34816
	ds_read_b128 v[212:215], v207 offset:35840
	ds_read_b128 v[216:219], v207 offset:36864
	ds_read_b128 v[220:223], v207 offset:37888
	ds_read_b128 v[224:227], v207 offset:38912
	ds_read_b128 v[228:231], v207 offset:39936
	global_load_lds_dwordx4 v[176:177], off
	v_lshl_add_u64 v[176:177], s[40:41], 0, v[142:143]
	s_mov_b32 m0, s51
	s_nop 0
	global_load_lds_dwordx4 v[176:177], off
	s_waitcnt vmcnt(8)
	s_waitcnt lgkmcnt(0)
	s_barrier
	s_waitcnt lgkmcnt(0)
	v_mfma_i32_16x16x64_i8 v[94:97], v[90:93], v[198:201], v[94:97]
	v_mfma_i32_16x16x64_i8 v[138:141], v[102:105], v[198:201], v[138:141]
	v_mfma_i32_16x16x64_i8 v[130:133], v[90:93], v[208:211], v[130:133]
	v_mfma_i32_16x16x64_i8 v[122:125], v[102:105], v[208:211], v[122:125]
	v_mfma_i32_16x16x64_i8 v[110:113], v[90:93], v[216:219], v[110:113]
	v_mfma_i32_16x16x64_i8 v[106:109], v[102:105], v[216:219], v[106:109]
	v_mfma_i32_16x16x64_i8 v[82:85], v[90:93], v[224:227], v[82:85]
	v_mfma_i32_16x16x64_i8 v[74:77], v[102:105], v[224:227], v[74:77]
	v_mfma_i32_16x16x64_i8 v[94:97], v[98:101], v[202:205], v[94:97]
	v_mfma_i32_16x16x64_i8 v[138:141], v[160:163], v[202:205], v[138:141]
	v_mfma_i32_16x16x64_i8 v[130:133], v[98:101], v[212:215], v[130:133]
	v_mfma_i32_16x16x64_i8 v[122:125], v[160:163], v[212:215], v[122:125]
	v_mfma_i32_16x16x64_i8 v[110:113], v[98:101], v[220:223], v[110:113]
	v_mfma_i32_16x16x64_i8 v[106:109], v[160:163], v[220:223], v[106:109]
	v_mfma_i32_16x16x64_i8 v[82:85], v[98:101], v[228:231], v[82:85]
	v_mfma_i32_16x16x64_i8 v[74:77], v[160:163], v[228:231], v[74:77]
	v_mfma_i32_16x16x64_i8 v[134:137], v[182:185], v[198:201], v[134:137]
	v_mfma_i32_16x16x64_i8 v[126:129], v[190:193], v[198:201], v[126:129]
	v_mfma_i32_16x16x64_i8 v[118:121], v[182:185], v[208:211], v[118:121]
	v_mfma_i32_16x16x64_i8 v[114:117], v[190:193], v[208:211], v[114:117]
	v_mfma_i32_16x16x64_i8 v[86:89], v[182:185], v[216:219], v[86:89]
	v_mfma_i32_16x16x64_i8 v[78:81], v[190:193], v[216:219], v[78:81]
	v_mfma_i32_16x16x64_i8 v[70:73], v[182:185], v[224:227], v[70:73]
	v_mfma_i32_16x16x64_i8 v[66:69], v[190:193], v[224:227], v[66:69]
	v_mfma_i32_16x16x64_i8 v[134:137], v[186:189], v[202:205], v[134:137]
	v_mfma_i32_16x16x64_i8 v[126:129], v[194:197], v[202:205], v[126:129]
	v_mfma_i32_16x16x64_i8 v[118:121], v[186:189], v[212:215], v[118:121]
	v_mfma_i32_16x16x64_i8 v[114:117], v[194:197], v[212:215], v[114:117]
	v_mfma_i32_16x16x64_i8 v[86:89], v[186:189], v[220:223], v[86:89]
	v_mfma_i32_16x16x64_i8 v[78:81], v[194:197], v[220:223], v[78:81]
	v_mfma_i32_16x16x64_i8 v[70:73], v[186:189], v[228:231], v[70:73]
	v_mfma_i32_16x16x64_i8 v[66:69], v[194:197], v[228:231], v[66:69]
	s_barrier
; #define PG8_STAGE(bufoff, gbase, voff) do { _Pragma("unroll") for (int _i = 0; _i < 2; ++_i) \
;         __builtin_amdgcn_global_load_lds((const unsigned*)((const char*)(gbase) + (voff)[_i]), (LAS unsigned*)(lds + (bufoff) + ldsw + _i * 8192), 16, 0, 0); } while (0)
; #define PG8_LDA(dst, b, h) do { _Pragma("unroll") for (int m = 0; m < 4; ++m) _Pragma("unroll") for (int k = 0; k < 2; ++k) dst[m][k] = *(const LAS bf16x8*)(lds + PG8_SA(b, h) + aoff + m * 2048 + k * 1024); } while (0)
; #define PG8_LDB(dst, b, h) do { _Pragma("unroll") for (int n = 0; n < 2; ++n) _Pragma("unroll") for (int k = 0; k < 2; ++k) dst[n][k] = *(const LAS bf16x8*)(lds + PG8_SB(b, h) + boff + n * 2048 + k * 1024); } while (0)
; #define PG8_WAIT_V(n) asm volatile("s_waitcnt vmcnt(" #n ")" ::: "memory")
; template <class Epi, class Geom, class Sched, bool ALIGN_EPI, bool I8 = false>
; __device__ __forceinline__ void gemm_phase(LAS unsigned char* lds, const Gemm g, const Sched& S, const Epi& E) {
;     ...
;         for (int t = 0; t < nt; t += 2) {
;             const bool last = (t == nt - 2);
;             const char* a1 = cA + (size_t)(t + 1) * kstep;
;             const char* a2 = last ? nA : cA + (size_t)(t + 2) * kstep; const char* b2 = last ? nB : cB + (size_t)(t + 2) * kstep;
;             const char* a3 = a2 + kstep; const char* b3 = b2 + kstep;
;             PG8_LDB(B0, 0, 0); PG8_LDB(B1, 0, 1); PG8_SCHED; PG8_LDA(At, 0, 0); PG8_STAGE(PG8_SA(1, 1), a1 + hsA, voffA);
;             PG8_WAIT_V(8); PG8_WAIT_L(0); PG8_BAR; PG8_MMA(0, 0, At, B0); PG8_MMA(0, 1, At, B1); PG8_BAR; PG8_SCHED;
;             PG8_LDA(At, 0, 1); PG8_STAGE(PG8_SB(0, 0), b2, voffB); PG8_STAGE(PG8_SB(0, 1), b2 + hsB, voffB); PG8_STAGE(PG8_SA(0, 0), a2, voffA);
;             PG8_WAIT_V(8); PG8_WAIT_L(0); PG8_BAR; PG8_MMA(1, 0, At, B0); PG8_MMA(1, 1, At, B1); PG8_BAR; PG8_SCHED;
;             PG8_LDB(B0, 1, 0); PG8_LDB(B1, 1, 1); PG8_SCHED; PG8_LDA(At, 1, 0); PG8_STAGE(PG8_SA(0, 1), a2 + hsA, voffA);
;             PG8_WAIT_V(8); PG8_WAIT_L(0); PG8_BAR; PG8_MMA(0, 0, At, B0); PG8_MMA(0, 1, At, B1); PG8_BAR; PG8_SCHED;
;             PG8_LDA(At, 1, 1); PG8_STAGE(PG8_SB(1, 0), b3, voffB); PG8_STAGE(PG8_SB(1, 1), b3 + hsB, voffB); PG8_STAGE(PG8_SA(1, 0), a3, voffA);
;             PG8_WAIT_V(8); PG8_WAIT_L(0); PG8_BAR; PG8_MMA(1, 0, At, B0); PG8_MMA(1, 1, At, B1); PG8_BAR; PG8_SCHED;
;         }
	s_add_i32 s40, s63, s46
	v_lshl_add_u64 v[152:153], v[152:153], 0, s[20:21]
	s_mov_b32 m0, s40
	ds_read_b128 v[198:201], v207 offset:49152
	ds_read_b128 v[202:205], v207 offset:50176
	ds_read_b128 v[208:211], v207 offset:51200
	ds_read_b128 v[212:215], v207 offset:52224
	ds_read_b128 v[216:219], v207 offset:53248
	ds_read_b128 v[220:223], v207 offset:54272
	ds_read_b128 v[224:227], v207 offset:55296
	ds_read_b128 v[228:231], v207 offset:56320
	global_load_lds_dwordx4 v[152:153], off
	s_add_i32 m0, s40, 0x2000
	s_add_u32 s38, s38, 0x180080
	v_lshl_add_u64 v[152:153], v[156:157], 0, s[20:21]
	s_addc_u32 s39, s39, 0
	s_add_i32 s40, s64, s46
	global_load_lds_dwordx4 v[152:153], off
	v_lshl_add_u64 v[152:153], s[38:39], 0, v[144:145]
	s_mov_b32 m0, s40
	s_nop 0
	global_load_lds_dwordx4 v[152:153], off
	v_lshl_add_u64 v[152:153], s[38:39], 0, v[142:143]
	s_add_i32 m0, s40, 0x2000
	s_nop 0
	global_load_lds_dwordx4 v[152:153], off
	v_lshl_add_u64 v[152:153], v[166:167], 0, s[20:21]
	s_mov_b32 m0, s52
	s_nop 0
	global_load_lds_dwordx4 v[152:153], off
	v_lshl_add_u64 v[152:153], v[170:171], 0, s[20:21]
	s_mov_b32 m0, s53
	s_nop 0
	global_load_lds_dwordx4 v[152:153], off
	s_waitcnt vmcnt(8)
	s_waitcnt lgkmcnt(0)
	s_barrier
	s_waitcnt lgkmcnt(0)
	v_mfma_i32_16x16x64_i8 v[62:65], v[90:93], v[198:201], v[62:65]
	v_mfma_i32_16x16x64_i8 v[58:61], v[102:105], v[198:201], v[58:61]
	v_mfma_i32_16x16x64_i8 v[50:53], v[90:93], v[208:211], v[50:53]
	v_mfma_i32_16x16x64_i8 v[42:45], v[102:105], v[208:211], v[42:45]
	v_mfma_i32_16x16x64_i8 v[30:33], v[90:93], v[216:219], v[30:33]
	v_mfma_i32_16x16x64_i8 v[26:29], v[102:105], v[216:219], v[26:29]
	v_mfma_i32_16x16x64_i8 v[18:21], v[90:93], v[224:227], v[18:21]
	v_mfma_i32_16x16x64_i8 v[10:13], v[102:105], v[224:227], v[10:13]
	v_mfma_i32_16x16x64_i8 v[62:65], v[98:101], v[202:205], v[62:65]
	v_mfma_i32_16x16x64_i8 v[58:61], v[160:163], v[202:205], v[58:61]
	v_mfma_i32_16x16x64_i8 v[50:53], v[98:101], v[212:215], v[50:53]
	v_mfma_i32_16x16x64_i8 v[42:45], v[160:163], v[212:215], v[42:45]
	v_mfma_i32_16x16x64_i8 v[30:33], v[98:101], v[220:223], v[30:33]
	v_mfma_i32_16x16x64_i8 v[26:29], v[160:163], v[220:223], v[26:29]
	v_mfma_i32_16x16x64_i8 v[18:21], v[98:101], v[228:231], v[18:21]
	v_mfma_i32_16x16x64_i8 v[10:13], v[160:163], v[228:231], v[10:13]
	v_mfma_i32_16x16x64_i8 v[54:57], v[182:185], v[198:201], v[54:57]
	v_mfma_i32_16x16x64_i8 v[46:49], v[190:193], v[198:201], v[46:49]
	v_mfma_i32_16x16x64_i8 v[38:41], v[182:185], v[208:211], v[38:41]
	v_mfma_i32_16x16x64_i8 v[34:37], v[190:193], v[208:211], v[34:37]
	v_mfma_i32_16x16x64_i8 v[22:25], v[182:185], v[216:219], v[22:25]
	v_mfma_i32_16x16x64_i8 v[14:17], v[190:193], v[216:219], v[14:17]
	v_mfma_i32_16x16x64_i8 v[6:9], v[182:185], v[224:227], v[6:9]
	v_mfma_i32_16x16x64_i8 v[2:5], v[190:193], v[224:227], v[2:5]
	v_mfma_i32_16x16x64_i8 v[54:57], v[186:189], v[202:205], v[54:57]
	v_mfma_i32_16x16x64_i8 v[46:49], v[194:197], v[202:205], v[46:49]
	v_mfma_i32_16x16x64_i8 v[38:41], v[186:189], v[212:215], v[38:41]
	v_mfma_i32_16x16x64_i8 v[34:37], v[194:197], v[212:215], v[34:37]
	v_mfma_i32_16x16x64_i8 v[22:25], v[186:189], v[220:223], v[22:25]
	v_mfma_i32_16x16x64_i8 v[14:17], v[194:197], v[220:223], v[14:17]
	v_mfma_i32_16x16x64_i8 v[6:9], v[186:189], v[228:231], v[6:9]
	v_mfma_i32_16x16x64_i8 v[2:5], v[194:197], v[228:231], v[2:5]
	s_barrier
	s_add_i32 s62, s62, 2
	s_add_u32 s36, s36, 0x100
	s_addc_u32 s37, s37, 0
	s_add_u32 s60, s60, 0x100
	s_addc_u32 s61, s61, 0
	s_cmpk_gt_u32 s62, 0x5d
	s_cbranch_scc0 .LBB0_2872
	s_and_b64 vcc, exec, s[22:23]
	s_cbranch_vccz .LBB0_2875
	s_barrier

; #define PG8_STAGE(bufoff, gbase, voff) do { _Pragma("unroll") for (int _i = 0; _i < 2; ++_i) \
;         __builtin_amdgcn_global_load_lds((const unsigned*)((const char*)(gbase) + (voff)[_i]), (LAS unsigned*)(lds + (bufoff) + ldsw + _i * 8192), 16, 0, 0); } while (0)
; #define PG8_LDA(dst, b, h) do { _Pragma("unroll") for (int m = 0; m < 4; ++m) _Pragma("unroll") for (int k = 0; k < 2; ++k) dst[m][k] = *(const LAS bf16x8*)(lds + PG8_SA(b, h) + aoff + m * 2048 + k * 1024); } while (0)
; #define PG8_LDB(dst, b, h) do { _Pragma("unroll") for (int n = 0; n < 2; ++n) _Pragma("unroll") for (int k = 0; k < 2; ++k) dst[n][k] = *(const LAS bf16x8*)(lds + PG8_SB(b, h) + boff + n * 2048 + k * 1024); } while (0)
; #define PG8_WAIT_V(n) asm volatile("s_waitcnt vmcnt(" #n ")" ::: "memory")
; template <class Epi, class Geom, class Sched, bool ALIGN_EPI, bool I8 = false>
; __device__ __forceinline__ void gemm_phase(LAS unsigned char* lds, const Gemm g, const Sched& S, const Epi& E) {
;     ...
;         for (int t = 0; t < nt; t += 2) {
;             const bool last = (t == nt - 2);
;             const char* a1 = cA + (size_t)(t + 1) * kstep;
;             const char* a2 = last ? nA : cA + (size_t)(t + 2) * kstep; const char* b2 = last ? nB : cB + (size_t)(t + 2) * kstep;
;             const char* a3 = a2 + kstep; const char* b3 = b2 + kstep;
;             PG8_LDB(B0, 0, 0); PG8_LDB(B1, 0, 1); PG8_SCHED; PG8_LDA(At, 0, 0); PG8_STAGE(PG8_SA(1, 1), a1 + hsA, voffA);
;             PG8_WAIT_V(8); PG8_WAIT_L(0); PG8_BAR; PG8_MMA(0, 0, At, B0); PG8_MMA(0, 1, At, B1); PG8_BAR; PG8_SCHED;
;             PG8_LDA(At, 0, 1); PG8_STAGE(PG8_SB(0, 0), b2, voffB); PG8_STAGE(PG8_SB(0, 1), b2 + hsB, voffB); PG8_STAGE(PG8_SA(0, 0), a2, voffA);
;             PG8_WAIT_V(8); PG8_WAIT_L(0); PG8_BAR; PG8_MMA(1, 0, At, B0); PG8_MMA(1, 1, At, B1); PG8_BAR; PG8_SCHED;
;             PG8_LDB(B0, 1, 0); PG8_LDB(B1, 1, 1); PG8_SCHED; PG8_LDA(At, 1, 0); PG8_STAGE(PG8_SA(0, 1), a2 + hsA, voffA);
;             PG8_WAIT_V(8); PG8_WAIT_L(0); PG8_BAR; PG8_MMA(0, 0, At, B0); PG8_MMA(0, 1, At, B1); PG8_BAR; PG8_SCHED;
;             PG8_LDA(At, 1, 1); PG8_STAGE(PG8_SB(1, 0), b3, voffB); PG8_STAGE(PG8_SB(1, 1), b3 + hsB, voffB); PG8_STAGE(PG8_SA(1, 0), a3, voffA);
;             PG8_WAIT_V(8); PG8_WAIT_L(0); PG8_BAR; PG8_MMA(1, 0, At, B0); PG8_MMA(1, 1, At, B1); PG8_BAR; PG8_SCHED;
;         }
.LBB0_2884:
	ds_read_b128 v[118:121], v1
	ds_read_b128 v[148:151], v1 offset:1024
	ds_read_b128 v[152:155], v1 offset:2048
	ds_read_b128 v[156:159], v1 offset:3072
	ds_read_b128 v[160:163], v114
	ds_read_b128 v[164:167], v114 offset:1024
	ds_read_b128 v[168:171], v114 offset:2048
	ds_read_b128 v[172:175], v114 offset:3072
	s_add_u32 s14, s12, 0x100
	s_addc_u32 s15, s13, 0
	s_cmp_lg_u32 s33, 8
	s_cselect_b32 s16, s14, 0
	s_cselect_b32 s17, s15, 0
	s_add_u32 s18, s2, s16
	s_addc_u32 s19, s3, s17
	s_add_u32 s16, s0, s16
	s_addc_u32 s17, s1, s17
	s_mov_b32 m0, s34
	v_lshl_add_u64 v[208:209], v[110:111], 0, s[12:13]
	ds_read_b128 v[176:179], v115
	ds_read_b128 v[180:183], v115 offset:1024
	ds_read_b128 v[184:187], v115 offset:2048
	ds_read_b128 v[188:191], v115 offset:3072
	ds_read_b128 v[192:195], v115 offset:4096
	ds_read_b128 v[196:199], v115 offset:5120
	ds_read_b128 v[200:203], v115 offset:6144
	ds_read_b128 v[204:207], v115 offset:7168
	global_load_lds_dwordx4 v[208:209], off
	v_lshl_add_u64 v[208:209], v[112:113], 0, s[12:13]
	s_mov_b32 m0, s35
	s_nop 0
	global_load_lds_dwordx4 v[208:209], off
	s_waitcnt vmcnt(8)
	s_waitcnt lgkmcnt(0)
	s_barrier
	s_waitcnt lgkmcnt(0)
	v_mfma_i32_16x16x64_i8 v[142:145], v[118:121], v[176:179], v[142:145]
	v_mfma_i32_16x16x64_i8 v[138:141], v[152:155], v[176:179], v[138:141]
	v_mfma_i32_16x16x64_i8 v[126:129], v[118:121], v[184:187], v[126:129]
	v_mfma_i32_16x16x64_i8 v[122:125], v[152:155], v[184:187], v[122:125]
	v_mfma_i32_16x16x64_i8 v[94:97], v[118:121], v[192:195], v[94:97]
	v_mfma_i32_16x16x64_i8 v[90:93], v[152:155], v[192:195], v[90:93]
	v_mfma_i32_16x16x64_i8 v[78:81], v[118:121], v[200:203], v[78:81]
	v_mfma_i32_16x16x64_i8 v[74:77], v[152:155], v[200:203], v[74:77]
	v_mfma_i32_16x16x64_i8 v[142:145], v[148:151], v[180:183], v[142:145]
	v_mfma_i32_16x16x64_i8 v[138:141], v[156:159], v[180:183], v[138:141]
	v_mfma_i32_16x16x64_i8 v[126:129], v[148:151], v[188:191], v[126:129]
	v_mfma_i32_16x16x64_i8 v[122:125], v[156:159], v[188:191], v[122:125]
	v_mfma_i32_16x16x64_i8 v[94:97], v[148:151], v[196:199], v[94:97]
	v_mfma_i32_16x16x64_i8 v[90:93], v[156:159], v[196:199], v[90:93]
	v_mfma_i32_16x16x64_i8 v[78:81], v[148:151], v[204:207], v[78:81]
	v_mfma_i32_16x16x64_i8 v[74:77], v[156:159], v[204:207], v[74:77]
	v_mfma_i32_16x16x64_i8 v[134:137], v[160:163], v[176:179], v[134:137]
	v_mfma_i32_16x16x64_i8 v[130:133], v[168:171], v[176:179], v[130:133]
	v_mfma_i32_16x16x64_i8 v[102:105], v[160:163], v[184:187], v[102:105]
	v_mfma_i32_16x16x64_i8 v[98:101], v[168:171], v[184:187], v[98:101]
	v_mfma_i32_16x16x64_i8 v[86:89], v[160:163], v[192:195], v[86:89]
	v_mfma_i32_16x16x64_i8 v[82:85], v[168:171], v[192:195], v[82:85]
	v_mfma_i32_16x16x64_i8 v[70:73], v[160:163], v[200:203], v[70:73]
	v_mfma_i32_16x16x64_i8 v[66:69], v[168:171], v[200:203], v[66:69]
	v_mfma_i32_16x16x64_i8 v[134:137], v[164:167], v[180:183], v[134:137]
	v_mfma_i32_16x16x64_i8 v[130:133], v[172:175], v[180:183], v[130:133]
	v_mfma_i32_16x16x64_i8 v[102:105], v[164:167], v[188:191], v[102:105]
	v_mfma_i32_16x16x64_i8 v[98:101], v[172:175], v[188:191], v[98:101]
	v_mfma_i32_16x16x64_i8 v[86:89], v[164:167], v[196:199], v[86:89]
	v_mfma_i32_16x16x64_i8 v[82:85], v[172:175], v[196:199], v[82:85]
	v_mfma_i32_16x16x64_i8 v[70:73], v[164:167], v[204:207], v[70:73]
	v_mfma_i32_16x16x64_i8 v[66:69], v[172:175], v[204:207], v[66:69]
	s_barrier
	s_mov_b32 m0, s36
	v_lshl_add_u64 v[208:209], s[16:17], 0, v[108:109]
	s_add_u32 s12, s16, 0x180000
	ds_read_b128 v[176:179], v115 offset:16384
	ds_read_b128 v[180:183], v115 offset:17408
	ds_read_b128 v[184:187], v115 offset:18432
	ds_read_b128 v[188:191], v115 offset:19456
	ds_read_b128 v[192:195], v115 offset:20480
	ds_read_b128 v[196:199], v115 offset:21504
	ds_read_b128 v[200:203], v115 offset:22528
	ds_read_b128 v[204:207], v115 offset:23552
	global_load_lds_dwordx4 v[208:209], off
	v_lshl_add_u64 v[210:211], s[16:17], 0, v[106:107]
	s_mov_b32 m0, s37
	s_addc_u32 s13, s17, 0
	global_load_lds_dwordx4 v[210:211], off
	v_lshl_add_u64 v[212:213], s[12:13], 0, v[108:109]
	s_mov_b32 m0, s38
	v_lshl_add_u64 v[214:215], s[18:19], 0, v[106:107]
	global_load_lds_dwordx4 v[212:213], off
	v_lshl_add_u64 v[212:213], s[12:13], 0, v[106:107]
	s_mov_b32 m0, s39
	s_nop 0
	global_load_lds_dwordx4 v[212:213], off
	v_lshl_add_u64 v[212:213], s[18:19], 0, v[108:109]
	s_mov_b32 m0, s26
	s_nop 0
	global_load_lds_dwordx4 v[212:213], off
	s_mov_b32 m0, s27
	s_nop 0
	global_load_lds_dwordx4 v[214:215], off
	s_waitcnt vmcnt(8)
	s_waitcnt lgkmcnt(0)
	s_barrier
; #define PG8_STAGE(bufoff, gbase, voff) do { _Pragma("unroll") for (int _i = 0; _i < 2; ++_i) \
;         __builtin_amdgcn_global_load_lds((const unsigned*)((const char*)(gbase) + (voff)[_i]), (LAS unsigned*)(lds + (bufoff) + ldsw + _i * 8192), 16, 0, 0); } while (0)
; #define PG8_LDA(dst, b, h) do { _Pragma("unroll") for (int m = 0; m < 4; ++m) _Pragma("unroll") for (int k = 0; k < 2; ++k) dst[m][k] = *(const LAS bf16x8*)(lds + PG8_SA(b, h) + aoff + m * 2048 + k * 1024); } while (0)
; #define PG8_LDB(dst, b, h) do { _Pragma("unroll") for (int n = 0; n < 2; ++n) _Pragma("unroll") for (int k = 0; k < 2; ++k) dst[n][k] = *(const LAS bf16x8*)(lds + PG8_SB(b, h) + boff + n * 2048 + k * 1024); } while (0)
; #define PG8_WAIT_V(n) asm volatile("s_waitcnt vmcnt(" #n ")" ::: "memory")
; template <class Epi, class Geom, class Sched, bool ALIGN_EPI, bool I8 = false>
; __device__ __forceinline__ void gemm_phase(LAS unsigned char* lds, const Gemm g, const Sched& S, const Epi& E) {
;     ...
;         for (int t = 0; t < nt; t += 2) {
;             const bool last = (t == nt - 2);
;             const char* a1 = cA + (size_t)(t + 1) * kstep;
;             const char* a2 = last ? nA : cA + (size_t)(t + 2) * kstep; const char* b2 = last ? nB : cB + (size_t)(t + 2) * kstep;
;             const char* a3 = a2 + kstep; const char* b3 = b2 + kstep;
;             PG8_LDB(B0, 0, 0); PG8_LDB(B1, 0, 1); PG8_SCHED; PG8_LDA(At, 0, 0); PG8_STAGE(PG8_SA(1, 1), a1 + hsA, voffA);
;             PG8_WAIT_V(8); PG8_WAIT_L(0); PG8_BAR; PG8_MMA(0, 0, At, B0); PG8_MMA(0, 1, At, B1); PG8_BAR; PG8_SCHED;
;             PG8_LDA(At, 0, 1); PG8_STAGE(PG8_SB(0, 0), b2, voffB); PG8_STAGE(PG8_SB(0, 1), b2 + hsB, voffB); PG8_STAGE(PG8_SA(0, 0), a2, voffA);
;             PG8_WAIT_V(8); PG8_WAIT_L(0); PG8_BAR; PG8_MMA(1, 0, At, B0); PG8_MMA(1, 1, At, B1); PG8_BAR; PG8_SCHED;
;             PG8_LDB(B0, 1, 0); PG8_LDB(B1, 1, 1); PG8_SCHED; PG8_LDA(At, 1, 0); PG8_STAGE(PG8_SA(0, 1), a2 + hsA, voffA);
;             PG8_WAIT_V(8); PG8_WAIT_L(0); PG8_BAR; PG8_MMA(0, 0, At, B0); PG8_MMA(0, 1, At, B1); PG8_BAR; PG8_SCHED;
;             PG8_LDA(At, 1, 1); PG8_STAGE(PG8_SB(1, 0), b3, voffB); PG8_STAGE(PG8_SB(1, 1), b3 + hsB, voffB); PG8_STAGE(PG8_SA(1, 0), a3, voffA);
;             PG8_WAIT_V(8); PG8_WAIT_L(0); PG8_BAR; PG8_MMA(1, 0, At, B0); PG8_MMA(1, 1, At, B1); PG8_BAR; PG8_SCHED;
;         }
	s_waitcnt lgkmcnt(0)
	v_mfma_i32_16x16x64_i8 v[62:65], v[118:121], v[176:179], v[62:65]
	v_mfma_i32_16x16x64_i8 v[58:61], v[152:155], v[176:179], v[58:61]
	v_mfma_i32_16x16x64_i8 v[46:49], v[118:121], v[184:187], v[46:49]
	v_mfma_i32_16x16x64_i8 v[42:45], v[152:155], v[184:187], v[42:45]
	v_mfma_i32_16x16x64_i8 v[30:33], v[118:121], v[192:195], v[30:33]
	v_mfma_i32_16x16x64_i8 v[26:29], v[152:155], v[192:195], v[26:29]
	v_mfma_i32_16x16x64_i8 v[14:17], v[118:121], v[200:203], v[14:17]
	v_mfma_i32_16x16x64_i8 v[10:13], v[152:155], v[200:203], v[10:13]
	v_mfma_i32_16x16x64_i8 v[62:65], v[148:151], v[180:183], v[62:65]
	v_mfma_i32_16x16x64_i8 v[58:61], v[156:159], v[180:183], v[58:61]
	v_mfma_i32_16x16x64_i8 v[46:49], v[148:151], v[188:191], v[46:49]
	v_mfma_i32_16x16x64_i8 v[42:45], v[156:159], v[188:191], v[42:45]
	v_mfma_i32_16x16x64_i8 v[30:33], v[148:151], v[196:199], v[30:33]
	v_mfma_i32_16x16x64_i8 v[26:29], v[156:159], v[196:199], v[26:29]
	v_mfma_i32_16x16x64_i8 v[14:17], v[148:151], v[204:207], v[14:17]
	v_mfma_i32_16x16x64_i8 v[10:13], v[156:159], v[204:207], v[10:13]
	v_mfma_i32_16x16x64_i8 v[54:57], v[160:163], v[176:179], v[54:57]
	v_mfma_i32_16x16x64_i8 v[50:53], v[168:171], v[176:179], v[50:53]
	v_mfma_i32_16x16x64_i8 v[38:41], v[160:163], v[184:187], v[38:41]
	v_mfma_i32_16x16x64_i8 v[34:37], v[168:171], v[184:187], v[34:37]
	v_mfma_i32_16x16x64_i8 v[22:25], v[160:163], v[192:195], v[22:25]
	v_mfma_i32_16x16x64_i8 v[18:21], v[168:171], v[192:195], v[18:21]
	v_mfma_i32_16x16x64_i8 v[6:9], v[160:163], v[200:203], v[6:9]
	v_mfma_i32_16x16x64_i8 v[2:5], v[168:171], v[200:203], v[2:5]
	v_mfma_i32_16x16x64_i8 v[54:57], v[164:167], v[180:183], v[54:57]
	v_mfma_i32_16x16x64_i8 v[50:53], v[172:175], v[180:183], v[50:53]
	v_mfma_i32_16x16x64_i8 v[38:41], v[164:167], v[188:191], v[38:41]
	v_mfma_i32_16x16x64_i8 v[34:37], v[172:175], v[188:191], v[34:37]
	v_mfma_i32_16x16x64_i8 v[22:25], v[164:167], v[196:199], v[22:25]
	v_mfma_i32_16x16x64_i8 v[18:21], v[172:175], v[196:199], v[18:21]
	v_mfma_i32_16x16x64_i8 v[6:9], v[164:167], v[204:207], v[6:9]
	v_mfma_i32_16x16x64_i8 v[2:5], v[172:175], v[204:207], v[2:5]
	s_barrier
	ds_read_b128 v[118:121], v116
	ds_read_b128 v[148:151], v116 offset:1024
	ds_read_b128 v[152:155], v116 offset:2048
	ds_read_b128 v[156:159], v116 offset:3072
	ds_read_b128 v[160:163], v117
	ds_read_b128 v[164:167], v117 offset:1024
	ds_read_b128 v[168:171], v117 offset:2048
	ds_read_b128 v[172:175], v117 offset:3072
	s_add_u32 s12, s18, 0x180000
	s_addc_u32 s13, s19, 0
	s_mov_b32 m0, s28
	v_lshl_add_u64 v[216:217], s[12:13], 0, v[108:109]
	ds_read_b128 v[176:179], v115 offset:32768
	ds_read_b128 v[180:183], v115 offset:33792
	ds_read_b128 v[184:187], v115 offset:34816
	ds_read_b128 v[188:191], v115 offset:35840
	ds_read_b128 v[192:195], v115 offset:36864
	ds_read_b128 v[196:199], v115 offset:37888
	ds_read_b128 v[200:203], v115 offset:38912
	ds_read_b128 v[204:207], v115 offset:39936
	global_load_lds_dwordx4 v[216:217], off
	v_lshl_add_u64 v[216:217], s[12:13], 0, v[106:107]
	s_mov_b32 m0, s29
	s_nop 0
	global_load_lds_dwordx4 v[216:217], off
	s_waitcnt vmcnt(8)
	s_waitcnt lgkmcnt(0)
	s_barrier
	s_waitcnt lgkmcnt(0)
	v_mfma_i32_16x16x64_i8 v[142:145], v[118:121], v[176:179], v[142:145]
	v_mfma_i32_16x16x64_i8 v[138:141], v[152:155], v[176:179], v[138:141]
	v_mfma_i32_16x16x64_i8 v[126:129], v[118:121], v[184:187], v[126:129]
	v_mfma_i32_16x16x64_i8 v[122:125], v[152:155], v[184:187], v[122:125]
	v_mfma_i32_16x16x64_i8 v[94:97], v[118:121], v[192:195], v[94:97]
	v_mfma_i32_16x16x64_i8 v[90:93], v[152:155], v[192:195], v[90:93]
	v_mfma_i32_16x16x64_i8 v[78:81], v[118:121], v[200:203], v[78:81]
	v_mfma_i32_16x16x64_i8 v[74:77], v[152:155], v[200:203], v[74:77]
	v_mfma_i32_16x16x64_i8 v[142:145], v[148:151], v[180:183], v[142:145]
	v_mfma_i32_16x16x64_i8 v[138:141], v[156:159], v[180:183], v[138:141]
	v_mfma_i32_16x16x64_i8 v[126:129], v[148:151], v[188:191], v[126:129]
	v_mfma_i32_16x16x64_i8 v[122:125], v[156:159], v[188:191], v[122:125]
	v_mfma_i32_16x16x64_i8 v[94:97], v[148:151], v[196:199], v[94:97]
	v_mfma_i32_16x16x64_i8 v[90:93], v[156:159], v[196:199], v[90:93]
	v_mfma_i32_16x16x64_i8 v[78:81], v[148:151], v[204:207], v[78:81]
	v_mfma_i32_16x16x64_i8 v[74:77], v[156:159], v[204:207], v[74:77]
	v_mfma_i32_16x16x64_i8 v[134:137], v[160:163], v[176:179], v[134:137]
	v_mfma_i32_16x16x64_i8 v[130:133], v[168:171], v[176:179], v[130:133]
	v_mfma_i32_16x16x64_i8 v[102:105], v[160:163], v[184:187], v[102:105]
	v_mfma_i32_16x16x64_i8 v[98:101], v[168:171], v[184:187], v[98:101]
	v_mfma_i32_16x16x64_i8 v[86:89], v[160:163], v[192:195], v[86:89]
	v_mfma_i32_16x16x64_i8 v[82:85], v[168:171], v[192:195], v[82:85]
	v_mfma_i32_16x16x64_i8 v[70:73], v[160:163], v[200:203], v[70:73]
	v_mfma_i32_16x16x64_i8 v[66:69], v[168:171], v[200:203], v[66:69]
	v_mfma_i32_16x16x64_i8 v[134:137], v[164:167], v[180:183], v[134:137]
	v_mfma_i32_16x16x64_i8 v[130:133], v[172:175], v[180:183], v[130:133]
	v_mfma_i32_16x16x64_i8 v[102:105], v[164:167], v[188:191], v[102:105]
	v_mfma_i32_16x16x64_i8 v[98:101], v[172:175], v[188:191], v[98:101]
	v_mfma_i32_16x16x64_i8 v[86:89], v[164:167], v[196:199], v[86:89]
	v_mfma_i32_16x16x64_i8 v[82:85], v[172:175], v[196:199], v[82:85]
	v_mfma_i32_16x16x64_i8 v[70:73], v[164:167], v[204:207], v[70:73]
	v_mfma_i32_16x16x64_i8 v[66:69], v[172:175], v[204:207], v[66:69]
	s_barrier
; #define PG8_STAGE(bufoff, gbase, voff) do { _Pragma("unroll") for (int _i = 0; _i < 2; ++_i) \
;         __builtin_amdgcn_global_load_lds((const unsigned*)((const char*)(gbase) + (voff)[_i]), (LAS unsigned*)(lds + (bufoff) + ldsw + _i * 8192), 16, 0, 0); } while (0)
; #define PG8_LDA(dst, b, h) do { _Pragma("unroll") for (int m = 0; m < 4; ++m) _Pragma("unroll") for (int k = 0; k < 2; ++k) dst[m][k] = *(const LAS bf16x8*)(lds + PG8_SA(b, h) + aoff + m * 2048 + k * 1024); } while (0)
; #define PG8_LDB(dst, b, h) do { _Pragma("unroll") for (int n = 0; n < 2; ++n) _Pragma("unroll") for (int k = 0; k < 2; ++k) dst[n][k] = *(const LAS bf16x8*)(lds + PG8_SB(b, h) + boff + n * 2048 + k * 1024); } while (0)
; #define PG8_WAIT_V(n) asm volatile("s_waitcnt vmcnt(" #n ")" ::: "memory")
; template <class Epi, class Geom, class Sched, bool ALIGN_EPI, bool I8 = false>
; __device__ __forceinline__ void gemm_phase(LAS unsigned char* lds, const Gemm g, const Sched& S, const Epi& E) {
;     ...
;         for (int t = 0; t < nt; t += 2) {
;             const bool last = (t == nt - 2);
;             const char* a1 = cA + (size_t)(t + 1) * kstep;
;             const char* a2 = last ? nA : cA + (size_t)(t + 2) * kstep; const char* b2 = last ? nB : cB + (size_t)(t + 2) * kstep;
;             const char* a3 = a2 + kstep; const char* b3 = b2 + kstep;
;             PG8_LDB(B0, 0, 0); PG8_LDB(B1, 0, 1); PG8_SCHED; PG8_LDA(At, 0, 0); PG8_STAGE(PG8_SA(1, 1), a1 + hsA, voffA);
;             PG8_WAIT_V(8); PG8_WAIT_L(0); PG8_BAR; PG8_MMA(0, 0, At, B0); PG8_MMA(0, 1, At, B1); PG8_BAR; PG8_SCHED;
;             PG8_LDA(At, 0, 1); PG8_STAGE(PG8_SB(0, 0), b2, voffB); PG8_STAGE(PG8_SB(0, 1), b2 + hsB, voffB); PG8_STAGE(PG8_SA(0, 0), a2, voffA);
;             PG8_WAIT_V(8); PG8_WAIT_L(0); PG8_BAR; PG8_MMA(1, 0, At, B0); PG8_MMA(1, 1, At, B1); PG8_BAR; PG8_SCHED;
;             PG8_LDB(B0, 1, 0); PG8_LDB(B1, 1, 1); PG8_SCHED; PG8_LDA(At, 1, 0); PG8_STAGE(PG8_SA(0, 1), a2 + hsA, voffA);
;             PG8_WAIT_V(8); PG8_WAIT_L(0); PG8_BAR; PG8_MMA(0, 0, At, B0); PG8_MMA(0, 1, At, B1); PG8_BAR; PG8_SCHED;
;             PG8_LDA(At, 1, 1); PG8_STAGE(PG8_SB(1, 0), b3, voffB); PG8_STAGE(PG8_SB(1, 1), b3 + hsB, voffB); PG8_STAGE(PG8_SA(1, 0), a3, voffA);
;             PG8_WAIT_V(8); PG8_WAIT_L(0); PG8_BAR; PG8_MMA(1, 0, At, B0); PG8_MMA(1, 1, At, B1); PG8_BAR; PG8_SCHED;
;         }
	s_mov_b32 m0, s40
	v_lshl_add_u64 v[208:209], v[208:209], 0, s[4:5]
	s_add_u32 s12, s16, 0x180080
	ds_read_b128 v[176:179], v115 offset:49152
	ds_read_b128 v[180:183], v115 offset:50176
	ds_read_b128 v[184:187], v115 offset:51200
	ds_read_b128 v[188:191], v115 offset:52224
	ds_read_b128 v[192:195], v115 offset:53248
	ds_read_b128 v[196:199], v115 offset:54272
	ds_read_b128 v[200:203], v115 offset:55296
	ds_read_b128 v[204:207], v115 offset:56320
	global_load_lds_dwordx4 v[208:209], off
	v_lshl_add_u64 v[208:209], v[210:211], 0, s[4:5]
	s_mov_b32 m0, s41
	s_addc_u32 s13, s17, 0
	global_load_lds_dwordx4 v[208:209], off
	v_lshl_add_u64 v[208:209], s[12:13], 0, v[108:109]
	s_mov_b32 m0, s42
	s_nop 0
	global_load_lds_dwordx4 v[208:209], off
	v_lshl_add_u64 v[208:209], s[12:13], 0, v[106:107]
	s_mov_b32 m0, s43
	s_nop 0
	global_load_lds_dwordx4 v[208:209], off
	v_lshl_add_u64 v[208:209], v[212:213], 0, s[4:5]
	s_mov_b32 m0, s30
	s_nop 0
	global_load_lds_dwordx4 v[208:209], off
	v_lshl_add_u64 v[208:209], v[214:215], 0, s[4:5]
	s_mov_b32 m0, s31
	s_nop 0
	global_load_lds_dwordx4 v[208:209], off
	s_waitcnt vmcnt(8)
	s_waitcnt lgkmcnt(0)
	s_barrier
	s_waitcnt lgkmcnt(0)
	v_mfma_i32_16x16x64_i8 v[62:65], v[118:121], v[176:179], v[62:65]
	v_mfma_i32_16x16x64_i8 v[58:61], v[152:155], v[176:179], v[58:61]
	v_mfma_i32_16x16x64_i8 v[46:49], v[118:121], v[184:187], v[46:49]
	v_mfma_i32_16x16x64_i8 v[42:45], v[152:155], v[184:187], v[42:45]
	v_mfma_i32_16x16x64_i8 v[30:33], v[118:121], v[192:195], v[30:33]
	v_mfma_i32_16x16x64_i8 v[26:29], v[152:155], v[192:195], v[26:29]
	v_mfma_i32_16x16x64_i8 v[14:17], v[118:121], v[200:203], v[14:17]
	v_mfma_i32_16x16x64_i8 v[10:13], v[152:155], v[200:203], v[10:13]
	v_mfma_i32_16x16x64_i8 v[62:65], v[148:151], v[180:183], v[62:65]
	v_mfma_i32_16x16x64_i8 v[58:61], v[156:159], v[180:183], v[58:61]
	v_mfma_i32_16x16x64_i8 v[46:49], v[148:151], v[188:191], v[46:49]
	v_mfma_i32_16x16x64_i8 v[42:45], v[156:159], v[188:191], v[42:45]
	v_mfma_i32_16x16x64_i8 v[30:33], v[148:151], v[196:199], v[30:33]
	v_mfma_i32_16x16x64_i8 v[26:29], v[156:159], v[196:199], v[26:29]
	v_mfma_i32_16x16x64_i8 v[14:17], v[148:151], v[204:207], v[14:17]
	v_mfma_i32_16x16x64_i8 v[10:13], v[156:159], v[204:207], v[10:13]
	v_mfma_i32_16x16x64_i8 v[54:57], v[160:163], v[176:179], v[54:57]
	v_mfma_i32_16x16x64_i8 v[50:53], v[168:171], v[176:179], v[50:53]
	v_mfma_i32_16x16x64_i8 v[38:41], v[160:163], v[184:187], v[38:41]
	v_mfma_i32_16x16x64_i8 v[34:37], v[168:171], v[184:187], v[34:37]
	v_mfma_i32_16x16x64_i8 v[22:25], v[160:163], v[192:195], v[22:25]
	v_mfma_i32_16x16x64_i8 v[18:21], v[168:171], v[192:195], v[18:21]
	v_mfma_i32_16x16x64_i8 v[6:9], v[160:163], v[200:203], v[6:9]
	v_mfma_i32_16x16x64_i8 v[2:5], v[168:171], v[200:203], v[2:5]
	v_mfma_i32_16x16x64_i8 v[54:57], v[164:167], v[180:183], v[54:57]
	v_mfma_i32_16x16x64_i8 v[50:53], v[172:175], v[180:183], v[50:53]
	v_mfma_i32_16x16x64_i8 v[38:41], v[164:167], v[188:191], v[38:41]
	v_mfma_i32_16x16x64_i8 v[34:37], v[172:175], v[188:191], v[34:37]
	v_mfma_i32_16x16x64_i8 v[22:25], v[164:167], v[196:199], v[22:25]
	v_mfma_i32_16x16x64_i8 v[18:21], v[172:175], v[196:199], v[18:21]
	v_mfma_i32_16x16x64_i8 v[6:9], v[164:167], v[204:207], v[6:9]
	v_mfma_i32_16x16x64_i8 v[2:5], v[172:175], v[204:207], v[2:5]
	s_barrier
	s_add_i32 s33, s33, 2
	s_cmp_gt_u32 s33, 9
	s_mov_b64 s[12:13], s[14:15]
	s_cbranch_scc0 .LBB0_2884
	s_cmpk_lt_u32 s23, 0x100
	s_cbranch_scc0 .LBB0_2887
	s_barrier
